# hand-written mode-0/1 and conv+SwiGLU GEMM epilogues (prefetched loads, dwordx4 stores, rcp-based silu), pipelined LDS reads in cross-attention
# speedup vs baseline: 1.0326x; 1.0326x over previous
; __device__ __forceinline__ int opaque_tid() { int t = (int)threadIdx.x; asm volatile("" : "+v"(t)); return t; }
; #define PG8_STAGE(bufoff, gbase, voff) do { _Pragma("unroll") for (int _i = 0; _i < 2; ++_i) \
;         __builtin_amdgcn_global_load_lds((const unsigned*)((const char*)(gbase) + (voff)[_i]), (LAS unsigned*)(lds + (bufoff) + ldsw + _i * 8192), 16, 0, 0); } while (0)
; __device__ __forceinline__ void gemm_phase(LAS unsigned char* lds, const GemmDesc& g) {
;     const int tid = opaque_tid(), wid = __builtin_amdgcn_readfirstlane(tid >> 6), lane = tid & 63, wr = wid >> 2, wc = wid & 3, fr = lane & 15, fq = lane >> 4;
;     const int K = g.K, nt = K / BK;
;     const bool perm = (g.mode != 2);
;     unsigned voffA[2], voffB[2];
; #pragma unroll
;     for (int i = 0; i < 2; ++i) { int R, C; stage_rc(tid * 16 + i * 8192, R, C); const int Rb = perm ? ((R & ~31) + perm32(R & 31)) : R;
;         const int Ra = (g.mode == 3) ? (8 * (16 * (R >> 6) + (R & 15)) + ((R >> 4) & 3)) : R;
;         voffA[i] = (unsigned)(Ra * K + C) * 2u; voffB[i] = (unsigned)(Rb * K + C) * 2u; }
;     const size_t kstep = (size_t)(BK * 2);
;     const size_t hstep = (size_t)HALF * K * 2;
;     const size_t tstep = 2 * hstep;
;     const size_t hstepA = (g.mode == 3) ? (size_t)4 * K * 2 : hstep;
;     const unsigned ldsw = (unsigned)wid * 1024u;
;     const int aoff = lds_byte(wr * 64 + fr, fq * 8), boff = lds_byte(wc * 32 + fr, fq * 8);
;     ...
;     Unit cur, nxt; int ui = 0;
;     if (!unit_next(g, 0, cur)) return;
;     f32x4 acc[2][2][4][2];
; #pragma unroll
;     for (int a = 0; a < 2; ++a)
; #pragma unroll
;         for (int b = 0; b < 2; ++b)
; #pragma unroll
;             for (int m = 0; m < 4; ++m)
; #pragma unroll
;                 for (int n = 0; n < 2; ++n) acc[a][b][m][n] = (f32x4){0.f, 0.f, 0.f, 0.f};
;     bf16x8 At[4][2], B0[2][2], B1[2][2];
;     const char* cA = (const char*)g.A + (size_t)cur.pm * tstep; const char* cB = (const char*)g.Bt + (size_t)cur.pn * tstep;
;     PG8_STAGE(PG8_SB(0, 0), cB, voffB); PG8_STAGE(PG8_SA(0, 0), cA, voffA); PG8_STAGE(PG8_SB(0, 1), cB + hstep, voffB); PG8_STAGE(PG8_SA(0, 1), cA + hstepA, voffA);
;     if (wr == 1) PG8_BAR;
;     PG8_WAIT_V(4); PG8_BAR;
;     PG8_STAGE(PG8_SB(1, 0), cB + kstep, voffB); PG8_STAGE(PG8_SA(1, 0), cA + kstep, voffA); PG8_STAGE(PG8_SB(1, 1), cB + hstep + kstep, voffB);
;     PG8_WAIT_V(6); PG8_BAR;
.LBB0_192:
	s_add_i32 m0, s5, 0x18000
	v_lshl_add_u64 v[4:5], v[4:5], 0, s[20:21]
	s_waitcnt vmcnt(4)
	s_barrier
	global_load_lds_dwordx4 v[4:5], off
	v_lshl_add_u64 v[4:5], v[6:7], 0, s[20:21]
	s_add_i32 m0, s5, 0x1a000
	s_add_i32 s49, s5, 0x8000
	global_load_lds_dwordx4 v[4:5], off
	v_lshl_add_u64 v[4:5], v[8:9], 0, s[20:21]
	s_mov_b32 m0, s49
	s_add_i32 s62, s5, 0xa000
	global_load_lds_dwordx4 v[4:5], off
	v_lshl_add_u64 v[4:5], v[10:11], 0, s[20:21]
	s_mov_b32 m0, s62
	s_xor_b64 s[0:1], s[0:1], -1
	global_load_lds_dwordx4 v[4:5], off
	s_add_i32 m0, s5, 0x1c000
	v_lshl_add_u64 v[4:5], v[12:13], 0, s[20:21]
	global_load_lds_dwordx4 v[4:5], off
	v_lshl_add_u64 v[4:5], v[14:15], 0, s[20:21]
	s_add_i32 m0, s5, 0x1e000
	v_bfe_u32 v17, v16, 4, 2
	global_load_lds_dwordx4 v[4:5], off
	v_writelane_b32 v254, s0, 55
	v_and_b32_e32 v198, 15, v16
	v_lshlrev_b32_e32 v18, 4, v17
	v_lshlrev_b32_e32 v21, 2, v16
	v_writelane_b32 v254, s1, 56
	s_and_b32 s7, s7, 3
	s_lshr_b32 s48, s18, 6
	v_lshl_or_b32 v19, v198, 6, v18
	s_lshl_b32 s0, s6, 13
	v_and_b32_e32 v21, 32, v21
	v_bitop3_b32 v22, v19, s0, v21 bitop3:0xde
	s_lshl_b32 s0, s7, 12
	s_add_i32 s63, s48, -2
	s_cmp_eq_u32 s7, 0
	v_bitop3_b32 v200, v19, s0, v21 bitop3:0xde
	s_cselect_b64 s[0:1], -1, 0
	v_writelane_b32 v254, s0, 57
	v_cmp_eq_u32_e64 s[38:39], 0, v198
	v_mov_b32_e32 v19, v3
	v_writelane_b32 v254, s1, 58
	s_lshl_b32 s0, s6, 3
	s_or_b32 s1, s0, 4
	v_mov_b32_e32 v5, s0
	v_readlane_b32 s0, v254, 54
	s_cmpk_gt_u32 s0, 0xff
	v_mov_b32_e32 v4, s1
	s_cselect_b64 s[0:1], -1, 0
	v_writelane_b32 v254, s0, 59
	v_cndmask_b32_e64 v201, v4, v5, s[38:39]
	v_lshlrev_b32_e32 v4, 3, v198
	v_writelane_b32 v254, s1, 60
	s_lshl_b32 s0, s7, 6
	v_readlane_b32 s22, v254, 47
	v_readlane_b32 s23, v254, 48
	s_add_u32 s0, s22, s0
	v_lshl_or_b32 v203, s6, 7, v4
	s_addc_u32 s1, s23, 0
	v_lshlrev_b32_e32 v4, 1, v16
	v_lshl_add_u64 v[168:169], s[0:1], 0, v[18:19]
	v_and_b32_e32 v4, 32, v4
	v_mov_b32_e32 v5, v3
	s_lshr_b32 s0, s12, 8
	v_lshl_add_u64 v[170:171], s[58:59], 0, v[4:5]
	v_mov_b32_e32 v4, s0
	v_readlane_b32 s0, v254, 51
	v_lshl_or_b32 v199, s6, 6, v198
	s_lshr_b32 s60, s12, 5
	v_mul_u32_u24_e32 v172, s0, v4
	s_ashr_i32 s0, s15, 31
	v_writelane_b32 v254, s0, 61
	v_cvt_f32_u32_e32 v4, s60
	v_readlane_b32 s1, v254, 46
	s_ashr_i32 s0, s1, 31
	v_writelane_b32 v254, s0, 62
	v_readfirstlane_b32 s0, v172
	s_lshr_b32 s6, s0, 3
	s_and_b32 s0, s0, 4
	v_writelane_b32 v254, s0, 63
	v_writelane_b32 v255, s6, 0
	s_add_i32 s0, s6, 1
	v_writelane_b32 v255, s0, 1
	s_lshr_b32 s0, s1, 2
	s_and_b32 s0, s0, 6
	s_or_b32 s0, s0, 1
	v_writelane_b32 v255, s0, 2
	s_lshl_b32 s0, s1, 3
	s_and_b32 s0, s0, 56
	s_ashr_i32 s1, s1, 5
	s_add_i32 s0, s0, s1
	v_writelane_b32 v255, s0, 3
	s_add_u32 s0, s50, 0xac00
	s_addc_u32 s1, s51, 0
	v_writelane_b32 v255, s0, 4
	v_rcp_iflag_f32_e32 v4, v4
	v_lshlrev_b32_e32 v20, 3, v17
	v_writelane_b32 v255, s1, 5
	s_add_u32 s0, s50, 0x15800
	s_addc_u32 s1, s51, 0
	v_writelane_b32 v255, s0, 6
	v_mul_f32_e32 v4, 0x4f7ffffe, v4
	v_lshl_or_b32 v211, s7, 5, v20
	v_writelane_b32 v255, s1, 7
	s_add_u32 s0, s50, 0x5600
	s_addc_u32 s1, s51, 0
	s_add_u32 s6, s50, 0x10200
	s_addc_u32 s7, s51, 0
	v_cvt_u32_f32_e32 v4, v4
	s_add_u32 s22, s50, 0x1ae00
	s_addc_u32 s23, s51, 0
	v_writelane_b32 v255, s0, 8
	s_add_u32 s26, s58, 0x5600
	s_addc_u32 s27, s59, 0
	v_writelane_b32 v255, s1, 9
	s_sub_i32 s0, 0, s60
	v_readfirstlane_b32 s1, v4
	s_mul_i32 s0, s0, s1
	s_waitcnt vmcnt(6)
	s_mul_hi_u32 s0, s1, s0
	s_add_i32 s0, s1, s0
	s_mov_b32 s13, 0
	v_cmp_gt_u32_e64 s[36:37], 2, v17
	v_or_b32_e32 v202, 2, v201
	v_or_b32_e32 v204, 1, v203
	v_or_b32_e32 v205, 2, v203
	v_or_b32_e32 v206, 3, v203
	v_or_b32_e32 v207, 4, v203
	v_or_b32_e32 v208, 5, v203
	v_or_b32_e32 v209, 6, v203
	v_or_b32_e32 v210, 7, v203
	v_mov_b32_e32 v173, v3
	v_writelane_b32 v255, s0, 10
	v_lshl_add_u64 v[174:175], s[68:69], 0, v[166:167]
	v_lshl_add_u64 v[176:177], s[68:69], 0, v[0:1]
	v_add_u32_e32 v229, 0, v22
	s_barrier
	s_branch .LBB0_195
.LBB0_194:
	s_mov_b64 s[42:43], s[24:25]
	v_readlane_b32 s24, v254, 17
	s_andn2_b64 vcc, exec, s[54:55]
	s_mov_b32 s9, s12
	s_mov_b32 s11, s10
	s_mov_b32 s18, s12
	s_mov_b32 s44, s10
	s_mov_b64 s[40:41], s[34:35]
	s_mov_b32 s13, s8
	v_readlane_b32 s25, v254, 18
	s_cbranch_vccz .LBB0_385

; __device__ __forceinline__ float bflo(unsigned u) { return __uint_as_float(u << 16); }
; __device__ __forceinline__ void gemm_epilogue(const GemmDesc& d, const f32x4 (&acc)[2][2][4][2], const Unit& u, int wr, int wc, int fr, int fq) {
;     ...
;         const int row0 = u.pm * BM + wr * 64 + fr, col0 = u.pn * BM + wc * 32 + 8 * fq;
;         bf16_t* O = (bf16_t*)d.C;
;         const bool ropet = (d.mode == 1) && (u.pn >= 12) && (u.pn < 20) && (wc == 0);
;         const float qs = (d.mode == 1 && (u.pn < 2 || (u.pn >= 12 && u.pn < 16))) ? 0.08838834764831845f : 1.0f;
;         const bool gate = (d.mode == 1) && (u.pn < 4);
;         const bf16_t* gtab = (const bf16_t*)d.aux + (u.pn & 1) * 256 + wc * 32 + 8 * fq;
;         const bool ginv = (u.pn >= 2);
; #pragma unroll
;         for (int ai = 0; ai < 2; ++ai)
; #pragma unroll
;             for (int m = 0; m < 4; ++m) {
;                 const int row = row0 + ai * HALF + m * 16;
;                 bf16_t* rowp = O + (size_t)row * d.ldc + col0;
;                 f32x4 c0 = {1.f, 1.f, 1.f, 1.f}, c1 = c0, s0 = {0.f, 0.f, 0.f, 0.f}, s1 = s0;
;                 if (ropet) { const float* tp = d.rope + (size_t)row * 32 + 8 * (fq & 1); c0 = *(const f32x4*)tp; c1 = *(const f32x4*)(tp + 4); s0 = *(const f32x4*)(tp + 16); s1 = *(const f32x4*)(tp + 20);
;                     if (fq < 2) { s0 = -s0; s1 = -s1; } }
; #pragma unroll
;                 for (int bj = 0; bj < 2; ++bj) {
;                     f32x4 v0 = acc[ai][bj][m][0] * qs, v1 = acc[ai][bj][m][1] * qs;
;                     if (gate) { const u32x4 e = *(const u32x4*)(gtab + (size_t)row * 512 + bj * HALF);
;                         float f[8] = {bflo(e.x), bfhi(e.x), bflo(e.y), bfhi(e.y), bflo(e.z), bfhi(e.z), bflo(e.w), bfhi(e.w)};
;                         if (ginv) {
; #pragma unroll
;                             for (int j = 0; j < 8; ++j) f[j] = __builtin_amdgcn_rcpf(f[j]); }
;                         v0[0] *= f[0]; v0[1] *= f[1]; v0[2] *= f[2]; v0[3] *= f[3]; v1[0] *= f[4]; v1[1] *= f[5]; v1[2] *= f[6]; v1[3] *= f[7]; }
;                     if (ropet) {
;                         f32x4 p0, p1;
; #pragma unroll
;                         for (int j = 0; j < 4; ++j) { p0[j] = __shfl_xor(v0[j], 32); p1[j] = __shfl_xor(v1[j], 32); }
;                         v0 = v0 * c0 + p0 * s0; v1 = v1 * c1 + p1 * s1;
;                     }
.LBB0_214:
	v_readlane_b32 s40, v254, 55
	v_readlane_b32 s41, v254, 56
	s_mov_b64 s[0:1], -1
	s_and_b64 vcc, exec, s[40:41]
	s_cbranch_vccz .LBB0_368
	v_lshl_add_u32 v142, s11, 8, v199
	s_lshl_b32 s0, s9, 8
	v_or_b32_e32 v146, s0, v211
	v_ashrrev_i32_e32 v147, 31, v146
	v_lshl_add_u64 v[146:147], v[146:147], 1, s[2:3]
	v_mad_u64_u32 v[180:181], s[0:1], s56, v142, 0
	v_mul_lo_u32 v148, s57, v142
	s_lshl_b32 s40, s56, 5
	s_mul_i32 s41, s56, 0xa0
	v_add_u32_e32 v181, v181, v148
	v_lshl_add_u64 v[180:181], v[180:181], 1, v[146:147]
	s_cmp_lt_i32 s9, 2
	s_cselect_b64 s[0:1], -1, 0
	s_and_b32 s13, s9, 0x7ffffffc
	s_cmp_eq_u32 s13, 12
	s_cselect_b64 s[42:43], -1, 0
	s_or_b64 s[42:43], s[0:1], s[42:43]
	s_and_b64 s[42:43], s[96:97], s[42:43]
	s_cmp_lg_u64 s[42:43], 0
	s_cselect_b32 s13, 0x3db504f3, 1.0
	v_mov_b32_e32 v140, s13
	v_mov_b32_e32 v141, s13
	s_and_b64 vcc, exec, s[96:97]
	s_cbranch_vccz .Lep1_plain
	s_cmp_lt_i32 s9, 4
	s_cbranch_scc1 .Lep1_gate
	s_add_i32 s0, s9, -12
	s_cmp_lt_u32 s0, 8
	s_cbranch_scc0 .Lep1_plain
	v_readlane_b32 s0, v254, 57
	s_nop 3
	s_cmp_lg_u32 s0, 0
	s_cbranch_scc1 .Lep1_rope
.Lep1_plain:
	v_pk_mul_f32 v[158:159], v[140:141], v[128:129]
	v_pk_mul_f32 v[160:161], v[140:141], v[130:131]
	v_pk_mul_f32 v[162:163], v[140:141], v[64:65]
	v_pk_mul_f32 v[178:179], v[140:141], v[66:67]
	v_cvt_pk_bf16_f32 v132, v158, v159
	v_cvt_pk_bf16_f32 v133, v160, v161
	v_cvt_pk_bf16_f32 v134, v162, v163
	v_cvt_pk_bf16_f32 v135, v178, v179
	global_store_dwordx4 v[180:181], v[132:135], off
	v_pk_mul_f32 v[158:159], v[140:141], v[124:125]
	v_pk_mul_f32 v[160:161], v[140:141], v[126:127]
	v_pk_mul_f32 v[162:163], v[140:141], v[60:61]
	v_pk_mul_f32 v[178:179], v[140:141], v[62:63]
	v_cvt_pk_bf16_f32 v132, v158, v159
	v_cvt_pk_bf16_f32 v133, v160, v161
	v_cvt_pk_bf16_f32 v134, v162, v163
	v_cvt_pk_bf16_f32 v135, v178, v179
	global_store_dwordx4 v[180:181], v[132:135], off offset:256
	v_add_co_u32_e32 v180, vcc, s40, v180
	s_nop 1
	v_addc_co_u32_e32 v181, vcc, 0, v181, vcc
	v_pk_mul_f32 v[158:159], v[140:141], v[120:121]
	v_pk_mul_f32 v[160:161], v[140:141], v[122:123]
	v_pk_mul_f32 v[162:163], v[140:141], v[56:57]
	v_pk_mul_f32 v[178:179], v[140:141], v[58:59]
	v_cvt_pk_bf16_f32 v132, v158, v159
	v_cvt_pk_bf16_f32 v133, v160, v161
	v_cvt_pk_bf16_f32 v134, v162, v163
	v_cvt_pk_bf16_f32 v135, v178, v179
	global_store_dwordx4 v[180:181], v[132:135], off
	v_pk_mul_f32 v[158:159], v[140:141], v[116:117]
	v_pk_mul_f32 v[160:161], v[140:141], v[118:119]
	v_pk_mul_f32 v[162:163], v[140:141], v[52:53]
	v_pk_mul_f32 v[178:179], v[140:141], v[54:55]
	v_cvt_pk_bf16_f32 v132, v158, v159
	v_cvt_pk_bf16_f32 v133, v160, v161
	v_cvt_pk_bf16_f32 v134, v162, v163
	v_cvt_pk_bf16_f32 v135, v178, v179
	global_store_dwordx4 v[180:181], v[132:135], off offset:256
	v_add_co_u32_e32 v180, vcc, s40, v180
	s_nop 1
	v_addc_co_u32_e32 v181, vcc, 0, v181, vcc
	v_pk_mul_f32 v[158:159], v[140:141], v[112:113]
	v_pk_mul_f32 v[160:161], v[140:141], v[114:115]
	v_pk_mul_f32 v[162:163], v[140:141], v[48:49]
	v_pk_mul_f32 v[178:179], v[140:141], v[50:51]
	v_cvt_pk_bf16_f32 v132, v158, v159
	v_cvt_pk_bf16_f32 v133, v160, v161
	v_cvt_pk_bf16_f32 v134, v162, v163
	v_cvt_pk_bf16_f32 v135, v178, v179
	global_store_dwordx4 v[180:181], v[132:135], off
	v_pk_mul_f32 v[158:159], v[140:141], v[108:109]
	v_pk_mul_f32 v[160:161], v[140:141], v[110:111]
	v_pk_mul_f32 v[162:163], v[140:141], v[44:45]
	v_pk_mul_f32 v[178:179], v[140:141], v[46:47]
	v_cvt_pk_bf16_f32 v132, v158, v159
	v_cvt_pk_bf16_f32 v133, v160, v161
	v_cvt_pk_bf16_f32 v134, v162, v163
	v_cvt_pk_bf16_f32 v135, v178, v179
	global_store_dwordx4 v[180:181], v[132:135], off offset:256
	v_add_co_u32_e32 v180, vcc, s40, v180
	s_nop 1
	v_addc_co_u32_e32 v181, vcc, 0, v181, vcc
	v_pk_mul_f32 v[158:159], v[140:141], v[104:105]
	v_pk_mul_f32 v[160:161], v[140:141], v[106:107]
	v_pk_mul_f32 v[162:163], v[140:141], v[40:41]
	v_pk_mul_f32 v[178:179], v[140:141], v[42:43]
	v_cvt_pk_bf16_f32 v132, v158, v159
	v_cvt_pk_bf16_f32 v133, v160, v161
	v_cvt_pk_bf16_f32 v134, v162, v163
	v_cvt_pk_bf16_f32 v135, v178, v179
	global_store_dwordx4 v[180:181], v[132:135], off
	v_pk_mul_f32 v[158:159], v[140:141], v[100:101]
	v_pk_mul_f32 v[160:161], v[140:141], v[102:103]
	v_pk_mul_f32 v[162:163], v[140:141], v[36:37]
	v_pk_mul_f32 v[178:179], v[140:141], v[38:39]
	v_cvt_pk_bf16_f32 v132, v158, v159
	v_cvt_pk_bf16_f32 v133, v160, v161
	v_cvt_pk_bf16_f32 v134, v162, v163
	v_cvt_pk_bf16_f32 v135, v178, v179
	global_store_dwordx4 v[180:181], v[132:135], off offset:256
	v_add_co_u32_e32 v180, vcc, s41, v180
	s_nop 1
	v_addc_co_u32_e32 v181, vcc, 0, v181, vcc
	v_pk_mul_f32 v[158:159], v[140:141], v[96:97]
	v_pk_mul_f32 v[160:161], v[140:141], v[98:99]
	v_pk_mul_f32 v[162:163], v[140:141], v[32:33]
	v_pk_mul_f32 v[178:179], v[140:141], v[34:35]
	v_cvt_pk_bf16_f32 v132, v158, v159
	v_cvt_pk_bf16_f32 v133, v160, v161
	v_cvt_pk_bf16_f32 v134, v162, v163
	v_cvt_pk_bf16_f32 v135, v178, v179
	global_store_dwordx4 v[180:181], v[132:135], off
	v_pk_mul_f32 v[158:159], v[140:141], v[92:93]
	v_pk_mul_f32 v[160:161], v[140:141], v[94:95]
	v_pk_mul_f32 v[162:163], v[140:141], v[28:29]
	v_pk_mul_f32 v[178:179], v[140:141], v[30:31]
	v_cvt_pk_bf16_f32 v132, v158, v159
	v_cvt_pk_bf16_f32 v133, v160, v161
	v_cvt_pk_bf16_f32 v134, v162, v163
	v_cvt_pk_bf16_f32 v135, v178, v179
	global_store_dwordx4 v[180:181], v[132:135], off offset:256
	v_add_co_u32_e32 v180, vcc, s40, v180
	s_nop 1
	v_addc_co_u32_e32 v181, vcc, 0, v181, vcc
	v_pk_mul_f32 v[158:159], v[140:141], v[88:89]
	v_pk_mul_f32 v[160:161], v[140:141], v[90:91]
	v_pk_mul_f32 v[162:163], v[140:141], v[24:25]
; __device__ __forceinline__ unsigned cvt_pk_bf16(float lo, float hi) { const f32x2v v = {lo, hi}; const b16x2v r = __builtin_convertvector(v, b16x2v); return __builtin_bit_cast(unsigned, r); }
; __device__ __forceinline__ float bflo(unsigned u) { return __uint_as_float(u << 16); }
; __device__ __forceinline__ float bfhi(unsigned u) { return __uint_as_float(u & 0xffff0000u); }
; __device__ __forceinline__ void gemm_epilogue(const GemmDesc& d, const f32x4 (&acc)[2][2][4][2], const Unit& u, int wr, int wc, int fr, int fq) {
;     ...
;                     if (gate) { const u32x4 e = *(const u32x4*)(gtab + (size_t)row * 512 + bj * HALF);
;                         float f[8] = {bflo(e.x), bfhi(e.x), bflo(e.y), bfhi(e.y), bflo(e.z), bfhi(e.z), bflo(e.w), bfhi(e.w)};
;                         if (ginv) {
; #pragma unroll
;                             for (int j = 0; j < 8; ++j) f[j] = __builtin_amdgcn_rcpf(f[j]); }
;                         v0[0] *= f[0]; v0[1] *= f[1]; v0[2] *= f[2]; v0[3] *= f[3]; v1[0] *= f[4]; v1[1] *= f[5]; v1[2] *= f[6]; v1[3] *= f[7]; }
;                     if (ropet) {
;                         f32x4 p0, p1;
; #pragma unroll
;                         for (int j = 0; j < 4; ++j) { p0[j] = __shfl_xor(v0[j], 32); p1[j] = __shfl_xor(v1[j], 32); }
;                         v0 = v0 * c0 + p0 * s0; v1 = v1 * c1 + p1 * s1;
;                     }
;                     u32x4 w; w.x = cvt_pk_bf16(v0[0], v0[1]); w.y = cvt_pk_bf16(v0[2], v0[3]); w.z = cvt_pk_bf16(v1[0], v1[1]); w.w = cvt_pk_bf16(v1[2], v1[3]);
;                     *(u32x4*)(rowp + bj * HALF) = w;
	v_pk_mul_f32 v[178:179], v[140:141], v[26:27]
	v_cvt_pk_bf16_f32 v132, v158, v159
	v_cvt_pk_bf16_f32 v133, v160, v161
	v_cvt_pk_bf16_f32 v134, v162, v163
	v_cvt_pk_bf16_f32 v135, v178, v179
	global_store_dwordx4 v[180:181], v[132:135], off
	v_pk_mul_f32 v[158:159], v[140:141], v[80:81]
	v_pk_mul_f32 v[160:161], v[140:141], v[82:83]
	v_pk_mul_f32 v[162:163], v[140:141], v[12:13]
	v_pk_mul_f32 v[178:179], v[140:141], v[14:15]
	v_cvt_pk_bf16_f32 v132, v158, v159
	v_cvt_pk_bf16_f32 v133, v160, v161
	v_cvt_pk_bf16_f32 v134, v162, v163
	v_cvt_pk_bf16_f32 v135, v178, v179
	global_store_dwordx4 v[180:181], v[132:135], off offset:256
	v_add_co_u32_e32 v180, vcc, s40, v180
	s_nop 1
	v_addc_co_u32_e32 v181, vcc, 0, v181, vcc
	v_pk_mul_f32 v[158:159], v[140:141], v[68:69]
	v_pk_mul_f32 v[160:161], v[140:141], v[70:71]
	v_pk_mul_f32 v[162:163], v[140:141], v[20:21]
	v_pk_mul_f32 v[178:179], v[140:141], v[22:23]
	v_cvt_pk_bf16_f32 v132, v158, v159
	v_cvt_pk_bf16_f32 v133, v160, v161
	v_cvt_pk_bf16_f32 v134, v162, v163
	v_cvt_pk_bf16_f32 v135, v178, v179
	global_store_dwordx4 v[180:181], v[132:135], off
	v_pk_mul_f32 v[158:159], v[140:141], v[76:77]
	v_pk_mul_f32 v[160:161], v[140:141], v[78:79]
	v_pk_mul_f32 v[162:163], v[140:141], v[8:9]
	v_pk_mul_f32 v[178:179], v[140:141], v[10:11]
	v_cvt_pk_bf16_f32 v132, v158, v159
	v_cvt_pk_bf16_f32 v133, v160, v161
	v_cvt_pk_bf16_f32 v134, v162, v163
	v_cvt_pk_bf16_f32 v135, v178, v179
	global_store_dwordx4 v[180:181], v[132:135], off offset:256
	v_add_co_u32_e32 v180, vcc, s40, v180
	s_nop 1
	v_addc_co_u32_e32 v181, vcc, 0, v181, vcc
	v_pk_mul_f32 v[158:159], v[140:141], v[84:85]
	v_pk_mul_f32 v[160:161], v[140:141], v[86:87]
	v_pk_mul_f32 v[162:163], v[140:141], v[16:17]
	v_pk_mul_f32 v[178:179], v[140:141], v[18:19]
	v_cvt_pk_bf16_f32 v132, v158, v159
	v_cvt_pk_bf16_f32 v133, v160, v161
	v_cvt_pk_bf16_f32 v134, v162, v163
	v_cvt_pk_bf16_f32 v135, v178, v179
	global_store_dwordx4 v[180:181], v[132:135], off
	v_pk_mul_f32 v[158:159], v[140:141], v[72:73]
	v_pk_mul_f32 v[160:161], v[140:141], v[74:75]
	v_pk_mul_f32 v[162:163], v[140:141], v[4:5]
	v_pk_mul_f32 v[178:179], v[140:141], v[6:7]
	v_cvt_pk_bf16_f32 v132, v158, v159
	v_cvt_pk_bf16_f32 v133, v160, v161
	v_cvt_pk_bf16_f32 v134, v162, v163
	v_cvt_pk_bf16_f32 v135, v178, v179
	global_store_dwordx4 v[180:181], v[132:135], off offset:256
	s_branch .Lep1_done
.Lep1_gate:
	s_lshl_b32 s13, s9, 9
	s_and_b32 s18, s13, 0x200
	v_mov_b32_e32 v147, 0
	v_mov_b32_e32 v146, v142
	v_lshlrev_b64 v[146:147], 10, v[146:147]
	v_lshl_add_u64 v[156:157], v[168:169], 0, s[18:19]
	v_lshl_add_u64 v[156:157], v[156:157], 0, v[146:147]
	global_load_dwordx4 v[230:233], v[156:157], off
	global_load_dwordx4 v[234:237], v[156:157], off offset:256
	v_add_co_u32_e32 v156, vcc, 0x4000, v156
	s_nop 1
	v_addc_co_u32_e32 v157, vcc, 0, v157, vcc
	global_load_dwordx4 v[238:241], v[156:157], off
	global_load_dwordx4 v[242:245], v[156:157], off offset:256
	v_add_co_u32_e32 v156, vcc, 0x4000, v156
	s_nop 1
	v_addc_co_u32_e32 v157, vcc, 0, v157, vcc
	global_load_dwordx4 v[246:249], v[156:157], off
	global_load_dwordx4 v[194:197], v[156:157], off offset:256
	v_add_co_u32_e32 v156, vcc, 0x4000, v156
	s_nop 1
	v_addc_co_u32_e32 v157, vcc, 0, v157, vcc
	global_load_dwordx4 v[220:223], v[156:157], off
	v_pk_mul_f32 v[158:159], v[140:141], v[128:129]
	v_pk_mul_f32 v[160:161], v[140:141], v[130:131]
	v_pk_mul_f32 v[162:163], v[140:141], v[64:65]
	v_pk_mul_f32 v[178:179], v[140:141], v[66:67]
	s_waitcnt vmcnt(6)
	v_lshlrev_b32_e32 v182, 16, v230
	v_and_b32_e32 v183, 0xffff0000, v230
	v_lshlrev_b32_e32 v184, 16, v231
	v_and_b32_e32 v185, 0xffff0000, v231
	v_lshlrev_b32_e32 v186, 16, v232
	v_and_b32_e32 v187, 0xffff0000, v232
	v_lshlrev_b32_e32 v188, 16, v233
	v_and_b32_e32 v189, 0xffff0000, v233
	global_load_dwordx4 v[230:233], v[156:157], off offset:256
	v_add_co_u32_e32 v156, vcc, 0x14000, v156
	s_nop 1
	v_addc_co_u32_e32 v157, vcc, 0, v157, vcc
	s_cmp_lt_i32 s9, 2
	s_cbranch_scc1 .Lep1_norcp0
	v_rcp_f32_e32 v182, v182
	v_rcp_f32_e32 v183, v183
	v_rcp_f32_e32 v184, v184
	v_rcp_f32_e32 v185, v185
	v_rcp_f32_e32 v186, v186
	v_rcp_f32_e32 v187, v187
	v_rcp_f32_e32 v188, v188
	v_rcp_f32_e32 v189, v189
	s_nop 0
.Lep1_norcp0:
	v_pk_mul_f32 v[158:159], v[158:159], v[182:183]
	v_pk_mul_f32 v[160:161], v[160:161], v[184:185]
	v_pk_mul_f32 v[162:163], v[162:163], v[186:187]
	v_pk_mul_f32 v[178:179], v[178:179], v[188:189]
	v_cvt_pk_bf16_f32 v132, v158, v159
	v_cvt_pk_bf16_f32 v133, v160, v161
	v_cvt_pk_bf16_f32 v134, v162, v163
	v_cvt_pk_bf16_f32 v135, v178, v179
	global_store_dwordx4 v[180:181], v[132:135], off
	v_pk_mul_f32 v[158:159], v[140:141], v[124:125]
	v_pk_mul_f32 v[160:161], v[140:141], v[126:127]
	v_pk_mul_f32 v[162:163], v[140:141], v[60:61]
	v_pk_mul_f32 v[178:179], v[140:141], v[62:63]
	s_waitcnt vmcnt(7)
	v_lshlrev_b32_e32 v182, 16, v234
	v_and_b32_e32 v183, 0xffff0000, v234
	v_lshlrev_b32_e32 v184, 16, v235
	v_and_b32_e32 v185, 0xffff0000, v235
	v_lshlrev_b32_e32 v186, 16, v236
	v_and_b32_e32 v187, 0xffff0000, v236
	v_lshlrev_b32_e32 v188, 16, v237
	v_and_b32_e32 v189, 0xffff0000, v237
	global_load_dwordx4 v[234:237], v[156:157], off
	s_cmp_lt_i32 s9, 2
	s_cbranch_scc1 .Lep1_norcp1
	v_rcp_f32_e32 v182, v182
	v_rcp_f32_e32 v183, v183
	v_rcp_f32_e32 v184, v184
	v_rcp_f32_e32 v185, v185
	v_rcp_f32_e32 v186, v186
	v_rcp_f32_e32 v187, v187
	v_rcp_f32_e32 v188, v188
	v_rcp_f32_e32 v189, v189
	s_nop 0
; __device__ __forceinline__ unsigned cvt_pk_bf16(float lo, float hi) { const f32x2v v = {lo, hi}; const b16x2v r = __builtin_convertvector(v, b16x2v); return __builtin_bit_cast(unsigned, r); }
; __device__ __forceinline__ float bflo(unsigned u) { return __uint_as_float(u << 16); }
; __device__ __forceinline__ float bfhi(unsigned u) { return __uint_as_float(u & 0xffff0000u); }
; __device__ __forceinline__ void gemm_epilogue(const GemmDesc& d, const f32x4 (&acc)[2][2][4][2], const Unit& u, int wr, int wc, int fr, int fq) {
;     ...
;                     if (gate) { const u32x4 e = *(const u32x4*)(gtab + (size_t)row * 512 + bj * HALF);
;                         float f[8] = {bflo(e.x), bfhi(e.x), bflo(e.y), bfhi(e.y), bflo(e.z), bfhi(e.z), bflo(e.w), bfhi(e.w)};
;                         if (ginv) {
; #pragma unroll
;                             for (int j = 0; j < 8; ++j) f[j] = __builtin_amdgcn_rcpf(f[j]); }
;                         v0[0] *= f[0]; v0[1] *= f[1]; v0[2] *= f[2]; v0[3] *= f[3]; v1[0] *= f[4]; v1[1] *= f[5]; v1[2] *= f[6]; v1[3] *= f[7]; }
;                     if (ropet) {
;                         f32x4 p0, p1;
; #pragma unroll
;                         for (int j = 0; j < 4; ++j) { p0[j] = __shfl_xor(v0[j], 32); p1[j] = __shfl_xor(v1[j], 32); }
;                         v0 = v0 * c0 + p0 * s0; v1 = v1 * c1 + p1 * s1;
;                     }
;                     u32x4 w; w.x = cvt_pk_bf16(v0[0], v0[1]); w.y = cvt_pk_bf16(v0[2], v0[3]); w.z = cvt_pk_bf16(v1[0], v1[1]); w.w = cvt_pk_bf16(v1[2], v1[3]);
;                     *(u32x4*)(rowp + bj * HALF) = w;
.Lep1_norcp1:
	v_pk_mul_f32 v[158:159], v[158:159], v[182:183]
	v_pk_mul_f32 v[160:161], v[160:161], v[184:185]
	v_pk_mul_f32 v[162:163], v[162:163], v[186:187]
	v_pk_mul_f32 v[178:179], v[178:179], v[188:189]
	v_cvt_pk_bf16_f32 v132, v158, v159
	v_cvt_pk_bf16_f32 v133, v160, v161
	v_cvt_pk_bf16_f32 v134, v162, v163
	v_cvt_pk_bf16_f32 v135, v178, v179
	global_store_dwordx4 v[180:181], v[132:135], off offset:256
	v_add_co_u32_e32 v180, vcc, s40, v180
	s_nop 1
	v_addc_co_u32_e32 v181, vcc, 0, v181, vcc
	v_pk_mul_f32 v[158:159], v[140:141], v[120:121]
	v_pk_mul_f32 v[160:161], v[140:141], v[122:123]
	v_pk_mul_f32 v[162:163], v[140:141], v[56:57]
	v_pk_mul_f32 v[178:179], v[140:141], v[58:59]
	s_waitcnt vmcnt(8)
	v_lshlrev_b32_e32 v182, 16, v238
	v_and_b32_e32 v183, 0xffff0000, v238
	v_lshlrev_b32_e32 v184, 16, v239
	v_and_b32_e32 v185, 0xffff0000, v239
	v_lshlrev_b32_e32 v186, 16, v240
	v_and_b32_e32 v187, 0xffff0000, v240
	v_lshlrev_b32_e32 v188, 16, v241
	v_and_b32_e32 v189, 0xffff0000, v241
	global_load_dwordx4 v[238:241], v[156:157], off offset:256
	v_add_co_u32_e32 v156, vcc, 0x4000, v156
	s_nop 1
	v_addc_co_u32_e32 v157, vcc, 0, v157, vcc
	s_cmp_lt_i32 s9, 2
	s_cbranch_scc1 .Lep1_norcp2
	v_rcp_f32_e32 v182, v182
	v_rcp_f32_e32 v183, v183
	v_rcp_f32_e32 v184, v184
	v_rcp_f32_e32 v185, v185
	v_rcp_f32_e32 v186, v186
	v_rcp_f32_e32 v187, v187
	v_rcp_f32_e32 v188, v188
	v_rcp_f32_e32 v189, v189
	s_nop 0
.Lep1_norcp2:
	v_pk_mul_f32 v[158:159], v[158:159], v[182:183]
	v_pk_mul_f32 v[160:161], v[160:161], v[184:185]
	v_pk_mul_f32 v[162:163], v[162:163], v[186:187]
	v_pk_mul_f32 v[178:179], v[178:179], v[188:189]
	v_cvt_pk_bf16_f32 v132, v158, v159
	v_cvt_pk_bf16_f32 v133, v160, v161
	v_cvt_pk_bf16_f32 v134, v162, v163
	v_cvt_pk_bf16_f32 v135, v178, v179
	global_store_dwordx4 v[180:181], v[132:135], off
	v_pk_mul_f32 v[158:159], v[140:141], v[116:117]
	v_pk_mul_f32 v[160:161], v[140:141], v[118:119]
	v_pk_mul_f32 v[162:163], v[140:141], v[52:53]
	v_pk_mul_f32 v[178:179], v[140:141], v[54:55]
	s_waitcnt vmcnt(9)
	v_lshlrev_b32_e32 v182, 16, v242
	v_and_b32_e32 v183, 0xffff0000, v242
	v_lshlrev_b32_e32 v184, 16, v243
	v_and_b32_e32 v185, 0xffff0000, v243
	v_lshlrev_b32_e32 v186, 16, v244
	v_and_b32_e32 v187, 0xffff0000, v244
	v_lshlrev_b32_e32 v188, 16, v245
	v_and_b32_e32 v189, 0xffff0000, v245
	global_load_dwordx4 v[242:245], v[156:157], off
	s_cmp_lt_i32 s9, 2
	s_cbranch_scc1 .Lep1_norcp3
	v_rcp_f32_e32 v182, v182
	v_rcp_f32_e32 v183, v183
	v_rcp_f32_e32 v184, v184
	v_rcp_f32_e32 v185, v185
	v_rcp_f32_e32 v186, v186
	v_rcp_f32_e32 v187, v187
	v_rcp_f32_e32 v188, v188
	v_rcp_f32_e32 v189, v189
	s_nop 0
.Lep1_norcp3:
	v_pk_mul_f32 v[158:159], v[158:159], v[182:183]
	v_pk_mul_f32 v[160:161], v[160:161], v[184:185]
	v_pk_mul_f32 v[162:163], v[162:163], v[186:187]
	v_pk_mul_f32 v[178:179], v[178:179], v[188:189]
	v_cvt_pk_bf16_f32 v132, v158, v159
	v_cvt_pk_bf16_f32 v133, v160, v161
	v_cvt_pk_bf16_f32 v134, v162, v163
	v_cvt_pk_bf16_f32 v135, v178, v179
	global_store_dwordx4 v[180:181], v[132:135], off offset:256
	v_add_co_u32_e32 v180, vcc, s40, v180
	s_nop 1
	v_addc_co_u32_e32 v181, vcc, 0, v181, vcc
	v_pk_mul_f32 v[158:159], v[140:141], v[112:113]
	v_pk_mul_f32 v[160:161], v[140:141], v[114:115]
	v_pk_mul_f32 v[162:163], v[140:141], v[48:49]
	v_pk_mul_f32 v[178:179], v[140:141], v[50:51]
	s_waitcnt vmcnt(10)
	v_lshlrev_b32_e32 v182, 16, v246
	v_and_b32_e32 v183, 0xffff0000, v246
	v_lshlrev_b32_e32 v184, 16, v247
	v_and_b32_e32 v185, 0xffff0000, v247
	v_lshlrev_b32_e32 v186, 16, v248
	v_and_b32_e32 v187, 0xffff0000, v248
	v_lshlrev_b32_e32 v188, 16, v249
	v_and_b32_e32 v189, 0xffff0000, v249
	global_load_dwordx4 v[246:249], v[156:157], off offset:256
	v_add_co_u32_e32 v156, vcc, 0x4000, v156
	s_nop 1
	v_addc_co_u32_e32 v157, vcc, 0, v157, vcc
	s_cmp_lt_i32 s9, 2
	s_cbranch_scc1 .Lep1_norcp4
	v_rcp_f32_e32 v182, v182
	v_rcp_f32_e32 v183, v183
	v_rcp_f32_e32 v184, v184
	v_rcp_f32_e32 v185, v185
	v_rcp_f32_e32 v186, v186
	v_rcp_f32_e32 v187, v187
	v_rcp_f32_e32 v188, v188
	v_rcp_f32_e32 v189, v189
	s_nop 0
.Lep1_norcp4:
	v_pk_mul_f32 v[158:159], v[158:159], v[182:183]
	v_pk_mul_f32 v[160:161], v[160:161], v[184:185]
	v_pk_mul_f32 v[162:163], v[162:163], v[186:187]
	v_pk_mul_f32 v[178:179], v[178:179], v[188:189]
	v_cvt_pk_bf16_f32 v132, v158, v159
	v_cvt_pk_bf16_f32 v133, v160, v161
	v_cvt_pk_bf16_f32 v134, v162, v163
	v_cvt_pk_bf16_f32 v135, v178, v179
	global_store_dwordx4 v[180:181], v[132:135], off
	v_pk_mul_f32 v[158:159], v[140:141], v[108:109]
	v_pk_mul_f32 v[160:161], v[140:141], v[110:111]
	v_pk_mul_f32 v[162:163], v[140:141], v[44:45]
	v_pk_mul_f32 v[178:179], v[140:141], v[46:47]
	s_waitcnt vmcnt(11)
	v_lshlrev_b32_e32 v182, 16, v194
	v_and_b32_e32 v183, 0xffff0000, v194
	v_lshlrev_b32_e32 v184, 16, v195
	v_and_b32_e32 v185, 0xffff0000, v195
	v_lshlrev_b32_e32 v186, 16, v196
	v_and_b32_e32 v187, 0xffff0000, v196
	v_lshlrev_b32_e32 v188, 16, v197
	v_and_b32_e32 v189, 0xffff0000, v197
	global_load_dwordx4 v[194:197], v[156:157], off
	s_cmp_lt_i32 s9, 2
	s_cbranch_scc1 .Lep1_norcp5
	v_rcp_f32_e32 v182, v182
	v_rcp_f32_e32 v183, v183
	v_rcp_f32_e32 v184, v184
	v_rcp_f32_e32 v185, v185
	v_rcp_f32_e32 v186, v186
	v_rcp_f32_e32 v187, v187
	v_rcp_f32_e32 v188, v188
	v_rcp_f32_e32 v189, v189
	s_nop 0
; __device__ __forceinline__ unsigned cvt_pk_bf16(float lo, float hi) { const f32x2v v = {lo, hi}; const b16x2v r = __builtin_convertvector(v, b16x2v); return __builtin_bit_cast(unsigned, r); }
; __device__ __forceinline__ float bflo(unsigned u) { return __uint_as_float(u << 16); }
; __device__ __forceinline__ float bfhi(unsigned u) { return __uint_as_float(u & 0xffff0000u); }
; __device__ __forceinline__ void gemm_epilogue(const GemmDesc& d, const f32x4 (&acc)[2][2][4][2], const Unit& u, int wr, int wc, int fr, int fq) {
;     ...
;                     if (gate) { const u32x4 e = *(const u32x4*)(gtab + (size_t)row * 512 + bj * HALF);
;                         float f[8] = {bflo(e.x), bfhi(e.x), bflo(e.y), bfhi(e.y), bflo(e.z), bfhi(e.z), bflo(e.w), bfhi(e.w)};
;                         if (ginv) {
; #pragma unroll
;                             for (int j = 0; j < 8; ++j) f[j] = __builtin_amdgcn_rcpf(f[j]); }
;                         v0[0] *= f[0]; v0[1] *= f[1]; v0[2] *= f[2]; v0[3] *= f[3]; v1[0] *= f[4]; v1[1] *= f[5]; v1[2] *= f[6]; v1[3] *= f[7]; }
;                     if (ropet) {
;                         f32x4 p0, p1;
; #pragma unroll
;                         for (int j = 0; j < 4; ++j) { p0[j] = __shfl_xor(v0[j], 32); p1[j] = __shfl_xor(v1[j], 32); }
;                         v0 = v0 * c0 + p0 * s0; v1 = v1 * c1 + p1 * s1;
;                     }
;                     u32x4 w; w.x = cvt_pk_bf16(v0[0], v0[1]); w.y = cvt_pk_bf16(v0[2], v0[3]); w.z = cvt_pk_bf16(v1[0], v1[1]); w.w = cvt_pk_bf16(v1[2], v1[3]);
;                     *(u32x4*)(rowp + bj * HALF) = w;
.Lep1_norcp5:
	v_pk_mul_f32 v[158:159], v[158:159], v[182:183]
	v_pk_mul_f32 v[160:161], v[160:161], v[184:185]
	v_pk_mul_f32 v[162:163], v[162:163], v[186:187]
	v_pk_mul_f32 v[178:179], v[178:179], v[188:189]
	v_cvt_pk_bf16_f32 v132, v158, v159
	v_cvt_pk_bf16_f32 v133, v160, v161
	v_cvt_pk_bf16_f32 v134, v162, v163
	v_cvt_pk_bf16_f32 v135, v178, v179
	global_store_dwordx4 v[180:181], v[132:135], off offset:256
	v_add_co_u32_e32 v180, vcc, s40, v180
	s_nop 1
	v_addc_co_u32_e32 v181, vcc, 0, v181, vcc
	v_pk_mul_f32 v[158:159], v[140:141], v[104:105]
	v_pk_mul_f32 v[160:161], v[140:141], v[106:107]
	v_pk_mul_f32 v[162:163], v[140:141], v[40:41]
	v_pk_mul_f32 v[178:179], v[140:141], v[42:43]
	s_waitcnt vmcnt(12)
	v_lshlrev_b32_e32 v182, 16, v220
	v_and_b32_e32 v183, 0xffff0000, v220
	v_lshlrev_b32_e32 v184, 16, v221
	v_and_b32_e32 v185, 0xffff0000, v221
	v_lshlrev_b32_e32 v186, 16, v222
	v_and_b32_e32 v187, 0xffff0000, v222
	v_lshlrev_b32_e32 v188, 16, v223
	v_and_b32_e32 v189, 0xffff0000, v223
	global_load_dwordx4 v[220:223], v[156:157], off offset:256
	v_add_co_u32_e32 v156, vcc, 0x4000, v156
	s_nop 1
	v_addc_co_u32_e32 v157, vcc, 0, v157, vcc
	s_cmp_lt_i32 s9, 2
	s_cbranch_scc1 .Lep1_norcp6
	v_rcp_f32_e32 v182, v182
	v_rcp_f32_e32 v183, v183
	v_rcp_f32_e32 v184, v184
	v_rcp_f32_e32 v185, v185
	v_rcp_f32_e32 v186, v186
	v_rcp_f32_e32 v187, v187
	v_rcp_f32_e32 v188, v188
	v_rcp_f32_e32 v189, v189
	s_nop 0
.Lep1_norcp6:
	v_pk_mul_f32 v[158:159], v[158:159], v[182:183]
	v_pk_mul_f32 v[160:161], v[160:161], v[184:185]
	v_pk_mul_f32 v[162:163], v[162:163], v[186:187]
	v_pk_mul_f32 v[178:179], v[178:179], v[188:189]
	v_cvt_pk_bf16_f32 v132, v158, v159
	v_cvt_pk_bf16_f32 v133, v160, v161
	v_cvt_pk_bf16_f32 v134, v162, v163
	v_cvt_pk_bf16_f32 v135, v178, v179
	global_store_dwordx4 v[180:181], v[132:135], off
	v_pk_mul_f32 v[158:159], v[140:141], v[100:101]
	v_pk_mul_f32 v[160:161], v[140:141], v[102:103]
	v_pk_mul_f32 v[162:163], v[140:141], v[36:37]
	v_pk_mul_f32 v[178:179], v[140:141], v[38:39]
	s_waitcnt vmcnt(13)
	v_lshlrev_b32_e32 v182, 16, v230
	v_and_b32_e32 v183, 0xffff0000, v230
	v_lshlrev_b32_e32 v184, 16, v231
	v_and_b32_e32 v185, 0xffff0000, v231
	v_lshlrev_b32_e32 v186, 16, v232
	v_and_b32_e32 v187, 0xffff0000, v232
	v_lshlrev_b32_e32 v188, 16, v233
	v_and_b32_e32 v189, 0xffff0000, v233
	global_load_dwordx4 v[230:233], v[156:157], off
	s_cmp_lt_i32 s9, 2
	s_cbranch_scc1 .Lep1_norcp7
	v_rcp_f32_e32 v182, v182
	v_rcp_f32_e32 v183, v183
	v_rcp_f32_e32 v184, v184
	v_rcp_f32_e32 v185, v185
	v_rcp_f32_e32 v186, v186
	v_rcp_f32_e32 v187, v187
	v_rcp_f32_e32 v188, v188
	v_rcp_f32_e32 v189, v189
	s_nop 0
.Lep1_norcp7:
	v_pk_mul_f32 v[158:159], v[158:159], v[182:183]
	v_pk_mul_f32 v[160:161], v[160:161], v[184:185]
	v_pk_mul_f32 v[162:163], v[162:163], v[186:187]
	v_pk_mul_f32 v[178:179], v[178:179], v[188:189]
	v_cvt_pk_bf16_f32 v132, v158, v159
	v_cvt_pk_bf16_f32 v133, v160, v161
	v_cvt_pk_bf16_f32 v134, v162, v163
	v_cvt_pk_bf16_f32 v135, v178, v179
	global_store_dwordx4 v[180:181], v[132:135], off offset:256
	v_add_co_u32_e32 v180, vcc, s41, v180
	s_nop 1
	v_addc_co_u32_e32 v181, vcc, 0, v181, vcc
	v_pk_mul_f32 v[158:159], v[140:141], v[96:97]
	v_pk_mul_f32 v[160:161], v[140:141], v[98:99]
	v_pk_mul_f32 v[162:163], v[140:141], v[32:33]
	v_pk_mul_f32 v[178:179], v[140:141], v[34:35]
	s_waitcnt vmcnt(13)
	v_lshlrev_b32_e32 v182, 16, v234
	v_and_b32_e32 v183, 0xffff0000, v234
	v_lshlrev_b32_e32 v184, 16, v235
	v_and_b32_e32 v185, 0xffff0000, v235
	v_lshlrev_b32_e32 v186, 16, v236
	v_and_b32_e32 v187, 0xffff0000, v236
	v_lshlrev_b32_e32 v188, 16, v237
	v_and_b32_e32 v189, 0xffff0000, v237
	global_load_dwordx4 v[234:237], v[156:157], off offset:256
	s_cmp_lt_i32 s9, 2
	s_cbranch_scc1 .Lep1_norcp8
	v_rcp_f32_e32 v182, v182
	v_rcp_f32_e32 v183, v183
	v_rcp_f32_e32 v184, v184
	v_rcp_f32_e32 v185, v185
	v_rcp_f32_e32 v186, v186
	v_rcp_f32_e32 v187, v187
	v_rcp_f32_e32 v188, v188
	v_rcp_f32_e32 v189, v189
	s_nop 0
.Lep1_norcp8:
	v_pk_mul_f32 v[158:159], v[158:159], v[182:183]
	v_pk_mul_f32 v[160:161], v[160:161], v[184:185]
	v_pk_mul_f32 v[162:163], v[162:163], v[186:187]
	v_pk_mul_f32 v[178:179], v[178:179], v[188:189]
	v_cvt_pk_bf16_f32 v132, v158, v159
	v_cvt_pk_bf16_f32 v133, v160, v161
	v_cvt_pk_bf16_f32 v134, v162, v163
	v_cvt_pk_bf16_f32 v135, v178, v179
	global_store_dwordx4 v[180:181], v[132:135], off
	v_pk_mul_f32 v[158:159], v[140:141], v[92:93]
	v_pk_mul_f32 v[160:161], v[140:141], v[94:95]
	v_pk_mul_f32 v[162:163], v[140:141], v[28:29]
	v_pk_mul_f32 v[178:179], v[140:141], v[30:31]
	s_waitcnt vmcnt(13)
	v_lshlrev_b32_e32 v182, 16, v238
	v_and_b32_e32 v183, 0xffff0000, v238
	v_lshlrev_b32_e32 v184, 16, v239
	v_and_b32_e32 v185, 0xffff0000, v239
	v_lshlrev_b32_e32 v186, 16, v240
	v_and_b32_e32 v187, 0xffff0000, v240
	v_lshlrev_b32_e32 v188, 16, v241
	v_and_b32_e32 v189, 0xffff0000, v241
	s_cmp_lt_i32 s9, 2
	s_cbranch_scc1 .Lep1_norcp9
	v_rcp_f32_e32 v182, v182
	v_rcp_f32_e32 v183, v183
	v_rcp_f32_e32 v184, v184
	v_rcp_f32_e32 v185, v185
	v_rcp_f32_e32 v186, v186
	v_rcp_f32_e32 v187, v187
	v_rcp_f32_e32 v188, v188
	v_rcp_f32_e32 v189, v189
	s_nop 0
; __device__ __forceinline__ unsigned cvt_pk_bf16(float lo, float hi) { const f32x2v v = {lo, hi}; const b16x2v r = __builtin_convertvector(v, b16x2v); return __builtin_bit_cast(unsigned, r); }
; __device__ __forceinline__ float bflo(unsigned u) { return __uint_as_float(u << 16); }
; __device__ __forceinline__ float bfhi(unsigned u) { return __uint_as_float(u & 0xffff0000u); }
; __device__ __forceinline__ void gemm_epilogue(const GemmDesc& d, const f32x4 (&acc)[2][2][4][2], const Unit& u, int wr, int wc, int fr, int fq) {
;     ...
;                     if (gate) { const u32x4 e = *(const u32x4*)(gtab + (size_t)row * 512 + bj * HALF);
;                         float f[8] = {bflo(e.x), bfhi(e.x), bflo(e.y), bfhi(e.y), bflo(e.z), bfhi(e.z), bflo(e.w), bfhi(e.w)};
;                         if (ginv) {
; #pragma unroll
;                             for (int j = 0; j < 8; ++j) f[j] = __builtin_amdgcn_rcpf(f[j]); }
;                         v0[0] *= f[0]; v0[1] *= f[1]; v0[2] *= f[2]; v0[3] *= f[3]; v1[0] *= f[4]; v1[1] *= f[5]; v1[2] *= f[6]; v1[3] *= f[7]; }
;                     if (ropet) {
;                         f32x4 p0, p1;
; #pragma unroll
;                         for (int j = 0; j < 4; ++j) { p0[j] = __shfl_xor(v0[j], 32); p1[j] = __shfl_xor(v1[j], 32); }
;                         v0 = v0 * c0 + p0 * s0; v1 = v1 * c1 + p1 * s1;
;                     }
;                     u32x4 w; w.x = cvt_pk_bf16(v0[0], v0[1]); w.y = cvt_pk_bf16(v0[2], v0[3]); w.z = cvt_pk_bf16(v1[0], v1[1]); w.w = cvt_pk_bf16(v1[2], v1[3]);
;                     *(u32x4*)(rowp + bj * HALF) = w;
.Lep1_norcp9:
	v_pk_mul_f32 v[158:159], v[158:159], v[182:183]
	v_pk_mul_f32 v[160:161], v[160:161], v[184:185]
	v_pk_mul_f32 v[162:163], v[162:163], v[186:187]
	v_pk_mul_f32 v[178:179], v[178:179], v[188:189]
	v_cvt_pk_bf16_f32 v132, v158, v159
	v_cvt_pk_bf16_f32 v133, v160, v161
	v_cvt_pk_bf16_f32 v134, v162, v163
	v_cvt_pk_bf16_f32 v135, v178, v179
	global_store_dwordx4 v[180:181], v[132:135], off offset:256
	v_add_co_u32_e32 v180, vcc, s40, v180
	s_nop 1
	v_addc_co_u32_e32 v181, vcc, 0, v181, vcc
	v_pk_mul_f32 v[158:159], v[140:141], v[88:89]
	v_pk_mul_f32 v[160:161], v[140:141], v[90:91]
	v_pk_mul_f32 v[162:163], v[140:141], v[24:25]
	v_pk_mul_f32 v[178:179], v[140:141], v[26:27]
	s_waitcnt vmcnt(12)
	v_lshlrev_b32_e32 v182, 16, v242
	v_and_b32_e32 v183, 0xffff0000, v242
	v_lshlrev_b32_e32 v184, 16, v243
	v_and_b32_e32 v185, 0xffff0000, v243
	v_lshlrev_b32_e32 v186, 16, v244
	v_and_b32_e32 v187, 0xffff0000, v244
	v_lshlrev_b32_e32 v188, 16, v245
	v_and_b32_e32 v189, 0xffff0000, v245
	s_cmp_lt_i32 s9, 2
	s_cbranch_scc1 .Lep1_norcp10
	v_rcp_f32_e32 v182, v182
	v_rcp_f32_e32 v183, v183
	v_rcp_f32_e32 v184, v184
	v_rcp_f32_e32 v185, v185
	v_rcp_f32_e32 v186, v186
	v_rcp_f32_e32 v187, v187
	v_rcp_f32_e32 v188, v188
	v_rcp_f32_e32 v189, v189
	s_nop 0
.Lep1_norcp10:
	v_pk_mul_f32 v[158:159], v[158:159], v[182:183]
	v_pk_mul_f32 v[160:161], v[160:161], v[184:185]
	v_pk_mul_f32 v[162:163], v[162:163], v[186:187]
	v_pk_mul_f32 v[178:179], v[178:179], v[188:189]
	v_cvt_pk_bf16_f32 v132, v158, v159
	v_cvt_pk_bf16_f32 v133, v160, v161
	v_cvt_pk_bf16_f32 v134, v162, v163
	v_cvt_pk_bf16_f32 v135, v178, v179
	global_store_dwordx4 v[180:181], v[132:135], off
	v_pk_mul_f32 v[158:159], v[140:141], v[80:81]
	v_pk_mul_f32 v[160:161], v[140:141], v[82:83]
	v_pk_mul_f32 v[162:163], v[140:141], v[12:13]
	v_pk_mul_f32 v[178:179], v[140:141], v[14:15]
	s_waitcnt vmcnt(11)
	v_lshlrev_b32_e32 v182, 16, v246
	v_and_b32_e32 v183, 0xffff0000, v246
	v_lshlrev_b32_e32 v184, 16, v247
	v_and_b32_e32 v185, 0xffff0000, v247
	v_lshlrev_b32_e32 v186, 16, v248
	v_and_b32_e32 v187, 0xffff0000, v248
	v_lshlrev_b32_e32 v188, 16, v249
	v_and_b32_e32 v189, 0xffff0000, v249
	s_cmp_lt_i32 s9, 2
	s_cbranch_scc1 .Lep1_norcp11
	v_rcp_f32_e32 v182, v182
	v_rcp_f32_e32 v183, v183
	v_rcp_f32_e32 v184, v184
	v_rcp_f32_e32 v185, v185
	v_rcp_f32_e32 v186, v186
	v_rcp_f32_e32 v187, v187
	v_rcp_f32_e32 v188, v188
	v_rcp_f32_e32 v189, v189
	s_nop 0
.Lep1_norcp11:
	v_pk_mul_f32 v[158:159], v[158:159], v[182:183]
	v_pk_mul_f32 v[160:161], v[160:161], v[184:185]
	v_pk_mul_f32 v[162:163], v[162:163], v[186:187]
	v_pk_mul_f32 v[178:179], v[178:179], v[188:189]
	v_cvt_pk_bf16_f32 v132, v158, v159
	v_cvt_pk_bf16_f32 v133, v160, v161
	v_cvt_pk_bf16_f32 v134, v162, v163
	v_cvt_pk_bf16_f32 v135, v178, v179
	global_store_dwordx4 v[180:181], v[132:135], off offset:256
	v_add_co_u32_e32 v180, vcc, s40, v180
	s_nop 1
	v_addc_co_u32_e32 v181, vcc, 0, v181, vcc
	v_pk_mul_f32 v[158:159], v[140:141], v[68:69]
	v_pk_mul_f32 v[160:161], v[140:141], v[70:71]
	v_pk_mul_f32 v[162:163], v[140:141], v[20:21]
	v_pk_mul_f32 v[178:179], v[140:141], v[22:23]
	s_waitcnt vmcnt(10)
	v_lshlrev_b32_e32 v182, 16, v194
	v_and_b32_e32 v183, 0xffff0000, v194
	v_lshlrev_b32_e32 v184, 16, v195
	v_and_b32_e32 v185, 0xffff0000, v195
	v_lshlrev_b32_e32 v186, 16, v196
	v_and_b32_e32 v187, 0xffff0000, v196
	v_lshlrev_b32_e32 v188, 16, v197
	v_and_b32_e32 v189, 0xffff0000, v197
	s_cmp_lt_i32 s9, 2
	s_cbranch_scc1 .Lep1_norcp12
	v_rcp_f32_e32 v182, v182
	v_rcp_f32_e32 v183, v183
	v_rcp_f32_e32 v184, v184
	v_rcp_f32_e32 v185, v185
	v_rcp_f32_e32 v186, v186
	v_rcp_f32_e32 v187, v187
	v_rcp_f32_e32 v188, v188
	v_rcp_f32_e32 v189, v189
	s_nop 0
.Lep1_norcp12:
	v_pk_mul_f32 v[158:159], v[158:159], v[182:183]
	v_pk_mul_f32 v[160:161], v[160:161], v[184:185]
	v_pk_mul_f32 v[162:163], v[162:163], v[186:187]
	v_pk_mul_f32 v[178:179], v[178:179], v[188:189]
	v_cvt_pk_bf16_f32 v132, v158, v159
	v_cvt_pk_bf16_f32 v133, v160, v161
	v_cvt_pk_bf16_f32 v134, v162, v163
	v_cvt_pk_bf16_f32 v135, v178, v179
	global_store_dwordx4 v[180:181], v[132:135], off
	v_pk_mul_f32 v[158:159], v[140:141], v[76:77]
	v_pk_mul_f32 v[160:161], v[140:141], v[78:79]
	v_pk_mul_f32 v[162:163], v[140:141], v[8:9]
	v_pk_mul_f32 v[178:179], v[140:141], v[10:11]
	s_waitcnt vmcnt(9)
	v_lshlrev_b32_e32 v182, 16, v220
	v_and_b32_e32 v183, 0xffff0000, v220
	v_lshlrev_b32_e32 v184, 16, v221
	v_and_b32_e32 v185, 0xffff0000, v221
	v_lshlrev_b32_e32 v186, 16, v222
	v_and_b32_e32 v187, 0xffff0000, v222
	v_lshlrev_b32_e32 v188, 16, v223
	v_and_b32_e32 v189, 0xffff0000, v223
	s_cmp_lt_i32 s9, 2
	s_cbranch_scc1 .Lep1_norcp13
	v_rcp_f32_e32 v182, v182
	v_rcp_f32_e32 v183, v183
	v_rcp_f32_e32 v184, v184
	v_rcp_f32_e32 v185, v185
	v_rcp_f32_e32 v186, v186
	v_rcp_f32_e32 v187, v187
	v_rcp_f32_e32 v188, v188
	v_rcp_f32_e32 v189, v189
	s_nop 0
.Lep1_norcp13:
	v_pk_mul_f32 v[158:159], v[158:159], v[182:183]
	v_pk_mul_f32 v[160:161], v[160:161], v[184:185]
	v_pk_mul_f32 v[162:163], v[162:163], v[186:187]
	v_pk_mul_f32 v[178:179], v[178:179], v[188:189]
	v_cvt_pk_bf16_f32 v132, v158, v159
	v_cvt_pk_bf16_f32 v133, v160, v161
	v_cvt_pk_bf16_f32 v134, v162, v163
	v_cvt_pk_bf16_f32 v135, v178, v179
	global_store_dwordx4 v[180:181], v[132:135], off offset:256
	v_add_co_u32_e32 v180, vcc, s40, v180
	s_nop 1
	v_addc_co_u32_e32 v181, vcc, 0, v181, vcc
	v_pk_mul_f32 v[158:159], v[140:141], v[84:85]
	v_pk_mul_f32 v[160:161], v[140:141], v[86:87]
	v_pk_mul_f32 v[162:163], v[140:141], v[16:17]
	v_pk_mul_f32 v[178:179], v[140:141], v[18:19]
	s_waitcnt vmcnt(8)
	v_lshlrev_b32_e32 v182, 16, v230
	v_and_b32_e32 v183, 0xffff0000, v230
	v_lshlrev_b32_e32 v184, 16, v231
	v_and_b32_e32 v185, 0xffff0000, v231
	v_lshlrev_b32_e32 v186, 16, v232
	v_and_b32_e32 v187, 0xffff0000, v232
	v_lshlrev_b32_e32 v188, 16, v233
	v_and_b32_e32 v189, 0xffff0000, v233
	s_cmp_lt_i32 s9, 2
	s_cbranch_scc1 .Lep1_norcp14
	v_rcp_f32_e32 v182, v182
	v_rcp_f32_e32 v183, v183
	v_rcp_f32_e32 v184, v184
	v_rcp_f32_e32 v185, v185
	v_rcp_f32_e32 v186, v186
	v_rcp_f32_e32 v187, v187
	v_rcp_f32_e32 v188, v188
	v_rcp_f32_e32 v189, v189
	s_nop 0
; __device__ __forceinline__ unsigned cvt_pk_bf16(float lo, float hi) { const f32x2v v = {lo, hi}; const b16x2v r = __builtin_convertvector(v, b16x2v); return __builtin_bit_cast(unsigned, r); }
; __device__ __forceinline__ float bflo(unsigned u) { return __uint_as_float(u << 16); }
; __device__ __forceinline__ float bfhi(unsigned u) { return __uint_as_float(u & 0xffff0000u); }
; __device__ __forceinline__ void gemm_epilogue(const GemmDesc& d, const f32x4 (&acc)[2][2][4][2], const Unit& u, int wr, int wc, int fr, int fq) {
;     ...
;                 if (ropet) { const float* tp = d.rope + (size_t)row * 32 + 8 * (fq & 1); c0 = *(const f32x4*)tp; c1 = *(const f32x4*)(tp + 4); s0 = *(const f32x4*)(tp + 16); s1 = *(const f32x4*)(tp + 20);
;                     if (fq < 2) { s0 = -s0; s1 = -s1; } }
; #pragma unroll
;                 for (int bj = 0; bj < 2; ++bj) {
;                     f32x4 v0 = acc[ai][bj][m][0] * qs, v1 = acc[ai][bj][m][1] * qs;
;                     if (gate) { const u32x4 e = *(const u32x4*)(gtab + (size_t)row * 512 + bj * HALF);
;                         float f[8] = {bflo(e.x), bfhi(e.x), bflo(e.y), bfhi(e.y), bflo(e.z), bfhi(e.z), bflo(e.w), bfhi(e.w)};
;                         if (ginv) {
; #pragma unroll
;                             for (int j = 0; j < 8; ++j) f[j] = __builtin_amdgcn_rcpf(f[j]); }
;                         v0[0] *= f[0]; v0[1] *= f[1]; v0[2] *= f[2]; v0[3] *= f[3]; v1[0] *= f[4]; v1[1] *= f[5]; v1[2] *= f[6]; v1[3] *= f[7]; }
;                     if (ropet) {
;                         f32x4 p0, p1;
; #pragma unroll
;                         for (int j = 0; j < 4; ++j) { p0[j] = __shfl_xor(v0[j], 32); p1[j] = __shfl_xor(v1[j], 32); }
;                         v0 = v0 * c0 + p0 * s0; v1 = v1 * c1 + p1 * s1;
;                     }
;                     u32x4 w; w.x = cvt_pk_bf16(v0[0], v0[1]); w.y = cvt_pk_bf16(v0[2], v0[3]); w.z = cvt_pk_bf16(v1[0], v1[1]); w.w = cvt_pk_bf16(v1[2], v1[3]);
;                     *(u32x4*)(rowp + bj * HALF) = w;
.Lep1_norcp14:
	v_pk_mul_f32 v[158:159], v[158:159], v[182:183]
	v_pk_mul_f32 v[160:161], v[160:161], v[184:185]
	v_pk_mul_f32 v[162:163], v[162:163], v[186:187]
	v_pk_mul_f32 v[178:179], v[178:179], v[188:189]
	v_cvt_pk_bf16_f32 v132, v158, v159
	v_cvt_pk_bf16_f32 v133, v160, v161
	v_cvt_pk_bf16_f32 v134, v162, v163
	v_cvt_pk_bf16_f32 v135, v178, v179
	global_store_dwordx4 v[180:181], v[132:135], off
	v_pk_mul_f32 v[158:159], v[140:141], v[72:73]
	v_pk_mul_f32 v[160:161], v[140:141], v[74:75]
	v_pk_mul_f32 v[162:163], v[140:141], v[4:5]
	v_pk_mul_f32 v[178:179], v[140:141], v[6:7]
	s_waitcnt vmcnt(7)
	v_lshlrev_b32_e32 v182, 16, v234
	v_and_b32_e32 v183, 0xffff0000, v234
	v_lshlrev_b32_e32 v184, 16, v235
	v_and_b32_e32 v185, 0xffff0000, v235
	v_lshlrev_b32_e32 v186, 16, v236
	v_and_b32_e32 v187, 0xffff0000, v236
	v_lshlrev_b32_e32 v188, 16, v237
	v_and_b32_e32 v189, 0xffff0000, v237
	s_cmp_lt_i32 s9, 2
	s_cbranch_scc1 .Lep1_norcp15
	v_rcp_f32_e32 v182, v182
	v_rcp_f32_e32 v183, v183
	v_rcp_f32_e32 v184, v184
	v_rcp_f32_e32 v185, v185
	v_rcp_f32_e32 v186, v186
	v_rcp_f32_e32 v187, v187
	v_rcp_f32_e32 v188, v188
	v_rcp_f32_e32 v189, v189
	s_nop 0
.Lep1_norcp15:
	v_pk_mul_f32 v[158:159], v[158:159], v[182:183]
	v_pk_mul_f32 v[160:161], v[160:161], v[184:185]
	v_pk_mul_f32 v[162:163], v[162:163], v[186:187]
	v_pk_mul_f32 v[178:179], v[178:179], v[188:189]
	v_cvt_pk_bf16_f32 v132, v158, v159
	v_cvt_pk_bf16_f32 v133, v160, v161
	v_cvt_pk_bf16_f32 v134, v162, v163
	v_cvt_pk_bf16_f32 v135, v178, v179
	global_store_dwordx4 v[180:181], v[132:135], off offset:256
	s_branch .Lep1_done
.Lep1_rope:
	v_lshlrev_b32_e32 v143, 2, v217
	v_mov_b32_e32 v144, 0x80000000
	v_cndmask_b32_e64 v144, 0, v144, s[36:37]
	v_mov_b32_e32 v147, 0
	v_mov_b32_e32 v146, v142
	v_lshlrev_b64 v[146:147], 7, v[146:147]
	v_lshl_add_u64 v[156:157], v[170:171], 0, v[146:147]
	global_load_dwordx4 v[230:233], v[156:157], off
	global_load_dwordx4 v[234:237], v[156:157], off offset:16
	global_load_dwordx4 v[238:241], v[156:157], off offset:64
	global_load_dwordx4 v[242:245], v[156:157], off offset:80
	v_add_co_u32_e32 v156, vcc, 0x800, v156
	s_nop 1
	v_addc_co_u32_e32 v157, vcc, 0, v157, vcc
	global_load_dwordx4 v[246:249], v[156:157], off
	global_load_dwordx4 v[194:197], v[156:157], off offset:16
	global_load_dwordx4 v[220:223], v[156:157], off offset:64
	global_load_dwordx4 v[190:193], v[156:157], off offset:80
	v_add_co_u32_e32 v156, vcc, 0x800, v156
	s_nop 1
	v_addc_co_u32_e32 v157, vcc, 0, v157, vcc
	v_pk_mul_f32 v[158:159], v[140:141], v[128:129]
	v_pk_mul_f32 v[160:161], v[140:141], v[130:131]
	v_pk_mul_f32 v[162:163], v[140:141], v[64:65]
	v_pk_mul_f32 v[178:179], v[140:141], v[66:67]
	ds_bpermute_b32 v182, v143, v158
	ds_bpermute_b32 v183, v143, v159
	ds_bpermute_b32 v184, v143, v160
	ds_bpermute_b32 v185, v143, v161
	ds_bpermute_b32 v186, v143, v162
	ds_bpermute_b32 v187, v143, v163
	ds_bpermute_b32 v188, v143, v178
	ds_bpermute_b32 v189, v143, v179
	s_waitcnt vmcnt(4)
	v_xor_b32_e32 v238, v144, v238
	v_xor_b32_e32 v239, v144, v239
	v_xor_b32_e32 v240, v144, v240
	v_xor_b32_e32 v241, v144, v241
	v_xor_b32_e32 v242, v144, v242
	v_xor_b32_e32 v243, v144, v243
	v_xor_b32_e32 v244, v144, v244
	v_xor_b32_e32 v245, v144, v245
	s_waitcnt lgkmcnt(0)
	v_pk_mul_f32 v[182:183], v[238:239], v[182:183]
	v_pk_mul_f32 v[184:185], v[240:241], v[184:185]
	v_pk_mul_f32 v[186:187], v[242:243], v[186:187]
	v_pk_mul_f32 v[188:189], v[244:245], v[188:189]
	v_pk_fma_f32 v[158:159], v[230:231], v[158:159], v[182:183]
	v_pk_fma_f32 v[160:161], v[232:233], v[160:161], v[184:185]
	v_pk_fma_f32 v[162:163], v[234:235], v[162:163], v[186:187]
	v_pk_fma_f32 v[178:179], v[236:237], v[178:179], v[188:189]
	v_cvt_pk_bf16_f32 v132, v158, v159
	v_cvt_pk_bf16_f32 v133, v160, v161
	v_cvt_pk_bf16_f32 v134, v162, v163
	v_cvt_pk_bf16_f32 v135, v178, v179
	global_store_dwordx4 v[180:181], v[132:135], off
	v_pk_mul_f32 v[158:159], v[140:141], v[124:125]
	v_pk_mul_f32 v[160:161], v[140:141], v[126:127]
	v_pk_mul_f32 v[162:163], v[140:141], v[60:61]
	v_pk_mul_f32 v[178:179], v[140:141], v[62:63]
	ds_bpermute_b32 v182, v143, v158
	ds_bpermute_b32 v183, v143, v159
	ds_bpermute_b32 v184, v143, v160
	ds_bpermute_b32 v185, v143, v161
	ds_bpermute_b32 v186, v143, v162
	ds_bpermute_b32 v187, v143, v163
	ds_bpermute_b32 v188, v143, v178
	ds_bpermute_b32 v189, v143, v179
	s_waitcnt lgkmcnt(0)
	v_pk_mul_f32 v[182:183], v[238:239], v[182:183]
	v_pk_mul_f32 v[184:185], v[240:241], v[184:185]
	v_pk_mul_f32 v[186:187], v[242:243], v[186:187]
	v_pk_mul_f32 v[188:189], v[244:245], v[188:189]
	v_pk_fma_f32 v[158:159], v[230:231], v[158:159], v[182:183]
	v_pk_fma_f32 v[160:161], v[232:233], v[160:161], v[184:185]
	v_pk_fma_f32 v[162:163], v[234:235], v[162:163], v[186:187]
	v_pk_fma_f32 v[178:179], v[236:237], v[178:179], v[188:189]
	v_cvt_pk_bf16_f32 v132, v158, v159
	v_cvt_pk_bf16_f32 v133, v160, v161
	v_cvt_pk_bf16_f32 v134, v162, v163
	v_cvt_pk_bf16_f32 v135, v178, v179
	global_store_dwordx4 v[180:181], v[132:135], off offset:256
	v_add_co_u32_e32 v180, vcc, s40, v180
	s_nop 1
	v_addc_co_u32_e32 v181, vcc, 0, v181, vcc
	global_load_dwordx4 v[128:131], v[156:157], off
	global_load_dwordx4 v[64:67], v[156:157], off offset:16
	global_load_dwordx4 v[124:127], v[156:157], off offset:64
	global_load_dwordx4 v[60:63], v[156:157], off offset:80
	v_add_co_u32_e32 v156, vcc, 0x800, v156
	s_nop 1
	v_addc_co_u32_e32 v157, vcc, 0, v157, vcc
	v_pk_mul_f32 v[158:159], v[140:141], v[120:121]
	v_pk_mul_f32 v[160:161], v[140:141], v[122:123]
	v_pk_mul_f32 v[162:163], v[140:141], v[56:57]
	v_pk_mul_f32 v[178:179], v[140:141], v[58:59]
	ds_bpermute_b32 v182, v143, v158
	ds_bpermute_b32 v183, v143, v159
	ds_bpermute_b32 v184, v143, v160
	ds_bpermute_b32 v185, v143, v161
	ds_bpermute_b32 v186, v143, v162
	ds_bpermute_b32 v187, v143, v163
	ds_bpermute_b32 v188, v143, v178
	ds_bpermute_b32 v189, v143, v179
	s_waitcnt vmcnt(6)
; __device__ __forceinline__ unsigned cvt_pk_bf16(float lo, float hi) { const f32x2v v = {lo, hi}; const b16x2v r = __builtin_convertvector(v, b16x2v); return __builtin_bit_cast(unsigned, r); }
; __device__ __forceinline__ float bflo(unsigned u) { return __uint_as_float(u << 16); }
; __device__ __forceinline__ float bfhi(unsigned u) { return __uint_as_float(u & 0xffff0000u); }
; __device__ __forceinline__ void gemm_epilogue(const GemmDesc& d, const f32x4 (&acc)[2][2][4][2], const Unit& u, int wr, int wc, int fr, int fq) {
;     ...
;                 if (ropet) { const float* tp = d.rope + (size_t)row * 32 + 8 * (fq & 1); c0 = *(const f32x4*)tp; c1 = *(const f32x4*)(tp + 4); s0 = *(const f32x4*)(tp + 16); s1 = *(const f32x4*)(tp + 20);
;                     if (fq < 2) { s0 = -s0; s1 = -s1; } }
; #pragma unroll
;                 for (int bj = 0; bj < 2; ++bj) {
;                     f32x4 v0 = acc[ai][bj][m][0] * qs, v1 = acc[ai][bj][m][1] * qs;
;                     if (gate) { const u32x4 e = *(const u32x4*)(gtab + (size_t)row * 512 + bj * HALF);
;                         float f[8] = {bflo(e.x), bfhi(e.x), bflo(e.y), bfhi(e.y), bflo(e.z), bfhi(e.z), bflo(e.w), bfhi(e.w)};
;                         if (ginv) {
; #pragma unroll
;                             for (int j = 0; j < 8; ++j) f[j] = __builtin_amdgcn_rcpf(f[j]); }
;                         v0[0] *= f[0]; v0[1] *= f[1]; v0[2] *= f[2]; v0[3] *= f[3]; v1[0] *= f[4]; v1[1] *= f[5]; v1[2] *= f[6]; v1[3] *= f[7]; }
;                     if (ropet) {
;                         f32x4 p0, p1;
; #pragma unroll
;                         for (int j = 0; j < 4; ++j) { p0[j] = __shfl_xor(v0[j], 32); p1[j] = __shfl_xor(v1[j], 32); }
;                         v0 = v0 * c0 + p0 * s0; v1 = v1 * c1 + p1 * s1;
;                     }
;                     u32x4 w; w.x = cvt_pk_bf16(v0[0], v0[1]); w.y = cvt_pk_bf16(v0[2], v0[3]); w.z = cvt_pk_bf16(v1[0], v1[1]); w.w = cvt_pk_bf16(v1[2], v1[3]);
;                     *(u32x4*)(rowp + bj * HALF) = w;
	v_xor_b32_e32 v220, v144, v220
	v_xor_b32_e32 v221, v144, v221
	v_xor_b32_e32 v222, v144, v222
	v_xor_b32_e32 v223, v144, v223
	v_xor_b32_e32 v190, v144, v190
	v_xor_b32_e32 v191, v144, v191
	v_xor_b32_e32 v192, v144, v192
	v_xor_b32_e32 v193, v144, v193
	s_waitcnt lgkmcnt(0)
	v_pk_mul_f32 v[182:183], v[220:221], v[182:183]
	v_pk_mul_f32 v[184:185], v[222:223], v[184:185]
	v_pk_mul_f32 v[186:187], v[190:191], v[186:187]
	v_pk_mul_f32 v[188:189], v[192:193], v[188:189]
	v_pk_fma_f32 v[158:159], v[246:247], v[158:159], v[182:183]
	v_pk_fma_f32 v[160:161], v[248:249], v[160:161], v[184:185]
	v_pk_fma_f32 v[162:163], v[194:195], v[162:163], v[186:187]
	v_pk_fma_f32 v[178:179], v[196:197], v[178:179], v[188:189]
	v_cvt_pk_bf16_f32 v132, v158, v159
	v_cvt_pk_bf16_f32 v133, v160, v161
	v_cvt_pk_bf16_f32 v134, v162, v163
	v_cvt_pk_bf16_f32 v135, v178, v179
	global_store_dwordx4 v[180:181], v[132:135], off
	v_pk_mul_f32 v[158:159], v[140:141], v[116:117]
	v_pk_mul_f32 v[160:161], v[140:141], v[118:119]
	v_pk_mul_f32 v[162:163], v[140:141], v[52:53]
	v_pk_mul_f32 v[178:179], v[140:141], v[54:55]
	ds_bpermute_b32 v182, v143, v158
	ds_bpermute_b32 v183, v143, v159
	ds_bpermute_b32 v184, v143, v160
	ds_bpermute_b32 v185, v143, v161
	ds_bpermute_b32 v186, v143, v162
	ds_bpermute_b32 v187, v143, v163
	ds_bpermute_b32 v188, v143, v178
	ds_bpermute_b32 v189, v143, v179
	s_waitcnt lgkmcnt(0)
	v_pk_mul_f32 v[182:183], v[220:221], v[182:183]
	v_pk_mul_f32 v[184:185], v[222:223], v[184:185]
	v_pk_mul_f32 v[186:187], v[190:191], v[186:187]
	v_pk_mul_f32 v[188:189], v[192:193], v[188:189]
	v_pk_fma_f32 v[158:159], v[246:247], v[158:159], v[182:183]
	v_pk_fma_f32 v[160:161], v[248:249], v[160:161], v[184:185]
	v_pk_fma_f32 v[162:163], v[194:195], v[162:163], v[186:187]
	v_pk_fma_f32 v[178:179], v[196:197], v[178:179], v[188:189]
	v_cvt_pk_bf16_f32 v132, v158, v159
	v_cvt_pk_bf16_f32 v133, v160, v161
	v_cvt_pk_bf16_f32 v134, v162, v163
	v_cvt_pk_bf16_f32 v135, v178, v179
	global_store_dwordx4 v[180:181], v[132:135], off offset:256
	v_add_co_u32_e32 v180, vcc, s40, v180
	s_nop 1
	v_addc_co_u32_e32 v181, vcc, 0, v181, vcc
	global_load_dwordx4 v[120:123], v[156:157], off
	global_load_dwordx4 v[56:59], v[156:157], off offset:16
	global_load_dwordx4 v[116:119], v[156:157], off offset:64
	global_load_dwordx4 v[52:55], v[156:157], off offset:80
	v_add_co_u32_e32 v156, vcc, 0x2800, v156
	s_nop 1
	v_addc_co_u32_e32 v157, vcc, 0, v157, vcc
	v_pk_mul_f32 v[158:159], v[140:141], v[112:113]
	v_pk_mul_f32 v[160:161], v[140:141], v[114:115]
	v_pk_mul_f32 v[162:163], v[140:141], v[48:49]
	v_pk_mul_f32 v[178:179], v[140:141], v[50:51]
	ds_bpermute_b32 v182, v143, v158
	ds_bpermute_b32 v183, v143, v159
	ds_bpermute_b32 v184, v143, v160
	ds_bpermute_b32 v185, v143, v161
	ds_bpermute_b32 v186, v143, v162
	ds_bpermute_b32 v187, v143, v163
	ds_bpermute_b32 v188, v143, v178
	ds_bpermute_b32 v189, v143, v179
	s_waitcnt vmcnt(6)
	v_xor_b32_e32 v124, v144, v124
	v_xor_b32_e32 v125, v144, v125
	v_xor_b32_e32 v126, v144, v126
	v_xor_b32_e32 v127, v144, v127
	v_xor_b32_e32 v60, v144, v60
	v_xor_b32_e32 v61, v144, v61
	v_xor_b32_e32 v62, v144, v62
	v_xor_b32_e32 v63, v144, v63
	s_waitcnt lgkmcnt(0)
	v_pk_mul_f32 v[182:183], v[124:125], v[182:183]
	v_pk_mul_f32 v[184:185], v[126:127], v[184:185]
	v_pk_mul_f32 v[186:187], v[60:61], v[186:187]
	v_pk_mul_f32 v[188:189], v[62:63], v[188:189]
	v_pk_fma_f32 v[158:159], v[128:129], v[158:159], v[182:183]
	v_pk_fma_f32 v[160:161], v[130:131], v[160:161], v[184:185]
	v_pk_fma_f32 v[162:163], v[64:65], v[162:163], v[186:187]
	v_pk_fma_f32 v[178:179], v[66:67], v[178:179], v[188:189]
	v_cvt_pk_bf16_f32 v132, v158, v159
	v_cvt_pk_bf16_f32 v133, v160, v161
	v_cvt_pk_bf16_f32 v134, v162, v163
	v_cvt_pk_bf16_f32 v135, v178, v179
	global_store_dwordx4 v[180:181], v[132:135], off
	v_pk_mul_f32 v[158:159], v[140:141], v[108:109]
	v_pk_mul_f32 v[160:161], v[140:141], v[110:111]
	v_pk_mul_f32 v[162:163], v[140:141], v[44:45]
	v_pk_mul_f32 v[178:179], v[140:141], v[46:47]
	ds_bpermute_b32 v182, v143, v158
	ds_bpermute_b32 v183, v143, v159
	ds_bpermute_b32 v184, v143, v160
	ds_bpermute_b32 v185, v143, v161
	ds_bpermute_b32 v186, v143, v162
	ds_bpermute_b32 v187, v143, v163
	ds_bpermute_b32 v188, v143, v178
	ds_bpermute_b32 v189, v143, v179
	s_waitcnt lgkmcnt(0)
	v_pk_mul_f32 v[182:183], v[124:125], v[182:183]
	v_pk_mul_f32 v[184:185], v[126:127], v[184:185]
	v_pk_mul_f32 v[186:187], v[60:61], v[186:187]
	v_pk_mul_f32 v[188:189], v[62:63], v[188:189]
	v_pk_fma_f32 v[158:159], v[128:129], v[158:159], v[182:183]
	v_pk_fma_f32 v[160:161], v[130:131], v[160:161], v[184:185]
	v_pk_fma_f32 v[162:163], v[64:65], v[162:163], v[186:187]
	v_pk_fma_f32 v[178:179], v[66:67], v[178:179], v[188:189]
	v_cvt_pk_bf16_f32 v132, v158, v159
	v_cvt_pk_bf16_f32 v133, v160, v161
	v_cvt_pk_bf16_f32 v134, v162, v163
	v_cvt_pk_bf16_f32 v135, v178, v179
	global_store_dwordx4 v[180:181], v[132:135], off offset:256
	v_add_co_u32_e32 v180, vcc, s40, v180
	s_nop 1
	v_addc_co_u32_e32 v181, vcc, 0, v181, vcc
	global_load_dwordx4 v[112:115], v[156:157], off
	global_load_dwordx4 v[48:51], v[156:157], off offset:16
	global_load_dwordx4 v[108:111], v[156:157], off offset:64
	global_load_dwordx4 v[44:47], v[156:157], off offset:80
	v_add_co_u32_e32 v156, vcc, 0x800, v156
	s_nop 1
	v_addc_co_u32_e32 v157, vcc, 0, v157, vcc
	v_pk_mul_f32 v[158:159], v[140:141], v[104:105]
	v_pk_mul_f32 v[160:161], v[140:141], v[106:107]
	v_pk_mul_f32 v[162:163], v[140:141], v[40:41]
	v_pk_mul_f32 v[178:179], v[140:141], v[42:43]
	ds_bpermute_b32 v182, v143, v158
	ds_bpermute_b32 v183, v143, v159
	ds_bpermute_b32 v184, v143, v160
	ds_bpermute_b32 v185, v143, v161
	ds_bpermute_b32 v186, v143, v162
	ds_bpermute_b32 v187, v143, v163
	ds_bpermute_b32 v188, v143, v178
	ds_bpermute_b32 v189, v143, v179
	s_waitcnt vmcnt(6)
; __device__ __forceinline__ unsigned cvt_pk_bf16(float lo, float hi) { const f32x2v v = {lo, hi}; const b16x2v r = __builtin_convertvector(v, b16x2v); return __builtin_bit_cast(unsigned, r); }
; __device__ __forceinline__ float bflo(unsigned u) { return __uint_as_float(u << 16); }
; __device__ __forceinline__ float bfhi(unsigned u) { return __uint_as_float(u & 0xffff0000u); }
; __device__ __forceinline__ void gemm_epilogue(const GemmDesc& d, const f32x4 (&acc)[2][2][4][2], const Unit& u, int wr, int wc, int fr, int fq) {
;     ...
;                 if (ropet) { const float* tp = d.rope + (size_t)row * 32 + 8 * (fq & 1); c0 = *(const f32x4*)tp; c1 = *(const f32x4*)(tp + 4); s0 = *(const f32x4*)(tp + 16); s1 = *(const f32x4*)(tp + 20);
;                     if (fq < 2) { s0 = -s0; s1 = -s1; } }
; #pragma unroll
;                 for (int bj = 0; bj < 2; ++bj) {
;                     f32x4 v0 = acc[ai][bj][m][0] * qs, v1 = acc[ai][bj][m][1] * qs;
;                     if (gate) { const u32x4 e = *(const u32x4*)(gtab + (size_t)row * 512 + bj * HALF);
;                         float f[8] = {bflo(e.x), bfhi(e.x), bflo(e.y), bfhi(e.y), bflo(e.z), bfhi(e.z), bflo(e.w), bfhi(e.w)};
;                         if (ginv) {
; #pragma unroll
;                             for (int j = 0; j < 8; ++j) f[j] = __builtin_amdgcn_rcpf(f[j]); }
;                         v0[0] *= f[0]; v0[1] *= f[1]; v0[2] *= f[2]; v0[3] *= f[3]; v1[0] *= f[4]; v1[1] *= f[5]; v1[2] *= f[6]; v1[3] *= f[7]; }
;                     if (ropet) {
;                         f32x4 p0, p1;
; #pragma unroll
;                         for (int j = 0; j < 4; ++j) { p0[j] = __shfl_xor(v0[j], 32); p1[j] = __shfl_xor(v1[j], 32); }
;                         v0 = v0 * c0 + p0 * s0; v1 = v1 * c1 + p1 * s1;
;                     }
;                     u32x4 w; w.x = cvt_pk_bf16(v0[0], v0[1]); w.y = cvt_pk_bf16(v0[2], v0[3]); w.z = cvt_pk_bf16(v1[0], v1[1]); w.w = cvt_pk_bf16(v1[2], v1[3]);
;                     *(u32x4*)(rowp + bj * HALF) = w;
	v_xor_b32_e32 v116, v144, v116
	v_xor_b32_e32 v117, v144, v117
	v_xor_b32_e32 v118, v144, v118
	v_xor_b32_e32 v119, v144, v119
	v_xor_b32_e32 v52, v144, v52
	v_xor_b32_e32 v53, v144, v53
	v_xor_b32_e32 v54, v144, v54
	v_xor_b32_e32 v55, v144, v55
	s_waitcnt lgkmcnt(0)
	v_pk_mul_f32 v[182:183], v[116:117], v[182:183]
	v_pk_mul_f32 v[184:185], v[118:119], v[184:185]
	v_pk_mul_f32 v[186:187], v[52:53], v[186:187]
	v_pk_mul_f32 v[188:189], v[54:55], v[188:189]
	v_pk_fma_f32 v[158:159], v[120:121], v[158:159], v[182:183]
	v_pk_fma_f32 v[160:161], v[122:123], v[160:161], v[184:185]
	v_pk_fma_f32 v[162:163], v[56:57], v[162:163], v[186:187]
	v_pk_fma_f32 v[178:179], v[58:59], v[178:179], v[188:189]
	v_cvt_pk_bf16_f32 v132, v158, v159
	v_cvt_pk_bf16_f32 v133, v160, v161
	v_cvt_pk_bf16_f32 v134, v162, v163
	v_cvt_pk_bf16_f32 v135, v178, v179
	global_store_dwordx4 v[180:181], v[132:135], off
	v_pk_mul_f32 v[158:159], v[140:141], v[100:101]
	v_pk_mul_f32 v[160:161], v[140:141], v[102:103]
	v_pk_mul_f32 v[162:163], v[140:141], v[36:37]
	v_pk_mul_f32 v[178:179], v[140:141], v[38:39]
	ds_bpermute_b32 v182, v143, v158
	ds_bpermute_b32 v183, v143, v159
	ds_bpermute_b32 v184, v143, v160
	ds_bpermute_b32 v185, v143, v161
	ds_bpermute_b32 v186, v143, v162
	ds_bpermute_b32 v187, v143, v163
	ds_bpermute_b32 v188, v143, v178
	ds_bpermute_b32 v189, v143, v179
	s_waitcnt lgkmcnt(0)
	v_pk_mul_f32 v[182:183], v[116:117], v[182:183]
	v_pk_mul_f32 v[184:185], v[118:119], v[184:185]
	v_pk_mul_f32 v[186:187], v[52:53], v[186:187]
	v_pk_mul_f32 v[188:189], v[54:55], v[188:189]
	v_pk_fma_f32 v[158:159], v[120:121], v[158:159], v[182:183]
	v_pk_fma_f32 v[160:161], v[122:123], v[160:161], v[184:185]
	v_pk_fma_f32 v[162:163], v[56:57], v[162:163], v[186:187]
	v_pk_fma_f32 v[178:179], v[58:59], v[178:179], v[188:189]
	v_cvt_pk_bf16_f32 v132, v158, v159
	v_cvt_pk_bf16_f32 v133, v160, v161
	v_cvt_pk_bf16_f32 v134, v162, v163
	v_cvt_pk_bf16_f32 v135, v178, v179
	global_store_dwordx4 v[180:181], v[132:135], off offset:256
	v_add_co_u32_e32 v180, vcc, s41, v180
	s_nop 1
	v_addc_co_u32_e32 v181, vcc, 0, v181, vcc
	global_load_dwordx4 v[104:107], v[156:157], off
	global_load_dwordx4 v[40:43], v[156:157], off offset:16
	global_load_dwordx4 v[100:103], v[156:157], off offset:64
	global_load_dwordx4 v[36:39], v[156:157], off offset:80
	v_add_co_u32_e32 v156, vcc, 0x800, v156
	s_nop 1
	v_addc_co_u32_e32 v157, vcc, 0, v157, vcc
	v_pk_mul_f32 v[158:159], v[140:141], v[96:97]
	v_pk_mul_f32 v[160:161], v[140:141], v[98:99]
	v_pk_mul_f32 v[162:163], v[140:141], v[32:33]
	v_pk_mul_f32 v[178:179], v[140:141], v[34:35]
	ds_bpermute_b32 v182, v143, v158
	ds_bpermute_b32 v183, v143, v159
	ds_bpermute_b32 v184, v143, v160
	ds_bpermute_b32 v185, v143, v161
	ds_bpermute_b32 v186, v143, v162
	ds_bpermute_b32 v187, v143, v163
	ds_bpermute_b32 v188, v143, v178
	ds_bpermute_b32 v189, v143, v179
	s_waitcnt vmcnt(6)
	v_xor_b32_e32 v108, v144, v108
	v_xor_b32_e32 v109, v144, v109
	v_xor_b32_e32 v110, v144, v110
	v_xor_b32_e32 v111, v144, v111
	v_xor_b32_e32 v44, v144, v44
	v_xor_b32_e32 v45, v144, v45
	v_xor_b32_e32 v46, v144, v46
	v_xor_b32_e32 v47, v144, v47
	s_waitcnt lgkmcnt(0)
	v_pk_mul_f32 v[182:183], v[108:109], v[182:183]
	v_pk_mul_f32 v[184:185], v[110:111], v[184:185]
	v_pk_mul_f32 v[186:187], v[44:45], v[186:187]
	v_pk_mul_f32 v[188:189], v[46:47], v[188:189]
	v_pk_fma_f32 v[158:159], v[112:113], v[158:159], v[182:183]
	v_pk_fma_f32 v[160:161], v[114:115], v[160:161], v[184:185]
	v_pk_fma_f32 v[162:163], v[48:49], v[162:163], v[186:187]
	v_pk_fma_f32 v[178:179], v[50:51], v[178:179], v[188:189]
	v_cvt_pk_bf16_f32 v132, v158, v159
	v_cvt_pk_bf16_f32 v133, v160, v161
	v_cvt_pk_bf16_f32 v134, v162, v163
	v_cvt_pk_bf16_f32 v135, v178, v179
	global_store_dwordx4 v[180:181], v[132:135], off
	v_pk_mul_f32 v[158:159], v[140:141], v[92:93]
	v_pk_mul_f32 v[160:161], v[140:141], v[94:95]
	v_pk_mul_f32 v[162:163], v[140:141], v[28:29]
	v_pk_mul_f32 v[178:179], v[140:141], v[30:31]
	ds_bpermute_b32 v182, v143, v158
	ds_bpermute_b32 v183, v143, v159
	ds_bpermute_b32 v184, v143, v160
	ds_bpermute_b32 v185, v143, v161
	ds_bpermute_b32 v186, v143, v162
	ds_bpermute_b32 v187, v143, v163
	ds_bpermute_b32 v188, v143, v178
	ds_bpermute_b32 v189, v143, v179
	s_waitcnt lgkmcnt(0)
	v_pk_mul_f32 v[182:183], v[108:109], v[182:183]
	v_pk_mul_f32 v[184:185], v[110:111], v[184:185]
	v_pk_mul_f32 v[186:187], v[44:45], v[186:187]
	v_pk_mul_f32 v[188:189], v[46:47], v[188:189]
	v_pk_fma_f32 v[158:159], v[112:113], v[158:159], v[182:183]
	v_pk_fma_f32 v[160:161], v[114:115], v[160:161], v[184:185]
	v_pk_fma_f32 v[162:163], v[48:49], v[162:163], v[186:187]
	v_pk_fma_f32 v[178:179], v[50:51], v[178:179], v[188:189]
	v_cvt_pk_bf16_f32 v132, v158, v159
	v_cvt_pk_bf16_f32 v133, v160, v161
	v_cvt_pk_bf16_f32 v134, v162, v163
	v_cvt_pk_bf16_f32 v135, v178, v179
	global_store_dwordx4 v[180:181], v[132:135], off offset:256
	v_add_co_u32_e32 v180, vcc, s40, v180
	s_nop 1
	v_addc_co_u32_e32 v181, vcc, 0, v181, vcc
	global_load_dwordx4 v[96:99], v[156:157], off
	global_load_dwordx4 v[32:35], v[156:157], off offset:16
	global_load_dwordx4 v[92:95], v[156:157], off offset:64
	global_load_dwordx4 v[28:31], v[156:157], off offset:80
	v_add_co_u32_e32 v156, vcc, 0x800, v156
	s_nop 1
	v_addc_co_u32_e32 v157, vcc, 0, v157, vcc
	v_pk_mul_f32 v[158:159], v[140:141], v[88:89]
	v_pk_mul_f32 v[160:161], v[140:141], v[90:91]
	v_pk_mul_f32 v[162:163], v[140:141], v[24:25]
	v_pk_mul_f32 v[178:179], v[140:141], v[26:27]
	ds_bpermute_b32 v182, v143, v158
	ds_bpermute_b32 v183, v143, v159
	ds_bpermute_b32 v184, v143, v160
	ds_bpermute_b32 v185, v143, v161
	ds_bpermute_b32 v186, v143, v162
	ds_bpermute_b32 v187, v143, v163
	ds_bpermute_b32 v188, v143, v178
	ds_bpermute_b32 v189, v143, v179
	s_waitcnt vmcnt(6)
; __device__ __forceinline__ unsigned cvt_pk_bf16(float lo, float hi) { const f32x2v v = {lo, hi}; const b16x2v r = __builtin_convertvector(v, b16x2v); return __builtin_bit_cast(unsigned, r); }
; __device__ __forceinline__ float bflo(unsigned u) { return __uint_as_float(u << 16); }
; __device__ __forceinline__ float bfhi(unsigned u) { return __uint_as_float(u & 0xffff0000u); }
; __device__ __forceinline__ void gemm_epilogue(const GemmDesc& d, const f32x4 (&acc)[2][2][4][2], const Unit& u, int wr, int wc, int fr, int fq) {
;     ...
;                 if (ropet) { const float* tp = d.rope + (size_t)row * 32 + 8 * (fq & 1); c0 = *(const f32x4*)tp; c1 = *(const f32x4*)(tp + 4); s0 = *(const f32x4*)(tp + 16); s1 = *(const f32x4*)(tp + 20);
;                     if (fq < 2) { s0 = -s0; s1 = -s1; } }
; #pragma unroll
;                 for (int bj = 0; bj < 2; ++bj) {
;                     f32x4 v0 = acc[ai][bj][m][0] * qs, v1 = acc[ai][bj][m][1] * qs;
;                     if (gate) { const u32x4 e = *(const u32x4*)(gtab + (size_t)row * 512 + bj * HALF);
;                         float f[8] = {bflo(e.x), bfhi(e.x), bflo(e.y), bfhi(e.y), bflo(e.z), bfhi(e.z), bflo(e.w), bfhi(e.w)};
;                         if (ginv) {
; #pragma unroll
;                             for (int j = 0; j < 8; ++j) f[j] = __builtin_amdgcn_rcpf(f[j]); }
;                         v0[0] *= f[0]; v0[1] *= f[1]; v0[2] *= f[2]; v0[3] *= f[3]; v1[0] *= f[4]; v1[1] *= f[5]; v1[2] *= f[6]; v1[3] *= f[7]; }
;                     if (ropet) {
;                         f32x4 p0, p1;
; #pragma unroll
;                         for (int j = 0; j < 4; ++j) { p0[j] = __shfl_xor(v0[j], 32); p1[j] = __shfl_xor(v1[j], 32); }
;                         v0 = v0 * c0 + p0 * s0; v1 = v1 * c1 + p1 * s1;
;                     }
;                     u32x4 w; w.x = cvt_pk_bf16(v0[0], v0[1]); w.y = cvt_pk_bf16(v0[2], v0[3]); w.z = cvt_pk_bf16(v1[0], v1[1]); w.w = cvt_pk_bf16(v1[2], v1[3]);
;                     *(u32x4*)(rowp + bj * HALF) = w;
	v_xor_b32_e32 v100, v144, v100
	v_xor_b32_e32 v101, v144, v101
	v_xor_b32_e32 v102, v144, v102
	v_xor_b32_e32 v103, v144, v103
	v_xor_b32_e32 v36, v144, v36
	v_xor_b32_e32 v37, v144, v37
	v_xor_b32_e32 v38, v144, v38
	v_xor_b32_e32 v39, v144, v39
	s_waitcnt lgkmcnt(0)
	v_pk_mul_f32 v[182:183], v[100:101], v[182:183]
	v_pk_mul_f32 v[184:185], v[102:103], v[184:185]
	v_pk_mul_f32 v[186:187], v[36:37], v[186:187]
	v_pk_mul_f32 v[188:189], v[38:39], v[188:189]
	v_pk_fma_f32 v[158:159], v[104:105], v[158:159], v[182:183]
	v_pk_fma_f32 v[160:161], v[106:107], v[160:161], v[184:185]
	v_pk_fma_f32 v[162:163], v[40:41], v[162:163], v[186:187]
	v_pk_fma_f32 v[178:179], v[42:43], v[178:179], v[188:189]
	v_cvt_pk_bf16_f32 v132, v158, v159
	v_cvt_pk_bf16_f32 v133, v160, v161
	v_cvt_pk_bf16_f32 v134, v162, v163
	v_cvt_pk_bf16_f32 v135, v178, v179
	global_store_dwordx4 v[180:181], v[132:135], off
	v_pk_mul_f32 v[158:159], v[140:141], v[80:81]
	v_pk_mul_f32 v[160:161], v[140:141], v[82:83]
	v_pk_mul_f32 v[162:163], v[140:141], v[12:13]
	v_pk_mul_f32 v[178:179], v[140:141], v[14:15]
	ds_bpermute_b32 v182, v143, v158
	ds_bpermute_b32 v183, v143, v159
	ds_bpermute_b32 v184, v143, v160
	ds_bpermute_b32 v185, v143, v161
	ds_bpermute_b32 v186, v143, v162
	ds_bpermute_b32 v187, v143, v163
	ds_bpermute_b32 v188, v143, v178
	ds_bpermute_b32 v189, v143, v179
	s_waitcnt lgkmcnt(0)
	v_pk_mul_f32 v[182:183], v[100:101], v[182:183]
	v_pk_mul_f32 v[184:185], v[102:103], v[184:185]
	v_pk_mul_f32 v[186:187], v[36:37], v[186:187]
	v_pk_mul_f32 v[188:189], v[38:39], v[188:189]
	v_pk_fma_f32 v[158:159], v[104:105], v[158:159], v[182:183]
	v_pk_fma_f32 v[160:161], v[106:107], v[160:161], v[184:185]
	v_pk_fma_f32 v[162:163], v[40:41], v[162:163], v[186:187]
	v_pk_fma_f32 v[178:179], v[42:43], v[178:179], v[188:189]
	v_cvt_pk_bf16_f32 v132, v158, v159
	v_cvt_pk_bf16_f32 v133, v160, v161
	v_cvt_pk_bf16_f32 v134, v162, v163
	v_cvt_pk_bf16_f32 v135, v178, v179
	global_store_dwordx4 v[180:181], v[132:135], off offset:256
	v_add_co_u32_e32 v180, vcc, s40, v180
	s_nop 1
	v_addc_co_u32_e32 v181, vcc, 0, v181, vcc
	global_load_dwordx4 v[88:91], v[156:157], off
	global_load_dwordx4 v[24:27], v[156:157], off offset:16
	global_load_dwordx4 v[80:83], v[156:157], off offset:64
	global_load_dwordx4 v[12:15], v[156:157], off offset:80
	v_pk_mul_f32 v[158:159], v[140:141], v[68:69]
	v_pk_mul_f32 v[160:161], v[140:141], v[70:71]
	v_pk_mul_f32 v[162:163], v[140:141], v[20:21]
	v_pk_mul_f32 v[178:179], v[140:141], v[22:23]
	ds_bpermute_b32 v182, v143, v158
	ds_bpermute_b32 v183, v143, v159
	ds_bpermute_b32 v184, v143, v160
	ds_bpermute_b32 v185, v143, v161
	ds_bpermute_b32 v186, v143, v162
	ds_bpermute_b32 v187, v143, v163
	ds_bpermute_b32 v188, v143, v178
	ds_bpermute_b32 v189, v143, v179
	s_waitcnt vmcnt(6)
	v_xor_b32_e32 v92, v144, v92
	v_xor_b32_e32 v93, v144, v93
	v_xor_b32_e32 v94, v144, v94
	v_xor_b32_e32 v95, v144, v95
	v_xor_b32_e32 v28, v144, v28
	v_xor_b32_e32 v29, v144, v29
	v_xor_b32_e32 v30, v144, v30
	v_xor_b32_e32 v31, v144, v31
	s_waitcnt lgkmcnt(0)
	v_pk_mul_f32 v[182:183], v[92:93], v[182:183]
	v_pk_mul_f32 v[184:185], v[94:95], v[184:185]
	v_pk_mul_f32 v[186:187], v[28:29], v[186:187]
	v_pk_mul_f32 v[188:189], v[30:31], v[188:189]
	v_pk_fma_f32 v[158:159], v[96:97], v[158:159], v[182:183]
	v_pk_fma_f32 v[160:161], v[98:99], v[160:161], v[184:185]
	v_pk_fma_f32 v[162:163], v[32:33], v[162:163], v[186:187]
	v_pk_fma_f32 v[178:179], v[34:35], v[178:179], v[188:189]
	v_cvt_pk_bf16_f32 v132, v158, v159
	v_cvt_pk_bf16_f32 v133, v160, v161
	v_cvt_pk_bf16_f32 v134, v162, v163
	v_cvt_pk_bf16_f32 v135, v178, v179
	global_store_dwordx4 v[180:181], v[132:135], off
	v_pk_mul_f32 v[158:159], v[140:141], v[76:77]
	v_pk_mul_f32 v[160:161], v[140:141], v[78:79]
	v_pk_mul_f32 v[162:163], v[140:141], v[8:9]
	v_pk_mul_f32 v[178:179], v[140:141], v[10:11]
	ds_bpermute_b32 v182, v143, v158
	ds_bpermute_b32 v183, v143, v159
	ds_bpermute_b32 v184, v143, v160
	ds_bpermute_b32 v185, v143, v161
	ds_bpermute_b32 v186, v143, v162
	ds_bpermute_b32 v187, v143, v163
	ds_bpermute_b32 v188, v143, v178
	ds_bpermute_b32 v189, v143, v179
	s_waitcnt lgkmcnt(0)
; __device__ __forceinline__ unsigned cvt_pk_bf16(float lo, float hi) { const f32x2v v = {lo, hi}; const b16x2v r = __builtin_convertvector(v, b16x2v); return __builtin_bit_cast(unsigned, r); }
; __device__ __forceinline__ float bflo(unsigned u) { return __uint_as_float(u << 16); }
; __device__ __forceinline__ float bfhi(unsigned u) { return __uint_as_float(u & 0xffff0000u); }
; __device__ __forceinline__ void gemm_epilogue(const GemmDesc& d, const f32x4 (&acc)[2][2][4][2], const Unit& u, int wr, int wc, int fr, int fq) {
;     ...
;                 if (ropet) { const float* tp = d.rope + (size_t)row * 32 + 8 * (fq & 1); c0 = *(const f32x4*)tp; c1 = *(const f32x4*)(tp + 4); s0 = *(const f32x4*)(tp + 16); s1 = *(const f32x4*)(tp + 20);
;                     if (fq < 2) { s0 = -s0; s1 = -s1; } }
; #pragma unroll
;                 for (int bj = 0; bj < 2; ++bj) {
;                     f32x4 v0 = acc[ai][bj][m][0] * qs, v1 = acc[ai][bj][m][1] * qs;
;                     if (gate) { const u32x4 e = *(const u32x4*)(gtab + (size_t)row * 512 + bj * HALF);
;                         float f[8] = {bflo(e.x), bfhi(e.x), bflo(e.y), bfhi(e.y), bflo(e.z), bfhi(e.z), bflo(e.w), bfhi(e.w)};
;                         if (ginv) {
; #pragma unroll
;                             for (int j = 0; j < 8; ++j) f[j] = __builtin_amdgcn_rcpf(f[j]); }
;                         v0[0] *= f[0]; v0[1] *= f[1]; v0[2] *= f[2]; v0[3] *= f[3]; v1[0] *= f[4]; v1[1] *= f[5]; v1[2] *= f[6]; v1[3] *= f[7]; }
;                     if (ropet) {
;                         f32x4 p0, p1;
; #pragma unroll
;                         for (int j = 0; j < 4; ++j) { p0[j] = __shfl_xor(v0[j], 32); p1[j] = __shfl_xor(v1[j], 32); }
;                         v0 = v0 * c0 + p0 * s0; v1 = v1 * c1 + p1 * s1;
;                     }
;                     u32x4 w; w.x = cvt_pk_bf16(v0[0], v0[1]); w.y = cvt_pk_bf16(v0[2], v0[3]); w.z = cvt_pk_bf16(v1[0], v1[1]); w.w = cvt_pk_bf16(v1[2], v1[3]);
;                     *(u32x4*)(rowp + bj * HALF) = w;
	v_pk_mul_f32 v[182:183], v[92:93], v[182:183]
	v_pk_mul_f32 v[184:185], v[94:95], v[184:185]
	v_pk_mul_f32 v[186:187], v[28:29], v[186:187]
	v_pk_mul_f32 v[188:189], v[30:31], v[188:189]
	v_pk_fma_f32 v[158:159], v[96:97], v[158:159], v[182:183]
	v_pk_fma_f32 v[160:161], v[98:99], v[160:161], v[184:185]
	v_pk_fma_f32 v[162:163], v[32:33], v[162:163], v[186:187]
	v_pk_fma_f32 v[178:179], v[34:35], v[178:179], v[188:189]
	v_cvt_pk_bf16_f32 v132, v158, v159
	v_cvt_pk_bf16_f32 v133, v160, v161
	v_cvt_pk_bf16_f32 v134, v162, v163
	v_cvt_pk_bf16_f32 v135, v178, v179
	global_store_dwordx4 v[180:181], v[132:135], off offset:256
	v_add_co_u32_e32 v180, vcc, s40, v180
	s_nop 1
	v_addc_co_u32_e32 v181, vcc, 0, v181, vcc
	v_pk_mul_f32 v[158:159], v[140:141], v[84:85]
	v_pk_mul_f32 v[160:161], v[140:141], v[86:87]
	v_pk_mul_f32 v[162:163], v[140:141], v[16:17]
	v_pk_mul_f32 v[178:179], v[140:141], v[18:19]
	ds_bpermute_b32 v182, v143, v158
	ds_bpermute_b32 v183, v143, v159
	ds_bpermute_b32 v184, v143, v160
	ds_bpermute_b32 v185, v143, v161
	ds_bpermute_b32 v186, v143, v162
	ds_bpermute_b32 v187, v143, v163
	ds_bpermute_b32 v188, v143, v178
	ds_bpermute_b32 v189, v143, v179
	s_waitcnt vmcnt(2)
	v_xor_b32_e32 v80, v144, v80
	v_xor_b32_e32 v81, v144, v81
	v_xor_b32_e32 v82, v144, v82
	v_xor_b32_e32 v83, v144, v83
	v_xor_b32_e32 v12, v144, v12
	v_xor_b32_e32 v13, v144, v13
	v_xor_b32_e32 v14, v144, v14
	v_xor_b32_e32 v15, v144, v15
	s_waitcnt lgkmcnt(0)
	v_pk_mul_f32 v[182:183], v[80:81], v[182:183]
	v_pk_mul_f32 v[184:185], v[82:83], v[184:185]
	v_pk_mul_f32 v[186:187], v[12:13], v[186:187]
	v_pk_mul_f32 v[188:189], v[14:15], v[188:189]
	v_pk_fma_f32 v[158:159], v[88:89], v[158:159], v[182:183]
	v_pk_fma_f32 v[160:161], v[90:91], v[160:161], v[184:185]
	v_pk_fma_f32 v[162:163], v[24:25], v[162:163], v[186:187]
	v_pk_fma_f32 v[178:179], v[26:27], v[178:179], v[188:189]
	v_cvt_pk_bf16_f32 v132, v158, v159
	v_cvt_pk_bf16_f32 v133, v160, v161
	v_cvt_pk_bf16_f32 v134, v162, v163
	v_cvt_pk_bf16_f32 v135, v178, v179
	global_store_dwordx4 v[180:181], v[132:135], off
	v_pk_mul_f32 v[158:159], v[140:141], v[72:73]
	v_pk_mul_f32 v[160:161], v[140:141], v[74:75]
	v_pk_mul_f32 v[162:163], v[140:141], v[4:5]
	v_pk_mul_f32 v[178:179], v[140:141], v[6:7]
	ds_bpermute_b32 v182, v143, v158
	ds_bpermute_b32 v183, v143, v159
	ds_bpermute_b32 v184, v143, v160
	ds_bpermute_b32 v185, v143, v161
	ds_bpermute_b32 v186, v143, v162
	ds_bpermute_b32 v187, v143, v163
	ds_bpermute_b32 v188, v143, v178
	ds_bpermute_b32 v189, v143, v179
	s_waitcnt lgkmcnt(0)
	v_pk_mul_f32 v[182:183], v[80:81], v[182:183]
	v_pk_mul_f32 v[184:185], v[82:83], v[184:185]
	v_pk_mul_f32 v[186:187], v[12:13], v[186:187]
	v_pk_mul_f32 v[188:189], v[14:15], v[188:189]
	v_pk_fma_f32 v[158:159], v[88:89], v[158:159], v[182:183]
	v_pk_fma_f32 v[160:161], v[90:91], v[160:161], v[184:185]
	v_pk_fma_f32 v[162:163], v[24:25], v[162:163], v[186:187]
	v_pk_fma_f32 v[178:179], v[26:27], v[178:179], v[188:189]
	v_cvt_pk_bf16_f32 v132, v158, v159
	v_cvt_pk_bf16_f32 v133, v160, v161
	v_cvt_pk_bf16_f32 v134, v162, v163
	v_cvt_pk_bf16_f32 v135, v178, v179
	global_store_dwordx4 v[180:181], v[132:135], off offset:256

; #define LAS __attribute__((address_space(3)))
; __device__ __forceinline__ float silu_f(float v) { return v / (1.0f + fexp2(-v * LOG2E)); }
; __device__ __forceinline__ void conv_epilogue(const GemmDesc& d, const f32x4 (&acc)[2][2][4][2], const Unit& u, int wr, int wc, int fr, int fq, LAS unsigned char* lds) {
;     const int L = 16 * wr + fr;
;     const bool seq_start = (u.pm & 15) == 0;
;     const int ch0 = u.pn * 128 + wc * 32 + fq * 8;
;     if (fr == 0 || fr == 15) {
;         const int rbase = (fr == 0) ? 4 * wr : 4 * wr + 2;
; #pragma unroll
;         for (int e2 = 0; e2 < 2; ++e2)
; #pragma unroll
;             for (int bj = 0; bj < 2; ++bj)
; #pragma unroll
;                 for (int n = 0; n < 2; ++n) {
;                     const f32x4 v = (fr == 0) ? acc[0][bj][e2][n] : acc[1][bj][2 + e2][n];
;                     *(f32x4*)(d.aux + ((size_t)((u.pm * 8 + rbase + e2) * 2 + bj)) * DFF + ch0 + 4 * n) = v;
;                 }
;     }
;     bf16_t* gout = (bf16_t*)d.C;
; #pragma unroll
;     for (int n = 0; n < 2; ++n) {
;         const int ch = ch0 + 4 * n;
;         const f32x4 wg0 = *(const f32x4*)(d.R + ch), wg1 = *(const f32x4*)(d.R + 11008 + ch), wg2 = *(const f32x4*)(d.R + 22016 + ch);
;         const f32x4 wu0 = *(const f32x4*)(d.R + DFF + ch), wu1 = *(const f32x4*)(d.R + 11008 + DFF + ch), wu2 = *(const f32x4*)(d.R + 22016 + DFF + ch);
;         const f32x4 bg = *(const f32x4*)(d.rope + ch), bu = *(const f32x4*)(d.rope + DFF + ch);
;         f32x4 pg2 = dpp_prev(acc[1][0][2][n]), pg1 = dpp_prev(acc[1][0][3][n]), pu2 = dpp_prev(acc[1][1][2][n]), pu1 = dpp_prev(acc[1][1][3][n]);
;         if (fr == 0) { pg2 = (f32x4){0.f, 0.f, 0.f, 0.f}; pg1 = pg2; pu2 = pg2; pu1 = pg2; }
; #pragma unroll
;         for (int e = 0; e < 8; ++e) {
;             const f32x4 cg_ = acc[e >> 2][0][e & 3][n], cu_ = acc[e >> 2][1][e & 3][n];
;             const f32x4 yg = bg + wg0 * pg2 + wg1 * pg1 + wg2 * cg_;
;             const f32x4 yu = bu + wu0 * pu2 + wu1 * pu1 + wu2 * cu_;
;             f32x4 r;
; #pragma unroll
;             for (int j = 0; j < 4; ++j) r[j] = silu_f(yg[j]) * yu[j];
;             u32x2 pk; pk.x = cvt_pk_bf16(r[0], r[1]); pk.y = cvt_pk_bf16(r[2], r[3]);
;             { const bool skip = (fr == 0) && (e < 2) && !(wr == 0 && seq_start);
;               if (!skip) *(u32x2*)(gout + (size_t)(u.pm * 256 + 8 * L + e) * DFF + ch) = pk; }
.LBB0_368:
	s_and_b64 vcc, exec, s[0:1]
	s_cbranch_vccz .LBB0_194
	v_lshl_or_b32 v169, s9, 7, v211
	v_lshlrev_b32_e32 v170, 2, v169
	global_load_dwordx4 v[132:135], v170, s[50:51]
	v_add_u32_e32 v171, 0xac00, v170
	global_load_dwordx4 v[136:139], v171, s[50:51]
	v_add_u32_e32 v171, 0x15800, v170
	global_load_dwordx4 v[140:143], v171, s[50:51]
	v_add_u32_e32 v171, 0x5600, v170
	global_load_dwordx4 v[144:147], v171, s[50:51]
	v_add_u32_e32 v171, 0x10200, v170
	global_load_dwordx4 v[148:151], v171, s[50:51]
	v_add_u32_e32 v171, 0x1ae00, v170
	global_load_dwordx4 v[152:155], v171, s[50:51]
	global_load_dwordx4 v[156:159], v170, s[58:59]
	v_add_u32_e32 v171, 0x5600, v170
	global_load_dwordx4 v[160:163], v171, s[58:59]
	global_load_dwordx4 v[178:181], v170, s[50:51] offset:16
	v_add_u32_e32 v171, 0xac00, v170
	global_load_dwordx4 v[182:185], v171, s[50:51] offset:16
	v_add_u32_e32 v171, 0x15800, v170
	global_load_dwordx4 v[186:189], v171, s[50:51] offset:16
	v_add_u32_e32 v171, 0x5600, v170
	global_load_dwordx4 v[190:193], v171, s[50:51] offset:16
	v_add_u32_e32 v171, 0x10200, v170
	global_load_dwordx4 v[194:197], v171, s[50:51] offset:16
	v_add_u32_e32 v171, 0x1ae00, v170
	global_load_dwordx4 v[230:233], v171, s[50:51] offset:16
	global_load_dwordx4 v[234:237], v170, s[58:59] offset:16
	v_add_u32_e32 v171, 0x5600, v170
	global_load_dwordx4 v[238:241], v171, s[58:59] offset:16
	v_readlane_b32 s40, v254, 47
	v_readlane_b32 s41, v254, 48
	s_lshl_b32 s13, s11, 4
	v_add_u32_e32 v171, s13, v201
	s_movk_i32 s13, 0x5600
	v_mad_u32_u24 v168, v171, s13, v170
	v_cmp_eq_u32_e64 s[0:1], 15, v198
	s_nop 1
	s_or_b64 s[0:1], s[0:1], s[38:39]
	s_and_saveexec_b64 s[44:45], s[0:1]
	v_cndmask_b32_e64 v242, v68, v128, s[38:39]
	v_cndmask_b32_e64 v243, v69, v129, s[38:39]
	v_cndmask_b32_e64 v244, v70, v130, s[38:39]
	v_cndmask_b32_e64 v245, v71, v131, s[38:39]
	global_store_dwordx4 v168, v[242:245], s[40:41]
	v_cndmask_b32_e64 v246, v20, v64, s[38:39]
	v_cndmask_b32_e64 v247, v21, v65, s[38:39]
	v_cndmask_b32_e64 v248, v22, v66, s[38:39]
	v_cndmask_b32_e64 v249, v23, v67, s[38:39]
	global_store_dwordx4 v168, v[246:249], s[40:41] offset:16
	v_add_u32_e32 v168, 0x5600, v168
	v_cndmask_b32_e64 v242, v76, v124, s[38:39]
	v_cndmask_b32_e64 v243, v77, v125, s[38:39]
	v_cndmask_b32_e64 v244, v78, v126, s[38:39]
	v_cndmask_b32_e64 v245, v79, v127, s[38:39]
	global_store_dwordx4 v168, v[242:245], s[40:41]
	v_cndmask_b32_e64 v246, v8, v60, s[38:39]
	v_cndmask_b32_e64 v247, v9, v61, s[38:39]
	v_cndmask_b32_e64 v248, v10, v62, s[38:39]
	v_cndmask_b32_e64 v249, v11, v63, s[38:39]
	global_store_dwordx4 v168, v[246:249], s[40:41] offset:16
	v_add_u32_e32 v168, 0x5600, v168
	v_cndmask_b32_e64 v242, v84, v120, s[38:39]
	v_cndmask_b32_e64 v243, v85, v121, s[38:39]
	v_cndmask_b32_e64 v244, v86, v122, s[38:39]
	v_cndmask_b32_e64 v245, v87, v123, s[38:39]
	global_store_dwordx4 v168, v[242:245], s[40:41]
	v_cndmask_b32_e64 v246, v16, v56, s[38:39]
	v_cndmask_b32_e64 v247, v17, v57, s[38:39]
	v_cndmask_b32_e64 v248, v18, v58, s[38:39]
	v_cndmask_b32_e64 v249, v19, v59, s[38:39]
	global_store_dwordx4 v168, v[246:249], s[40:41] offset:16
	v_add_u32_e32 v168, 0x5600, v168
	v_cndmask_b32_e64 v242, v72, v116, s[38:39]
	v_cndmask_b32_e64 v243, v73, v117, s[38:39]
	v_cndmask_b32_e64 v244, v74, v118, s[38:39]
	v_cndmask_b32_e64 v245, v75, v119, s[38:39]
	global_store_dwordx4 v168, v[242:245], s[40:41]
	v_cndmask_b32_e64 v246, v4, v52, s[38:39]
	v_cndmask_b32_e64 v247, v5, v53, s[38:39]
	v_cndmask_b32_e64 v248, v6, v54, s[38:39]
	v_cndmask_b32_e64 v249, v7, v55, s[38:39]
	global_store_dwordx4 v168, v[246:249], s[40:41] offset:16
	s_mov_b64 exec, s[44:45]
	s_lshl_b32 s13, s11, 8
	v_add_u32_e32 v171, s13, v203
	s_movk_i32 s13, 0x2b00
	v_mul_u32_u24_e32 v168, s13, v171
	v_lshl_add_u32 v168, v169, 1, v168
	s_and_b32 s0, s11, 15
	s_cmp_lg_u32 s0, 0
	s_cselect_b64 s[0:1], -1, 0
	v_readlane_b32 s42, v254, 59
	v_readlane_b32 s43, v254, 60
	s_nop 1
	s_or_b64 s[0:1], s[42:43], s[0:1]
	s_and_b64 s[0:1], s[0:1], s[38:39]
	s_andn2_b64 s[42:43], exec, s[0:1]
	s_waitcnt vmcnt(8)
	v_mov_b32_e32 v242, v156
	v_mov_b32_e32 v243, v157
	v_mov_b32_e32 v244, v158
	v_mov_b32_e32 v245, v159
	v_fmac_f32_dpp v242, v68, v132 row_shr:1 row_mask:0xf bank_mask:0xf bound_ctrl:1
	v_fmac_f32_dpp v243, v69, v133 row_shr:1 row_mask:0xf bank_mask:0xf bound_ctrl:1
	v_fmac_f32_dpp v244, v70, v134 row_shr:1 row_mask:0xf bank_mask:0xf bound_ctrl:1
	v_fmac_f32_dpp v245, v71, v135 row_shr:1 row_mask:0xf bank_mask:0xf bound_ctrl:1
	v_fmac_f32_dpp v242, v84, v136 row_shr:1 row_mask:0xf bank_mask:0xf bound_ctrl:1
	v_fmac_f32_dpp v243, v85, v137 row_shr:1 row_mask:0xf bank_mask:0xf bound_ctrl:1
	v_fmac_f32_dpp v244, v86, v138 row_shr:1 row_mask:0xf bank_mask:0xf bound_ctrl:1
	v_fmac_f32_dpp v245, v87, v139 row_shr:1 row_mask:0xf bank_mask:0xf bound_ctrl:1
	v_pk_fma_f32 v[242:243], v[140:141], v[128:129], v[242:243]
	v_pk_fma_f32 v[244:245], v[142:143], v[130:131], v[244:245]
	v_mul_f32_e32 v246, 0xbfb8aa3b, v242
	v_mul_f32_e32 v247, 0xbfb8aa3b, v243
	v_mul_f32_e32 v248, 0xbfb8aa3b, v244
	v_mul_f32_e32 v249, 0xbfb8aa3b, v245
	v_exp_f32_e32 v246, v246
	v_exp_f32_e32 v247, v247
	v_exp_f32_e32 v248, v248
	v_exp_f32_e32 v249, v249
	s_nop 0
	v_pk_add_f32 v[246:247], v[246:247], 1.0 op_sel_hi:[1,0]
	v_pk_add_f32 v[248:249], v[248:249], 1.0 op_sel_hi:[1,0]
	v_rcp_f32_e32 v246, v246
	v_rcp_f32_e32 v247, v247
	v_rcp_f32_e32 v248, v248
	v_rcp_f32_e32 v249, v249
	s_nop 0
	v_pk_mul_f32 v[242:243], v[242:243], v[246:247]
	v_pk_mul_f32 v[244:245], v[244:245], v[248:249]
	v_mov_b32_e32 v246, v160
	v_mov_b32_e32 v247, v161
	v_mov_b32_e32 v248, v162
; __device__ __forceinline__ unsigned cvt_pk_bf16(float lo, float hi) { const f32x2v v = {lo, hi}; const b16x2v r = __builtin_convertvector(v, b16x2v); return __builtin_bit_cast(unsigned, r); }
; __device__ __forceinline__ float silu_f(float v) { return v / (1.0f + fexp2(-v * LOG2E)); }
; __device__ __forceinline__ void conv_epilogue(const GemmDesc& d, const f32x4 (&acc)[2][2][4][2], const Unit& u, int wr, int wc, int fr, int fq, LAS unsigned char* lds) {
;     ...
;     for (int n = 0; n < 2; ++n) {
;         const int ch = ch0 + 4 * n;
;         const f32x4 wg0 = *(const f32x4*)(d.R + ch), wg1 = *(const f32x4*)(d.R + 11008 + ch), wg2 = *(const f32x4*)(d.R + 22016 + ch);
;         const f32x4 wu0 = *(const f32x4*)(d.R + DFF + ch), wu1 = *(const f32x4*)(d.R + 11008 + DFF + ch), wu2 = *(const f32x4*)(d.R + 22016 + DFF + ch);
;         const f32x4 bg = *(const f32x4*)(d.rope + ch), bu = *(const f32x4*)(d.rope + DFF + ch);
;         f32x4 pg2 = dpp_prev(acc[1][0][2][n]), pg1 = dpp_prev(acc[1][0][3][n]), pu2 = dpp_prev(acc[1][1][2][n]), pu1 = dpp_prev(acc[1][1][3][n]);
;         if (fr == 0) { pg2 = (f32x4){0.f, 0.f, 0.f, 0.f}; pg1 = pg2; pu2 = pg2; pu1 = pg2; }
; #pragma unroll
;         for (int e = 0; e < 8; ++e) {
;             const f32x4 cg_ = acc[e >> 2][0][e & 3][n], cu_ = acc[e >> 2][1][e & 3][n];
;             const f32x4 yg = bg + wg0 * pg2 + wg1 * pg1 + wg2 * cg_;
;             const f32x4 yu = bu + wu0 * pu2 + wu1 * pu1 + wu2 * cu_;
;             f32x4 r;
; #pragma unroll
;             for (int j = 0; j < 4; ++j) r[j] = silu_f(yg[j]) * yu[j];
;             u32x2 pk; pk.x = cvt_pk_bf16(r[0], r[1]); pk.y = cvt_pk_bf16(r[2], r[3]);
;             { const bool skip = (fr == 0) && (e < 2) && !(wr == 0 && seq_start);
;               if (!skip) *(u32x2*)(gout + (size_t)(u.pm * 256 + 8 * L + e) * DFF + ch) = pk; }
;             pg2 = pg1; pg1 = cg_; pu2 = pu1; pu1 = cu_;
	v_mov_b32_e32 v249, v163
	v_fmac_f32_dpp v246, v76, v144 row_shr:1 row_mask:0xf bank_mask:0xf bound_ctrl:1
	v_fmac_f32_dpp v247, v77, v145 row_shr:1 row_mask:0xf bank_mask:0xf bound_ctrl:1
	v_fmac_f32_dpp v248, v78, v146 row_shr:1 row_mask:0xf bank_mask:0xf bound_ctrl:1
	v_fmac_f32_dpp v249, v79, v147 row_shr:1 row_mask:0xf bank_mask:0xf bound_ctrl:1
	v_fmac_f32_dpp v246, v72, v148 row_shr:1 row_mask:0xf bank_mask:0xf bound_ctrl:1
	v_fmac_f32_dpp v247, v73, v149 row_shr:1 row_mask:0xf bank_mask:0xf bound_ctrl:1
	v_fmac_f32_dpp v248, v74, v150 row_shr:1 row_mask:0xf bank_mask:0xf bound_ctrl:1
	v_fmac_f32_dpp v249, v75, v151 row_shr:1 row_mask:0xf bank_mask:0xf bound_ctrl:1
	v_pk_fma_f32 v[246:247], v[152:153], v[124:125], v[246:247]
	v_pk_fma_f32 v[248:249], v[154:155], v[126:127], v[248:249]
	v_pk_mul_f32 v[242:243], v[246:247], v[242:243]
	v_pk_mul_f32 v[244:245], v[248:249], v[244:245]
	v_cvt_pk_bf16_f32 v220, v242, v243
	v_cvt_pk_bf16_f32 v221, v244, v245
	v_mov_b32_e32 v242, v234
	v_mov_b32_e32 v243, v235
	v_mov_b32_e32 v244, v236
	v_mov_b32_e32 v245, v237
	v_fmac_f32_dpp v242, v20, v178 row_shr:1 row_mask:0xf bank_mask:0xf bound_ctrl:1
	v_fmac_f32_dpp v243, v21, v179 row_shr:1 row_mask:0xf bank_mask:0xf bound_ctrl:1
	v_fmac_f32_dpp v244, v22, v180 row_shr:1 row_mask:0xf bank_mask:0xf bound_ctrl:1
	v_fmac_f32_dpp v245, v23, v181 row_shr:1 row_mask:0xf bank_mask:0xf bound_ctrl:1
	v_fmac_f32_dpp v242, v16, v182 row_shr:1 row_mask:0xf bank_mask:0xf bound_ctrl:1
	v_fmac_f32_dpp v243, v17, v183 row_shr:1 row_mask:0xf bank_mask:0xf bound_ctrl:1
	v_fmac_f32_dpp v244, v18, v184 row_shr:1 row_mask:0xf bank_mask:0xf bound_ctrl:1
	v_fmac_f32_dpp v245, v19, v185 row_shr:1 row_mask:0xf bank_mask:0xf bound_ctrl:1
	v_pk_fma_f32 v[242:243], v[186:187], v[64:65], v[242:243]
	v_pk_fma_f32 v[244:245], v[188:189], v[66:67], v[244:245]
	v_mul_f32_e32 v246, 0xbfb8aa3b, v242
	v_mul_f32_e32 v247, 0xbfb8aa3b, v243
	v_mul_f32_e32 v248, 0xbfb8aa3b, v244
	v_mul_f32_e32 v249, 0xbfb8aa3b, v245
	v_exp_f32_e32 v246, v246
	v_exp_f32_e32 v247, v247
	v_exp_f32_e32 v248, v248
	v_exp_f32_e32 v249, v249
	s_nop 0
	v_pk_add_f32 v[246:247], v[246:247], 1.0 op_sel_hi:[1,0]
	v_pk_add_f32 v[248:249], v[248:249], 1.0 op_sel_hi:[1,0]
	v_rcp_f32_e32 v246, v246
	v_rcp_f32_e32 v247, v247
	v_rcp_f32_e32 v248, v248
	v_rcp_f32_e32 v249, v249
	s_nop 0
	v_pk_mul_f32 v[242:243], v[242:243], v[246:247]
	v_pk_mul_f32 v[244:245], v[244:245], v[248:249]
	v_mov_b32_e32 v246, v238
	v_mov_b32_e32 v247, v239
	v_mov_b32_e32 v248, v240
	v_mov_b32_e32 v249, v241
	v_fmac_f32_dpp v246, v8, v190 row_shr:1 row_mask:0xf bank_mask:0xf bound_ctrl:1
	v_fmac_f32_dpp v247, v9, v191 row_shr:1 row_mask:0xf bank_mask:0xf bound_ctrl:1
	v_fmac_f32_dpp v248, v10, v192 row_shr:1 row_mask:0xf bank_mask:0xf bound_ctrl:1
	v_fmac_f32_dpp v249, v11, v193 row_shr:1 row_mask:0xf bank_mask:0xf bound_ctrl:1
	v_fmac_f32_dpp v246, v4, v194 row_shr:1 row_mask:0xf bank_mask:0xf bound_ctrl:1
	v_fmac_f32_dpp v247, v5, v195 row_shr:1 row_mask:0xf bank_mask:0xf bound_ctrl:1
	v_fmac_f32_dpp v248, v6, v196 row_shr:1 row_mask:0xf bank_mask:0xf bound_ctrl:1
	v_fmac_f32_dpp v249, v7, v197 row_shr:1 row_mask:0xf bank_mask:0xf bound_ctrl:1
	v_pk_fma_f32 v[246:247], v[230:231], v[60:61], v[246:247]
	v_pk_fma_f32 v[248:249], v[232:233], v[62:63], v[248:249]
	v_pk_mul_f32 v[242:243], v[246:247], v[242:243]
	v_pk_mul_f32 v[244:245], v[248:249], v[244:245]
	v_cvt_pk_bf16_f32 v222, v242, v243
	v_cvt_pk_bf16_f32 v223, v244, v245
	s_mov_b64 s[44:45], exec
	s_mov_b64 exec, s[42:43]
	global_store_dwordx4 v168, v[220:223], s[2:3]
	s_mov_b64 exec, s[44:45]
	v_add_u32_e32 v168, 0x2b00, v168
	v_mov_b32_e32 v242, v156
	v_mov_b32_e32 v243, v157
	v_mov_b32_e32 v244, v158
	v_mov_b32_e32 v245, v159
	v_fmac_f32_dpp v242, v84, v132 row_shr:1 row_mask:0xf bank_mask:0xf bound_ctrl:1
	v_fmac_f32_dpp v243, v85, v133 row_shr:1 row_mask:0xf bank_mask:0xf bound_ctrl:1
	v_fmac_f32_dpp v244, v86, v134 row_shr:1 row_mask:0xf bank_mask:0xf bound_ctrl:1
	v_fmac_f32_dpp v245, v87, v135 row_shr:1 row_mask:0xf bank_mask:0xf bound_ctrl:1
	v_pk_fma_f32 v[242:243], v[136:137], v[128:129], v[242:243]
	v_pk_fma_f32 v[244:245], v[138:139], v[130:131], v[244:245]
	v_pk_fma_f32 v[242:243], v[140:141], v[120:121], v[242:243]
	v_pk_fma_f32 v[244:245], v[142:143], v[122:123], v[244:245]
	v_mul_f32_e32 v246, 0xbfb8aa3b, v242
	v_mul_f32_e32 v247, 0xbfb8aa3b, v243
	v_mul_f32_e32 v248, 0xbfb8aa3b, v244
	v_mul_f32_e32 v249, 0xbfb8aa3b, v245
	v_exp_f32_e32 v246, v246
	v_exp_f32_e32 v247, v247
	v_exp_f32_e32 v248, v248
	v_exp_f32_e32 v249, v249
	s_nop 0
	v_pk_add_f32 v[246:247], v[246:247], 1.0 op_sel_hi:[1,0]
	v_pk_add_f32 v[248:249], v[248:249], 1.0 op_sel_hi:[1,0]
	v_rcp_f32_e32 v246, v246
	v_rcp_f32_e32 v247, v247
	v_rcp_f32_e32 v248, v248
	v_rcp_f32_e32 v249, v249
	s_nop 0
	v_pk_mul_f32 v[242:243], v[242:243], v[246:247]
	v_pk_mul_f32 v[244:245], v[244:245], v[248:249]
	v_mov_b32_e32 v246, v160
	v_mov_b32_e32 v247, v161
	v_mov_b32_e32 v248, v162
	v_mov_b32_e32 v249, v163
	v_fmac_f32_dpp v246, v72, v144 row_shr:1 row_mask:0xf bank_mask:0xf bound_ctrl:1
	v_fmac_f32_dpp v247, v73, v145 row_shr:1 row_mask:0xf bank_mask:0xf bound_ctrl:1
	v_fmac_f32_dpp v248, v74, v146 row_shr:1 row_mask:0xf bank_mask:0xf bound_ctrl:1
	v_fmac_f32_dpp v249, v75, v147 row_shr:1 row_mask:0xf bank_mask:0xf bound_ctrl:1
	v_pk_fma_f32 v[246:247], v[148:149], v[124:125], v[246:247]
	v_pk_fma_f32 v[248:249], v[150:151], v[126:127], v[248:249]
	v_pk_fma_f32 v[246:247], v[152:153], v[116:117], v[246:247]
	v_pk_fma_f32 v[248:249], v[154:155], v[118:119], v[248:249]
	v_pk_mul_f32 v[242:243], v[246:247], v[242:243]
; __device__ __forceinline__ unsigned cvt_pk_bf16(float lo, float hi) { const f32x2v v = {lo, hi}; const b16x2v r = __builtin_convertvector(v, b16x2v); return __builtin_bit_cast(unsigned, r); }
; __device__ __forceinline__ float silu_f(float v) { return v / (1.0f + fexp2(-v * LOG2E)); }
; __device__ __forceinline__ void conv_epilogue(const GemmDesc& d, const f32x4 (&acc)[2][2][4][2], const Unit& u, int wr, int wc, int fr, int fq, LAS unsigned char* lds) {
;     ...
;     for (int n = 0; n < 2; ++n) {
;         const int ch = ch0 + 4 * n;
;         const f32x4 wg0 = *(const f32x4*)(d.R + ch), wg1 = *(const f32x4*)(d.R + 11008 + ch), wg2 = *(const f32x4*)(d.R + 22016 + ch);
;         const f32x4 wu0 = *(const f32x4*)(d.R + DFF + ch), wu1 = *(const f32x4*)(d.R + 11008 + DFF + ch), wu2 = *(const f32x4*)(d.R + 22016 + DFF + ch);
;         const f32x4 bg = *(const f32x4*)(d.rope + ch), bu = *(const f32x4*)(d.rope + DFF + ch);
;         f32x4 pg2 = dpp_prev(acc[1][0][2][n]), pg1 = dpp_prev(acc[1][0][3][n]), pu2 = dpp_prev(acc[1][1][2][n]), pu1 = dpp_prev(acc[1][1][3][n]);
;         if (fr == 0) { pg2 = (f32x4){0.f, 0.f, 0.f, 0.f}; pg1 = pg2; pu2 = pg2; pu1 = pg2; }
; #pragma unroll
;         for (int e = 0; e < 8; ++e) {
;             const f32x4 cg_ = acc[e >> 2][0][e & 3][n], cu_ = acc[e >> 2][1][e & 3][n];
;             const f32x4 yg = bg + wg0 * pg2 + wg1 * pg1 + wg2 * cg_;
;             const f32x4 yu = bu + wu0 * pu2 + wu1 * pu1 + wu2 * cu_;
;             f32x4 r;
; #pragma unroll
;             for (int j = 0; j < 4; ++j) r[j] = silu_f(yg[j]) * yu[j];
;             u32x2 pk; pk.x = cvt_pk_bf16(r[0], r[1]); pk.y = cvt_pk_bf16(r[2], r[3]);
;             { const bool skip = (fr == 0) && (e < 2) && !(wr == 0 && seq_start);
;               if (!skip) *(u32x2*)(gout + (size_t)(u.pm * 256 + 8 * L + e) * DFF + ch) = pk; }
;             pg2 = pg1; pg1 = cg_; pu2 = pu1; pu1 = cu_;
	v_pk_mul_f32 v[244:245], v[248:249], v[244:245]
	v_cvt_pk_bf16_f32 v220, v242, v243
	v_cvt_pk_bf16_f32 v221, v244, v245
	v_mov_b32_e32 v242, v234
	v_mov_b32_e32 v243, v235
	v_mov_b32_e32 v244, v236
	v_mov_b32_e32 v245, v237
	v_fmac_f32_dpp v242, v16, v178 row_shr:1 row_mask:0xf bank_mask:0xf bound_ctrl:1
	v_fmac_f32_dpp v243, v17, v179 row_shr:1 row_mask:0xf bank_mask:0xf bound_ctrl:1
	v_fmac_f32_dpp v244, v18, v180 row_shr:1 row_mask:0xf bank_mask:0xf bound_ctrl:1
	v_fmac_f32_dpp v245, v19, v181 row_shr:1 row_mask:0xf bank_mask:0xf bound_ctrl:1
	v_pk_fma_f32 v[242:243], v[182:183], v[64:65], v[242:243]
	v_pk_fma_f32 v[244:245], v[184:185], v[66:67], v[244:245]
	v_pk_fma_f32 v[242:243], v[186:187], v[56:57], v[242:243]
	v_pk_fma_f32 v[244:245], v[188:189], v[58:59], v[244:245]
	v_mul_f32_e32 v246, 0xbfb8aa3b, v242
	v_mul_f32_e32 v247, 0xbfb8aa3b, v243
	v_mul_f32_e32 v248, 0xbfb8aa3b, v244
	v_mul_f32_e32 v249, 0xbfb8aa3b, v245
	v_exp_f32_e32 v246, v246
	v_exp_f32_e32 v247, v247
	v_exp_f32_e32 v248, v248
	v_exp_f32_e32 v249, v249
	s_nop 0
	v_pk_add_f32 v[246:247], v[246:247], 1.0 op_sel_hi:[1,0]
	v_pk_add_f32 v[248:249], v[248:249], 1.0 op_sel_hi:[1,0]
	v_rcp_f32_e32 v246, v246
	v_rcp_f32_e32 v247, v247
	v_rcp_f32_e32 v248, v248
	v_rcp_f32_e32 v249, v249
	s_nop 0
	v_pk_mul_f32 v[242:243], v[242:243], v[246:247]
	v_pk_mul_f32 v[244:245], v[244:245], v[248:249]
	v_mov_b32_e32 v246, v238
	v_mov_b32_e32 v247, v239
	v_mov_b32_e32 v248, v240
	v_mov_b32_e32 v249, v241
	v_fmac_f32_dpp v246, v4, v190 row_shr:1 row_mask:0xf bank_mask:0xf bound_ctrl:1
	v_fmac_f32_dpp v247, v5, v191 row_shr:1 row_mask:0xf bank_mask:0xf bound_ctrl:1
	v_fmac_f32_dpp v248, v6, v192 row_shr:1 row_mask:0xf bank_mask:0xf bound_ctrl:1
	v_fmac_f32_dpp v249, v7, v193 row_shr:1 row_mask:0xf bank_mask:0xf bound_ctrl:1
	v_pk_fma_f32 v[246:247], v[194:195], v[60:61], v[246:247]
	v_pk_fma_f32 v[248:249], v[196:197], v[62:63], v[248:249]
	v_pk_fma_f32 v[246:247], v[230:231], v[52:53], v[246:247]
	v_pk_fma_f32 v[248:249], v[232:233], v[54:55], v[248:249]
	v_pk_mul_f32 v[242:243], v[246:247], v[242:243]
	v_pk_mul_f32 v[244:245], v[248:249], v[244:245]
	v_cvt_pk_bf16_f32 v222, v242, v243
	v_cvt_pk_bf16_f32 v223, v244, v245
	s_mov_b64 s[44:45], exec
	s_mov_b64 exec, s[42:43]
	global_store_dwordx4 v168, v[220:223], s[2:3]
	s_mov_b64 exec, s[44:45]
	v_add_u32_e32 v168, 0x2b00, v168
	v_pk_fma_f32 v[242:243], v[132:133], v[128:129], v[156:157]
	v_pk_fma_f32 v[244:245], v[134:135], v[130:131], v[158:159]
	v_pk_fma_f32 v[242:243], v[136:137], v[120:121], v[242:243]
	v_pk_fma_f32 v[244:245], v[138:139], v[122:123], v[244:245]
	v_pk_fma_f32 v[242:243], v[140:141], v[112:113], v[242:243]
	v_pk_fma_f32 v[244:245], v[142:143], v[114:115], v[244:245]
	v_mul_f32_e32 v246, 0xbfb8aa3b, v242
	v_mul_f32_e32 v247, 0xbfb8aa3b, v243
	v_mul_f32_e32 v248, 0xbfb8aa3b, v244
	v_mul_f32_e32 v249, 0xbfb8aa3b, v245
	v_exp_f32_e32 v246, v246
	v_exp_f32_e32 v247, v247
	v_exp_f32_e32 v248, v248
	v_exp_f32_e32 v249, v249
	s_nop 0
	v_pk_add_f32 v[246:247], v[246:247], 1.0 op_sel_hi:[1,0]
	v_pk_add_f32 v[248:249], v[248:249], 1.0 op_sel_hi:[1,0]
	v_rcp_f32_e32 v246, v246
	v_rcp_f32_e32 v247, v247
	v_rcp_f32_e32 v248, v248
	v_rcp_f32_e32 v249, v249
	s_nop 0
	v_pk_mul_f32 v[242:243], v[242:243], v[246:247]
	v_pk_mul_f32 v[244:245], v[244:245], v[248:249]
	v_pk_fma_f32 v[246:247], v[144:145], v[124:125], v[160:161]
	v_pk_fma_f32 v[248:249], v[146:147], v[126:127], v[162:163]
	v_pk_fma_f32 v[246:247], v[148:149], v[116:117], v[246:247]
	v_pk_fma_f32 v[248:249], v[150:151], v[118:119], v[248:249]
	v_pk_fma_f32 v[246:247], v[152:153], v[108:109], v[246:247]
	v_pk_fma_f32 v[248:249], v[154:155], v[110:111], v[248:249]
	v_pk_mul_f32 v[242:243], v[246:247], v[242:243]
	v_pk_mul_f32 v[244:245], v[248:249], v[244:245]
	v_cvt_pk_bf16_f32 v220, v242, v243
	v_cvt_pk_bf16_f32 v221, v244, v245
	v_pk_fma_f32 v[242:243], v[178:179], v[64:65], v[234:235]
	v_pk_fma_f32 v[244:245], v[180:181], v[66:67], v[236:237]
	v_pk_fma_f32 v[242:243], v[182:183], v[56:57], v[242:243]
	v_pk_fma_f32 v[244:245], v[184:185], v[58:59], v[244:245]
	v_pk_fma_f32 v[242:243], v[186:187], v[48:49], v[242:243]
	v_pk_fma_f32 v[244:245], v[188:189], v[50:51], v[244:245]
	v_mul_f32_e32 v246, 0xbfb8aa3b, v242
	v_mul_f32_e32 v247, 0xbfb8aa3b, v243
	v_mul_f32_e32 v248, 0xbfb8aa3b, v244
	v_mul_f32_e32 v249, 0xbfb8aa3b, v245
	v_exp_f32_e32 v246, v246
	v_exp_f32_e32 v247, v247
	v_exp_f32_e32 v248, v248
	v_exp_f32_e32 v249, v249
	s_nop 0
	v_pk_add_f32 v[246:247], v[246:247], 1.0 op_sel_hi:[1,0]
	v_pk_add_f32 v[248:249], v[248:249], 1.0 op_sel_hi:[1,0]
	v_rcp_f32_e32 v246, v246
	v_rcp_f32_e32 v247, v247
	v_rcp_f32_e32 v248, v248
	v_rcp_f32_e32 v249, v249
	s_nop 0
	v_pk_mul_f32 v[242:243], v[242:243], v[246:247]
	v_pk_mul_f32 v[244:245], v[244:245], v[248:249]
	v_pk_fma_f32 v[246:247], v[190:191], v[60:61], v[238:239]
	v_pk_fma_f32 v[248:249], v[192:193], v[62:63], v[240:241]
	v_pk_fma_f32 v[246:247], v[194:195], v[52:53], v[246:247]
	v_pk_fma_f32 v[248:249], v[196:197], v[54:55], v[248:249]
	v_pk_fma_f32 v[246:247], v[230:231], v[44:45], v[246:247]
	v_pk_fma_f32 v[248:249], v[232:233], v[46:47], v[248:249]
	v_pk_mul_f32 v[242:243], v[246:247], v[242:243]
	v_pk_mul_f32 v[244:245], v[248:249], v[244:245]
	v_cvt_pk_bf16_f32 v222, v242, v243
	v_cvt_pk_bf16_f32 v223, v244, v245
	global_store_dwordx4 v168, v[220:223], s[2:3]
	v_add_u32_e32 v168, 0x2b00, v168
	v_pk_fma_f32 v[242:243], v[132:133], v[120:121], v[156:157]
	v_pk_fma_f32 v[244:245], v[134:135], v[122:123], v[158:159]
	v_pk_fma_f32 v[242:243], v[136:137], v[112:113], v[242:243]
	v_pk_fma_f32 v[244:245], v[138:139], v[114:115], v[244:245]
; __device__ __forceinline__ unsigned cvt_pk_bf16(float lo, float hi) { const f32x2v v = {lo, hi}; const b16x2v r = __builtin_convertvector(v, b16x2v); return __builtin_bit_cast(unsigned, r); }
; __device__ __forceinline__ float silu_f(float v) { return v / (1.0f + fexp2(-v * LOG2E)); }
; __device__ __forceinline__ void conv_epilogue(const GemmDesc& d, const f32x4 (&acc)[2][2][4][2], const Unit& u, int wr, int wc, int fr, int fq, LAS unsigned char* lds) {
;     ...
;     for (int n = 0; n < 2; ++n) {
;         const int ch = ch0 + 4 * n;
;         const f32x4 wg0 = *(const f32x4*)(d.R + ch), wg1 = *(const f32x4*)(d.R + 11008 + ch), wg2 = *(const f32x4*)(d.R + 22016 + ch);
;         const f32x4 wu0 = *(const f32x4*)(d.R + DFF + ch), wu1 = *(const f32x4*)(d.R + 11008 + DFF + ch), wu2 = *(const f32x4*)(d.R + 22016 + DFF + ch);
;         const f32x4 bg = *(const f32x4*)(d.rope + ch), bu = *(const f32x4*)(d.rope + DFF + ch);
;         f32x4 pg2 = dpp_prev(acc[1][0][2][n]), pg1 = dpp_prev(acc[1][0][3][n]), pu2 = dpp_prev(acc[1][1][2][n]), pu1 = dpp_prev(acc[1][1][3][n]);
;         if (fr == 0) { pg2 = (f32x4){0.f, 0.f, 0.f, 0.f}; pg1 = pg2; pu2 = pg2; pu1 = pg2; }
; #pragma unroll
;         for (int e = 0; e < 8; ++e) {
;             const f32x4 cg_ = acc[e >> 2][0][e & 3][n], cu_ = acc[e >> 2][1][e & 3][n];
;             const f32x4 yg = bg + wg0 * pg2 + wg1 * pg1 + wg2 * cg_;
;             const f32x4 yu = bu + wu0 * pu2 + wu1 * pu1 + wu2 * cu_;
;             f32x4 r;
; #pragma unroll
;             for (int j = 0; j < 4; ++j) r[j] = silu_f(yg[j]) * yu[j];
;             u32x2 pk; pk.x = cvt_pk_bf16(r[0], r[1]); pk.y = cvt_pk_bf16(r[2], r[3]);
;             { const bool skip = (fr == 0) && (e < 2) && !(wr == 0 && seq_start);
;               if (!skip) *(u32x2*)(gout + (size_t)(u.pm * 256 + 8 * L + e) * DFF + ch) = pk; }
;             pg2 = pg1; pg1 = cg_; pu2 = pu1; pu1 = cu_;
	v_pk_fma_f32 v[242:243], v[140:141], v[104:105], v[242:243]
	v_pk_fma_f32 v[244:245], v[142:143], v[106:107], v[244:245]
	v_mul_f32_e32 v246, 0xbfb8aa3b, v242
	v_mul_f32_e32 v247, 0xbfb8aa3b, v243
	v_mul_f32_e32 v248, 0xbfb8aa3b, v244
	v_mul_f32_e32 v249, 0xbfb8aa3b, v245
	v_exp_f32_e32 v246, v246
	v_exp_f32_e32 v247, v247
	v_exp_f32_e32 v248, v248
	v_exp_f32_e32 v249, v249
	s_nop 0
	v_pk_add_f32 v[246:247], v[246:247], 1.0 op_sel_hi:[1,0]
	v_pk_add_f32 v[248:249], v[248:249], 1.0 op_sel_hi:[1,0]
	v_rcp_f32_e32 v246, v246
	v_rcp_f32_e32 v247, v247
	v_rcp_f32_e32 v248, v248
	v_rcp_f32_e32 v249, v249
	s_nop 0
	v_pk_mul_f32 v[242:243], v[242:243], v[246:247]
	v_pk_mul_f32 v[244:245], v[244:245], v[248:249]
	v_pk_fma_f32 v[246:247], v[144:145], v[116:117], v[160:161]
	v_pk_fma_f32 v[248:249], v[146:147], v[118:119], v[162:163]
	v_pk_fma_f32 v[246:247], v[148:149], v[108:109], v[246:247]
	v_pk_fma_f32 v[248:249], v[150:151], v[110:111], v[248:249]
	v_pk_fma_f32 v[246:247], v[152:153], v[100:101], v[246:247]
	v_pk_fma_f32 v[248:249], v[154:155], v[102:103], v[248:249]
	v_pk_mul_f32 v[242:243], v[246:247], v[242:243]
	v_pk_mul_f32 v[244:245], v[248:249], v[244:245]
	v_cvt_pk_bf16_f32 v220, v242, v243
	v_cvt_pk_bf16_f32 v221, v244, v245
	v_pk_fma_f32 v[242:243], v[178:179], v[56:57], v[234:235]
	v_pk_fma_f32 v[244:245], v[180:181], v[58:59], v[236:237]
	v_pk_fma_f32 v[242:243], v[182:183], v[48:49], v[242:243]
	v_pk_fma_f32 v[244:245], v[184:185], v[50:51], v[244:245]
	v_pk_fma_f32 v[242:243], v[186:187], v[40:41], v[242:243]
	v_pk_fma_f32 v[244:245], v[188:189], v[42:43], v[244:245]
	v_mul_f32_e32 v246, 0xbfb8aa3b, v242
	v_mul_f32_e32 v247, 0xbfb8aa3b, v243
	v_mul_f32_e32 v248, 0xbfb8aa3b, v244
	v_mul_f32_e32 v249, 0xbfb8aa3b, v245
	v_exp_f32_e32 v246, v246
	v_exp_f32_e32 v247, v247
	v_exp_f32_e32 v248, v248
	v_exp_f32_e32 v249, v249
	s_nop 0
	v_pk_add_f32 v[246:247], v[246:247], 1.0 op_sel_hi:[1,0]
	v_pk_add_f32 v[248:249], v[248:249], 1.0 op_sel_hi:[1,0]
	v_rcp_f32_e32 v246, v246
	v_rcp_f32_e32 v247, v247
	v_rcp_f32_e32 v248, v248
	v_rcp_f32_e32 v249, v249
	s_nop 0
	v_pk_mul_f32 v[242:243], v[242:243], v[246:247]
	v_pk_mul_f32 v[244:245], v[244:245], v[248:249]
	v_pk_fma_f32 v[246:247], v[190:191], v[52:53], v[238:239]
	v_pk_fma_f32 v[248:249], v[192:193], v[54:55], v[240:241]
	v_pk_fma_f32 v[246:247], v[194:195], v[44:45], v[246:247]
	v_pk_fma_f32 v[248:249], v[196:197], v[46:47], v[248:249]
	v_pk_fma_f32 v[246:247], v[230:231], v[36:37], v[246:247]
	v_pk_fma_f32 v[248:249], v[232:233], v[38:39], v[248:249]
	v_pk_mul_f32 v[242:243], v[246:247], v[242:243]
	v_pk_mul_f32 v[244:245], v[248:249], v[244:245]
	v_cvt_pk_bf16_f32 v222, v242, v243
	v_cvt_pk_bf16_f32 v223, v244, v245
	global_store_dwordx4 v168, v[220:223], s[2:3]
	v_add_u32_e32 v168, 0x2b00, v168
	v_pk_fma_f32 v[242:243], v[132:133], v[112:113], v[156:157]
	v_pk_fma_f32 v[244:245], v[134:135], v[114:115], v[158:159]
	v_pk_fma_f32 v[242:243], v[136:137], v[104:105], v[242:243]
	v_pk_fma_f32 v[244:245], v[138:139], v[106:107], v[244:245]
	v_pk_fma_f32 v[242:243], v[140:141], v[96:97], v[242:243]
	v_pk_fma_f32 v[244:245], v[142:143], v[98:99], v[244:245]
	v_mul_f32_e32 v246, 0xbfb8aa3b, v242
	v_mul_f32_e32 v247, 0xbfb8aa3b, v243
	v_mul_f32_e32 v248, 0xbfb8aa3b, v244
	v_mul_f32_e32 v249, 0xbfb8aa3b, v245
	v_exp_f32_e32 v246, v246
	v_exp_f32_e32 v247, v247
	v_exp_f32_e32 v248, v248
	v_exp_f32_e32 v249, v249
	s_nop 0
	v_pk_add_f32 v[246:247], v[246:247], 1.0 op_sel_hi:[1,0]
	v_pk_add_f32 v[248:249], v[248:249], 1.0 op_sel_hi:[1,0]
	v_rcp_f32_e32 v246, v246
	v_rcp_f32_e32 v247, v247
	v_rcp_f32_e32 v248, v248
	v_rcp_f32_e32 v249, v249
	s_nop 0
	v_pk_mul_f32 v[242:243], v[242:243], v[246:247]
	v_pk_mul_f32 v[244:245], v[244:245], v[248:249]
	v_pk_fma_f32 v[246:247], v[144:145], v[108:109], v[160:161]
	v_pk_fma_f32 v[248:249], v[146:147], v[110:111], v[162:163]
	v_pk_fma_f32 v[246:247], v[148:149], v[100:101], v[246:247]
	v_pk_fma_f32 v[248:249], v[150:151], v[102:103], v[248:249]
	v_pk_fma_f32 v[246:247], v[152:153], v[92:93], v[246:247]
	v_pk_fma_f32 v[248:249], v[154:155], v[94:95], v[248:249]
	v_pk_mul_f32 v[242:243], v[246:247], v[242:243]
	v_pk_mul_f32 v[244:245], v[248:249], v[244:245]
	v_cvt_pk_bf16_f32 v220, v242, v243
	v_cvt_pk_bf16_f32 v221, v244, v245
	v_pk_fma_f32 v[242:243], v[178:179], v[48:49], v[234:235]
	v_pk_fma_f32 v[244:245], v[180:181], v[50:51], v[236:237]
	v_pk_fma_f32 v[242:243], v[182:183], v[40:41], v[242:243]
	v_pk_fma_f32 v[244:245], v[184:185], v[42:43], v[244:245]
	v_pk_fma_f32 v[242:243], v[186:187], v[32:33], v[242:243]
	v_pk_fma_f32 v[244:245], v[188:189], v[34:35], v[244:245]
	v_mul_f32_e32 v246, 0xbfb8aa3b, v242
	v_mul_f32_e32 v247, 0xbfb8aa3b, v243
	v_mul_f32_e32 v248, 0xbfb8aa3b, v244
	v_mul_f32_e32 v249, 0xbfb8aa3b, v245
	v_exp_f32_e32 v246, v246
	v_exp_f32_e32 v247, v247
	v_exp_f32_e32 v248, v248
	v_exp_f32_e32 v249, v249
	s_nop 0
	v_pk_add_f32 v[246:247], v[246:247], 1.0 op_sel_hi:[1,0]
	v_pk_add_f32 v[248:249], v[248:249], 1.0 op_sel_hi:[1,0]
	v_rcp_f32_e32 v246, v246
	v_rcp_f32_e32 v247, v247
	v_rcp_f32_e32 v248, v248
	v_rcp_f32_e32 v249, v249
	s_nop 0
	v_pk_mul_f32 v[242:243], v[242:243], v[246:247]
	v_pk_mul_f32 v[244:245], v[244:245], v[248:249]
	v_pk_fma_f32 v[246:247], v[190:191], v[44:45], v[238:239]
	v_pk_fma_f32 v[248:249], v[192:193], v[46:47], v[240:241]
	v_pk_fma_f32 v[246:247], v[194:195], v[36:37], v[246:247]
	v_pk_fma_f32 v[248:249], v[196:197], v[38:39], v[248:249]
	v_pk_fma_f32 v[246:247], v[230:231], v[28:29], v[246:247]
	v_pk_fma_f32 v[248:249], v[232:233], v[30:31], v[248:249]
	v_pk_mul_f32 v[242:243], v[246:247], v[242:243]
; __device__ __forceinline__ unsigned cvt_pk_bf16(float lo, float hi) { const f32x2v v = {lo, hi}; const b16x2v r = __builtin_convertvector(v, b16x2v); return __builtin_bit_cast(unsigned, r); }
; __device__ __forceinline__ float silu_f(float v) { return v / (1.0f + fexp2(-v * LOG2E)); }
; __device__ __forceinline__ void conv_epilogue(const GemmDesc& d, const f32x4 (&acc)[2][2][4][2], const Unit& u, int wr, int wc, int fr, int fq, LAS unsigned char* lds) {
;     ...
;     for (int n = 0; n < 2; ++n) {
;         const int ch = ch0 + 4 * n;
;         const f32x4 wg0 = *(const f32x4*)(d.R + ch), wg1 = *(const f32x4*)(d.R + 11008 + ch), wg2 = *(const f32x4*)(d.R + 22016 + ch);
;         const f32x4 wu0 = *(const f32x4*)(d.R + DFF + ch), wu1 = *(const f32x4*)(d.R + 11008 + DFF + ch), wu2 = *(const f32x4*)(d.R + 22016 + DFF + ch);
;         const f32x4 bg = *(const f32x4*)(d.rope + ch), bu = *(const f32x4*)(d.rope + DFF + ch);
;         f32x4 pg2 = dpp_prev(acc[1][0][2][n]), pg1 = dpp_prev(acc[1][0][3][n]), pu2 = dpp_prev(acc[1][1][2][n]), pu1 = dpp_prev(acc[1][1][3][n]);
;         if (fr == 0) { pg2 = (f32x4){0.f, 0.f, 0.f, 0.f}; pg1 = pg2; pu2 = pg2; pu1 = pg2; }
; #pragma unroll
;         for (int e = 0; e < 8; ++e) {
;             const f32x4 cg_ = acc[e >> 2][0][e & 3][n], cu_ = acc[e >> 2][1][e & 3][n];
;             const f32x4 yg = bg + wg0 * pg2 + wg1 * pg1 + wg2 * cg_;
;             const f32x4 yu = bu + wu0 * pu2 + wu1 * pu1 + wu2 * cu_;
;             f32x4 r;
; #pragma unroll
;             for (int j = 0; j < 4; ++j) r[j] = silu_f(yg[j]) * yu[j];
;             u32x2 pk; pk.x = cvt_pk_bf16(r[0], r[1]); pk.y = cvt_pk_bf16(r[2], r[3]);
;             { const bool skip = (fr == 0) && (e < 2) && !(wr == 0 && seq_start);
;               if (!skip) *(u32x2*)(gout + (size_t)(u.pm * 256 + 8 * L + e) * DFF + ch) = pk; }
;             pg2 = pg1; pg1 = cg_; pu2 = pu1; pu1 = cu_;
;         }
	v_pk_mul_f32 v[244:245], v[248:249], v[244:245]
	v_cvt_pk_bf16_f32 v222, v242, v243
	v_cvt_pk_bf16_f32 v223, v244, v245
	global_store_dwordx4 v168, v[220:223], s[2:3]
	v_add_u32_e32 v168, 0x2b00, v168
	v_pk_fma_f32 v[242:243], v[132:133], v[104:105], v[156:157]
	v_pk_fma_f32 v[244:245], v[134:135], v[106:107], v[158:159]
	v_pk_fma_f32 v[242:243], v[136:137], v[96:97], v[242:243]
	v_pk_fma_f32 v[244:245], v[138:139], v[98:99], v[244:245]
	v_pk_fma_f32 v[242:243], v[140:141], v[88:89], v[242:243]
	v_pk_fma_f32 v[244:245], v[142:143], v[90:91], v[244:245]
	v_mul_f32_e32 v246, 0xbfb8aa3b, v242
	v_mul_f32_e32 v247, 0xbfb8aa3b, v243
	v_mul_f32_e32 v248, 0xbfb8aa3b, v244
	v_mul_f32_e32 v249, 0xbfb8aa3b, v245
	v_exp_f32_e32 v246, v246
	v_exp_f32_e32 v247, v247
	v_exp_f32_e32 v248, v248
	v_exp_f32_e32 v249, v249
	s_nop 0
	v_pk_add_f32 v[246:247], v[246:247], 1.0 op_sel_hi:[1,0]
	v_pk_add_f32 v[248:249], v[248:249], 1.0 op_sel_hi:[1,0]
	v_rcp_f32_e32 v246, v246
	v_rcp_f32_e32 v247, v247
	v_rcp_f32_e32 v248, v248
	v_rcp_f32_e32 v249, v249
	s_nop 0
	v_pk_mul_f32 v[242:243], v[242:243], v[246:247]
	v_pk_mul_f32 v[244:245], v[244:245], v[248:249]
	v_pk_fma_f32 v[246:247], v[144:145], v[100:101], v[160:161]
	v_pk_fma_f32 v[248:249], v[146:147], v[102:103], v[162:163]
	v_pk_fma_f32 v[246:247], v[148:149], v[92:93], v[246:247]
	v_pk_fma_f32 v[248:249], v[150:151], v[94:95], v[248:249]
	v_pk_fma_f32 v[246:247], v[152:153], v[80:81], v[246:247]
	v_pk_fma_f32 v[248:249], v[154:155], v[82:83], v[248:249]
	v_pk_mul_f32 v[242:243], v[246:247], v[242:243]
	v_pk_mul_f32 v[244:245], v[248:249], v[244:245]
	v_cvt_pk_bf16_f32 v220, v242, v243
	v_cvt_pk_bf16_f32 v221, v244, v245
	v_pk_fma_f32 v[242:243], v[178:179], v[40:41], v[234:235]
	v_pk_fma_f32 v[244:245], v[180:181], v[42:43], v[236:237]
	v_pk_fma_f32 v[242:243], v[182:183], v[32:33], v[242:243]
	v_pk_fma_f32 v[244:245], v[184:185], v[34:35], v[244:245]
	v_pk_fma_f32 v[242:243], v[186:187], v[24:25], v[242:243]
	v_pk_fma_f32 v[244:245], v[188:189], v[26:27], v[244:245]
	v_mul_f32_e32 v246, 0xbfb8aa3b, v242
	v_mul_f32_e32 v247, 0xbfb8aa3b, v243
	v_mul_f32_e32 v248, 0xbfb8aa3b, v244
	v_mul_f32_e32 v249, 0xbfb8aa3b, v245
	v_exp_f32_e32 v246, v246
	v_exp_f32_e32 v247, v247
	v_exp_f32_e32 v248, v248
	v_exp_f32_e32 v249, v249
	s_nop 0
	v_pk_add_f32 v[246:247], v[246:247], 1.0 op_sel_hi:[1,0]
	v_pk_add_f32 v[248:249], v[248:249], 1.0 op_sel_hi:[1,0]
	v_rcp_f32_e32 v246, v246
	v_rcp_f32_e32 v247, v247
	v_rcp_f32_e32 v248, v248
	v_rcp_f32_e32 v249, v249
	s_nop 0
	v_pk_mul_f32 v[242:243], v[242:243], v[246:247]
	v_pk_mul_f32 v[244:245], v[244:245], v[248:249]
	v_pk_fma_f32 v[246:247], v[190:191], v[36:37], v[238:239]
	v_pk_fma_f32 v[248:249], v[192:193], v[38:39], v[240:241]
	v_pk_fma_f32 v[246:247], v[194:195], v[28:29], v[246:247]
	v_pk_fma_f32 v[248:249], v[196:197], v[30:31], v[248:249]
	v_pk_fma_f32 v[246:247], v[230:231], v[12:13], v[246:247]
	v_pk_fma_f32 v[248:249], v[232:233], v[14:15], v[248:249]
	v_pk_mul_f32 v[242:243], v[246:247], v[242:243]
	v_pk_mul_f32 v[244:245], v[248:249], v[244:245]
	v_cvt_pk_bf16_f32 v222, v242, v243
	v_cvt_pk_bf16_f32 v223, v244, v245
	global_store_dwordx4 v168, v[220:223], s[2:3]
	v_add_u32_e32 v168, 0x2b00, v168
	v_pk_fma_f32 v[242:243], v[132:133], v[96:97], v[156:157]
	v_pk_fma_f32 v[244:245], v[134:135], v[98:99], v[158:159]
	v_pk_fma_f32 v[242:243], v[136:137], v[88:89], v[242:243]
	v_pk_fma_f32 v[244:245], v[138:139], v[90:91], v[244:245]
	v_pk_fma_f32 v[242:243], v[140:141], v[68:69], v[242:243]
	v_pk_fma_f32 v[244:245], v[142:143], v[70:71], v[244:245]
	v_mul_f32_e32 v246, 0xbfb8aa3b, v242
	v_mul_f32_e32 v247, 0xbfb8aa3b, v243
	v_mul_f32_e32 v248, 0xbfb8aa3b, v244
	v_mul_f32_e32 v249, 0xbfb8aa3b, v245
	v_exp_f32_e32 v246, v246
	v_exp_f32_e32 v247, v247
	v_exp_f32_e32 v248, v248
	v_exp_f32_e32 v249, v249
	s_nop 0
	v_pk_add_f32 v[246:247], v[246:247], 1.0 op_sel_hi:[1,0]
	v_pk_add_f32 v[248:249], v[248:249], 1.0 op_sel_hi:[1,0]
	v_rcp_f32_e32 v246, v246
	v_rcp_f32_e32 v247, v247
	v_rcp_f32_e32 v248, v248
	v_rcp_f32_e32 v249, v249
	s_nop 0
	v_pk_mul_f32 v[242:243], v[242:243], v[246:247]
	v_pk_mul_f32 v[244:245], v[244:245], v[248:249]
	v_pk_fma_f32 v[246:247], v[144:145], v[92:93], v[160:161]
	v_pk_fma_f32 v[248:249], v[146:147], v[94:95], v[162:163]
	v_pk_fma_f32 v[246:247], v[148:149], v[80:81], v[246:247]
	v_pk_fma_f32 v[248:249], v[150:151], v[82:83], v[248:249]
	v_pk_fma_f32 v[246:247], v[152:153], v[76:77], v[246:247]
	v_pk_fma_f32 v[248:249], v[154:155], v[78:79], v[248:249]
	v_pk_mul_f32 v[242:243], v[246:247], v[242:243]
	v_pk_mul_f32 v[244:245], v[248:249], v[244:245]
; __device__ __forceinline__ unsigned cvt_pk_bf16(float lo, float hi) { const f32x2v v = {lo, hi}; const b16x2v r = __builtin_convertvector(v, b16x2v); return __builtin_bit_cast(unsigned, r); }
; __device__ __forceinline__ float silu_f(float v) { return v / (1.0f + fexp2(-v * LOG2E)); }
; __device__ __forceinline__ void conv_epilogue(const GemmDesc& d, const f32x4 (&acc)[2][2][4][2], const Unit& u, int wr, int wc, int fr, int fq, LAS unsigned char* lds) {
;     ...
; #pragma unroll
;         for (int e = 0; e < 8; ++e) {
;             const f32x4 cg_ = acc[e >> 2][0][e & 3][n], cu_ = acc[e >> 2][1][e & 3][n];
;             const f32x4 yg = bg + wg0 * pg2 + wg1 * pg1 + wg2 * cg_;
;             const f32x4 yu = bu + wu0 * pu2 + wu1 * pu1 + wu2 * cu_;
;             f32x4 r;
; #pragma unroll
;             for (int j = 0; j < 4; ++j) r[j] = silu_f(yg[j]) * yu[j];
;             u32x2 pk; pk.x = cvt_pk_bf16(r[0], r[1]); pk.y = cvt_pk_bf16(r[2], r[3]);
;             { const bool skip = (fr == 0) && (e < 2) && !(wr == 0 && seq_start);
;               if (!skip) *(u32x2*)(gout + (size_t)(u.pm * 256 + 8 * L + e) * DFF + ch) = pk; }
;             pg2 = pg1; pg1 = cg_; pu2 = pu1; pu1 = cu_;
;         }
	v_cvt_pk_bf16_f32 v220, v242, v243
	v_cvt_pk_bf16_f32 v221, v244, v245
	v_pk_fma_f32 v[242:243], v[178:179], v[32:33], v[234:235]
	v_pk_fma_f32 v[244:245], v[180:181], v[34:35], v[236:237]
	v_pk_fma_f32 v[242:243], v[182:183], v[24:25], v[242:243]
	v_pk_fma_f32 v[244:245], v[184:185], v[26:27], v[244:245]
	v_pk_fma_f32 v[242:243], v[186:187], v[20:21], v[242:243]
	v_pk_fma_f32 v[244:245], v[188:189], v[22:23], v[244:245]
	v_mul_f32_e32 v246, 0xbfb8aa3b, v242
	v_mul_f32_e32 v247, 0xbfb8aa3b, v243
	v_mul_f32_e32 v248, 0xbfb8aa3b, v244
	v_mul_f32_e32 v249, 0xbfb8aa3b, v245
	v_exp_f32_e32 v246, v246
	v_exp_f32_e32 v247, v247
	v_exp_f32_e32 v248, v248
	v_exp_f32_e32 v249, v249
	s_nop 0
	v_pk_add_f32 v[246:247], v[246:247], 1.0 op_sel_hi:[1,0]
	v_pk_add_f32 v[248:249], v[248:249], 1.0 op_sel_hi:[1,0]
	v_rcp_f32_e32 v246, v246
	v_rcp_f32_e32 v247, v247
	v_rcp_f32_e32 v248, v248
	v_rcp_f32_e32 v249, v249
	s_nop 0
	v_pk_mul_f32 v[242:243], v[242:243], v[246:247]
	v_pk_mul_f32 v[244:245], v[244:245], v[248:249]
	v_pk_fma_f32 v[246:247], v[190:191], v[28:29], v[238:239]
	v_pk_fma_f32 v[248:249], v[192:193], v[30:31], v[240:241]
	v_pk_fma_f32 v[246:247], v[194:195], v[12:13], v[246:247]
	v_pk_fma_f32 v[248:249], v[196:197], v[14:15], v[248:249]
	v_pk_fma_f32 v[246:247], v[230:231], v[8:9], v[246:247]
	v_pk_fma_f32 v[248:249], v[232:233], v[10:11], v[248:249]
	v_pk_mul_f32 v[242:243], v[246:247], v[242:243]
	v_pk_mul_f32 v[244:245], v[248:249], v[244:245]
	v_cvt_pk_bf16_f32 v222, v242, v243
	v_cvt_pk_bf16_f32 v223, v244, v245
	global_store_dwordx4 v168, v[220:223], s[2:3]
	v_add_u32_e32 v168, 0x2b00, v168
	v_pk_fma_f32 v[242:243], v[132:133], v[88:89], v[156:157]
	v_pk_fma_f32 v[244:245], v[134:135], v[90:91], v[158:159]
	v_pk_fma_f32 v[242:243], v[136:137], v[68:69], v[242:243]
	v_pk_fma_f32 v[244:245], v[138:139], v[70:71], v[244:245]
	v_pk_fma_f32 v[242:243], v[140:141], v[84:85], v[242:243]
	v_pk_fma_f32 v[244:245], v[142:143], v[86:87], v[244:245]
	v_mul_f32_e32 v246, 0xbfb8aa3b, v242
	v_mul_f32_e32 v247, 0xbfb8aa3b, v243
	v_mul_f32_e32 v248, 0xbfb8aa3b, v244
	v_mul_f32_e32 v249, 0xbfb8aa3b, v245
	v_exp_f32_e32 v246, v246
	v_exp_f32_e32 v247, v247
	v_exp_f32_e32 v248, v248
	v_exp_f32_e32 v249, v249
	s_nop 0
	v_pk_add_f32 v[246:247], v[246:247], 1.0 op_sel_hi:[1,0]
	v_pk_add_f32 v[248:249], v[248:249], 1.0 op_sel_hi:[1,0]
	v_rcp_f32_e32 v246, v246
	v_rcp_f32_e32 v247, v247
	v_rcp_f32_e32 v248, v248
	v_rcp_f32_e32 v249, v249
	s_nop 0
	v_pk_mul_f32 v[242:243], v[242:243], v[246:247]
	v_pk_mul_f32 v[244:245], v[244:245], v[248:249]
	v_pk_fma_f32 v[246:247], v[144:145], v[80:81], v[160:161]
	v_pk_fma_f32 v[248:249], v[146:147], v[82:83], v[162:163]
	v_pk_fma_f32 v[246:247], v[148:149], v[76:77], v[246:247]
	v_pk_fma_f32 v[248:249], v[150:151], v[78:79], v[248:249]
	v_pk_fma_f32 v[246:247], v[152:153], v[72:73], v[246:247]
	v_pk_fma_f32 v[248:249], v[154:155], v[74:75], v[248:249]
	v_pk_mul_f32 v[242:243], v[246:247], v[242:243]
	v_pk_mul_f32 v[244:245], v[248:249], v[244:245]
	v_cvt_pk_bf16_f32 v220, v242, v243
	v_cvt_pk_bf16_f32 v221, v244, v245
	v_pk_fma_f32 v[242:243], v[178:179], v[24:25], v[234:235]
	v_pk_fma_f32 v[244:245], v[180:181], v[26:27], v[236:237]
	v_pk_fma_f32 v[242:243], v[182:183], v[20:21], v[242:243]
	v_pk_fma_f32 v[244:245], v[184:185], v[22:23], v[244:245]
	v_pk_fma_f32 v[242:243], v[186:187], v[16:17], v[242:243]
	v_pk_fma_f32 v[244:245], v[188:189], v[18:19], v[244:245]
	v_mul_f32_e32 v246, 0xbfb8aa3b, v242
	v_mul_f32_e32 v247, 0xbfb8aa3b, v243
	v_mul_f32_e32 v248, 0xbfb8aa3b, v244
	v_mul_f32_e32 v249, 0xbfb8aa3b, v245
	v_exp_f32_e32 v246, v246
	v_exp_f32_e32 v247, v247
	v_exp_f32_e32 v248, v248
	v_exp_f32_e32 v249, v249
	s_nop 0
	v_pk_add_f32 v[246:247], v[246:247], 1.0 op_sel_hi:[1,0]
	v_pk_add_f32 v[248:249], v[248:249], 1.0 op_sel_hi:[1,0]
	v_rcp_f32_e32 v246, v246
	v_rcp_f32_e32 v247, v247
	v_rcp_f32_e32 v248, v248
	v_rcp_f32_e32 v249, v249
	s_nop 0
	v_pk_mul_f32 v[242:243], v[242:243], v[246:247]
	v_pk_mul_f32 v[244:245], v[244:245], v[248:249]
	v_pk_fma_f32 v[246:247], v[190:191], v[12:13], v[238:239]
	v_pk_fma_f32 v[248:249], v[192:193], v[14:15], v[240:241]
	v_pk_fma_f32 v[246:247], v[194:195], v[8:9], v[246:247]
	v_pk_fma_f32 v[248:249], v[196:197], v[10:11], v[248:249]
	v_pk_fma_f32 v[246:247], v[230:231], v[4:5], v[246:247]
	v_pk_fma_f32 v[248:249], v[232:233], v[6:7], v[248:249]
	v_pk_mul_f32 v[242:243], v[246:247], v[242:243]
	v_pk_mul_f32 v[244:245], v[248:249], v[244:245]
	v_cvt_pk_bf16_f32 v222, v242, v243
	v_cvt_pk_bf16_f32 v223, v244, v245
	global_store_dwordx4 v168, v[220:223], s[2:3]
	s_branch .LBB0_194

; #define LAS __attribute__((address_space(3)))
; __device__ __forceinline__ f32x4 mfma16(bf16x8 a, bf16x8 b, f32x4 c) { return __builtin_amdgcn_mfma_f32_16x16x32_bf16(a, b, c, 0, 0, 0); }
; #define LDS_BARRIER() do { asm volatile("s_waitcnt lgkmcnt(0)" ::: "memory"); __builtin_amdgcn_s_barrier(); asm volatile("" ::: "memory"); } while (0)
; #define XLOAD(kvbase, c8) do { const bf16_t* _src = (kvbase) + (((c8) >= 4) ? 2048 : 0) + ((c8) & 3) * 128 + piece * 8; \
;         _Pragma("unroll") for (int _it = 0; _it < 8; ++_it) pre[_it] = *(const u32x4*)(_src + (size_t)(srow + 32 * _it) * 4096); } while (0)
; #define XSTORE(buf) do { _Pragma("unroll") for (int _it = 0; _it < 8; ++_it) *(LAS u32x4*)((buf) + (srow + 32 * _it) * KV_STRIDE + piece * 16) = pre[_it]; } while (0)
; __device__ void cross_items(const Params& p, LAS unsigned char* lds) {
;     ...
;         for (int c = 0; c < 4; ++c) {
;             LAS unsigned char* buf = lds + (c & 1) * KV_BUF;
;             XSTORE(buf);
;             bf16x8 qf[4];
; #pragma unroll
;             for (int ks = 0; ks < 4; ++ks) qf[ks] = *(const bf16x8*)(qrow + c * 128 + 32 * ks);
;             XLOAD(kvb, c + 1);
;             LDS_BARRIER();
; #pragma unroll
;             for (int kt = 0; kt < 16; ++kt)
; #pragma unroll
;                 for (int ks = 0; ks < 4; ++ks) sc[kt] = mfma16(frag_row(buf, KV_STRIDE, 16 * kt, 32 * ks, idx, g), qf[ks], sc[kt]);
;         }
.LBB0_393:
	s_bitcmp1_b32 s8, 0
	s_cselect_b32 s9, 0x11000, 0
	s_add_i32 s9, s9, 0
	v_add3_u32 v100, s9, v0, v157
	s_waitcnt vmcnt(7)
	ds_write_b128 v100, v[8:11]
	s_waitcnt vmcnt(6)
	ds_write_b128 v100, v[12:15] offset:8704
	s_waitcnt vmcnt(5)
	ds_write_b128 v100, v[16:19] offset:17408
	s_waitcnt vmcnt(4)
	ds_write_b128 v100, v[20:23] offset:26112
	s_waitcnt vmcnt(3)
	ds_write_b128 v100, v[28:31] offset:34816
	s_waitcnt vmcnt(2)
	ds_write_b128 v100, v[32:35] offset:43520
	s_waitcnt vmcnt(1)
	ds_write_b128 v100, v[36:39] offset:52224
	s_waitcnt vmcnt(0)
	ds_write_b128 v100, v[44:47] offset:60928
	v_lshl_add_u64 v[8:9], v[116:117], 0, s[2:3]
	global_load_dwordx4 v[112:115], v[8:9], off
	global_load_dwordx4 v[108:111], v[8:9], off offset:64
	global_load_dwordx4 v[104:107], v[8:9], off offset:128
	global_load_dwordx4 v[100:103], v[8:9], off offset:192
	v_lshl_add_u64 v[44:45], v[148:149], 0, s[2:3]
	s_mov_b32 s10, 0xc400000
	v_add_co_u32_e32 v8, vcc, s10, v44
	s_mov_b32 s10, 0xc440000
	s_nop 0
	v_addc_co_u32_e32 v9, vcc, 0, v45, vcc
	v_add_co_u32_e32 v12, vcc, s10, v44
	s_mov_b32 s10, 0xc480000
	s_nop 0
	v_addc_co_u32_e32 v13, vcc, 0, v45, vcc
	v_add_co_u32_e32 v16, vcc, s10, v44
	s_mov_b32 s10, 0xc4c0000
	s_nop 0
	v_addc_co_u32_e32 v17, vcc, 0, v45, vcc
	v_add_co_u32_e32 v20, vcc, s10, v44
	s_mov_b32 s10, 0xc500000
	s_nop 0
	v_addc_co_u32_e32 v21, vcc, 0, v45, vcc
	v_add_co_u32_e32 v28, vcc, s10, v44
	s_mov_b32 s10, 0xc540000
	s_nop 0
	v_addc_co_u32_e32 v29, vcc, 0, v45, vcc
	v_add_co_u32_e32 v32, vcc, s10, v44
	s_mov_b32 s10, 0xc580000
	s_nop 0
	v_addc_co_u32_e32 v33, vcc, 0, v45, vcc
	v_add_co_u32_e32 v36, vcc, s10, v44
	s_mov_b32 s10, 0xc5c0000
	s_nop 0
	v_addc_co_u32_e32 v37, vcc, 0, v45, vcc
	v_add_co_u32_e32 v44, vcc, s10, v44
	global_load_dwordx4 v[8:11], v[8:9], off offset:256
	s_nop 0
	v_addc_co_u32_e32 v45, vcc, 0, v45, vcc
	global_load_dwordx4 v[12:15], v[12:13], off offset:256
	v_add3_u32 v118, s9, v138, v158
	global_load_dwordx4 v[16:19], v[16:17], off offset:256
	s_add_i32 s8, s8, 1
	global_load_dwordx4 v[20:23], v[20:21], off offset:256
	s_add_u32 s2, s2, 0x100
	global_load_dwordx4 v[28:31], v[28:29], off offset:256
	s_addc_u32 s3, s3, 0
	global_load_dwordx4 v[32:35], v[32:33], off offset:256
	s_cmpk_lg_i32 s2, 0x300
	global_load_dwordx4 v[36:39], v[36:37], off offset:256
	s_nop 0
	global_load_dwordx4 v[44:47], v[44:45], off offset:256
	s_waitcnt lgkmcnt(0)
	s_barrier
	ds_read_b128 v[152:155], v118
	ds_read_b128 v[220:223], v118 offset:64
	ds_read_b128 v[230:233], v118 offset:128
	ds_read_b128 v[234:237], v118 offset:192
	ds_read_b128 v[238:241], v118 offset:4352
	ds_read_b128 v[242:245], v118 offset:4416
	ds_read_b128 v[246:249], v118 offset:4480
	s_waitcnt vmcnt(11) lgkmcnt(6)
	v_mfma_f32_16x16x32_bf16 v[96:99], v[152:155], v[112:115], v[96:99]
	ds_read_b128 v[152:155], v118 offset:4544
	s_waitcnt vmcnt(10) lgkmcnt(6)
	v_mfma_f32_16x16x32_bf16 v[96:99], v[220:223], v[108:111], v[96:99]
	ds_read_b128 v[220:223], v118 offset:8704
	s_waitcnt vmcnt(9) lgkmcnt(6)
	v_mfma_f32_16x16x32_bf16 v[96:99], v[230:233], v[104:107], v[96:99]
	ds_read_b128 v[230:233], v118 offset:8768
	s_waitcnt vmcnt(8) lgkmcnt(6)
	v_mfma_f32_16x16x32_bf16 v[96:99], v[234:237], v[100:103], v[96:99]
	ds_read_b128 v[234:237], v118 offset:8832
	s_waitcnt lgkmcnt(6)
	v_mfma_f32_16x16x32_bf16 v[92:95], v[238:241], v[112:115], v[92:95]
	ds_read_b128 v[238:241], v118 offset:8896
	s_waitcnt lgkmcnt(6)
	v_mfma_f32_16x16x32_bf16 v[92:95], v[242:245], v[108:111], v[92:95]
	ds_read_b128 v[242:245], v118 offset:13056
	s_waitcnt lgkmcnt(6)
	v_mfma_f32_16x16x32_bf16 v[92:95], v[246:249], v[104:107], v[92:95]
	ds_read_b128 v[246:249], v118 offset:13120
	s_waitcnt lgkmcnt(6)
	v_mfma_f32_16x16x32_bf16 v[92:95], v[152:155], v[100:103], v[92:95]
	ds_read_b128 v[152:155], v118 offset:13184
	s_waitcnt lgkmcnt(6)
	v_mfma_f32_16x16x32_bf16 v[88:91], v[220:223], v[112:115], v[88:91]
	ds_read_b128 v[220:223], v118 offset:13248
	s_waitcnt lgkmcnt(6)
	v_mfma_f32_16x16x32_bf16 v[88:91], v[230:233], v[108:111], v[88:91]
	ds_read_b128 v[230:233], v118 offset:17408
	s_waitcnt lgkmcnt(6)
	v_mfma_f32_16x16x32_bf16 v[88:91], v[234:237], v[104:107], v[88:91]
	ds_read_b128 v[234:237], v118 offset:17472
	s_waitcnt lgkmcnt(6)
	v_mfma_f32_16x16x32_bf16 v[88:91], v[238:241], v[100:103], v[88:91]
	ds_read_b128 v[238:241], v118 offset:17536
	s_waitcnt lgkmcnt(6)
	v_mfma_f32_16x16x32_bf16 v[84:87], v[242:245], v[112:115], v[84:87]
	ds_read_b128 v[242:245], v118 offset:17600
	s_waitcnt lgkmcnt(6)
	v_mfma_f32_16x16x32_bf16 v[84:87], v[246:249], v[108:111], v[84:87]
	ds_read_b128 v[246:249], v118 offset:21760
	s_waitcnt lgkmcnt(6)
	v_mfma_f32_16x16x32_bf16 v[84:87], v[152:155], v[104:107], v[84:87]
	ds_read_b128 v[152:155], v118 offset:21824
	s_waitcnt lgkmcnt(6)
	v_mfma_f32_16x16x32_bf16 v[84:87], v[220:223], v[100:103], v[84:87]
	ds_read_b128 v[220:223], v118 offset:21888
	s_waitcnt lgkmcnt(6)
	v_mfma_f32_16x16x32_bf16 v[80:83], v[230:233], v[112:115], v[80:83]
	ds_read_b128 v[230:233], v118 offset:21952
	s_waitcnt lgkmcnt(6)
	v_mfma_f32_16x16x32_bf16 v[80:83], v[234:237], v[108:111], v[80:83]
	ds_read_b128 v[234:237], v118 offset:26112
	s_waitcnt lgkmcnt(6)
	v_mfma_f32_16x16x32_bf16 v[80:83], v[238:241], v[104:107], v[80:83]
	ds_read_b128 v[238:241], v118 offset:26176
	s_waitcnt lgkmcnt(6)
	v_mfma_f32_16x16x32_bf16 v[80:83], v[242:245], v[100:103], v[80:83]
	ds_read_b128 v[242:245], v118 offset:26240
	s_waitcnt lgkmcnt(6)
	v_mfma_f32_16x16x32_bf16 v[76:79], v[246:249], v[112:115], v[76:79]
	ds_read_b128 v[246:249], v118 offset:26304
	s_waitcnt lgkmcnt(6)
; __device__ __forceinline__ f32x4 mfma16(bf16x8 a, bf16x8 b, f32x4 c) { return __builtin_amdgcn_mfma_f32_16x16x32_bf16(a, b, c, 0, 0, 0); }
; __device__ void cross_items(const Params& p, LAS unsigned char* lds) {
;     ...
; #pragma unroll
;             for (int kt = 0; kt < 16; ++kt)
; #pragma unroll
;                 for (int ks = 0; ks < 4; ++ks) sc[kt] = mfma16(frag_row(buf, KV_STRIDE, 16 * kt, 32 * ks, idx, g), qf[ks], sc[kt]);
	v_mfma_f32_16x16x32_bf16 v[76:79], v[152:155], v[108:111], v[76:79]
	ds_read_b128 v[152:155], v118 offset:30464
	s_waitcnt lgkmcnt(6)
	v_mfma_f32_16x16x32_bf16 v[76:79], v[220:223], v[104:107], v[76:79]
	ds_read_b128 v[220:223], v118 offset:30528
	s_waitcnt lgkmcnt(6)
	v_mfma_f32_16x16x32_bf16 v[76:79], v[230:233], v[100:103], v[76:79]
	ds_read_b128 v[230:233], v118 offset:30592
	s_waitcnt lgkmcnt(6)
	v_mfma_f32_16x16x32_bf16 v[72:75], v[234:237], v[112:115], v[72:75]
	ds_read_b128 v[234:237], v118 offset:30656
	s_waitcnt lgkmcnt(6)
	v_mfma_f32_16x16x32_bf16 v[72:75], v[238:241], v[108:111], v[72:75]
	ds_read_b128 v[238:241], v118 offset:34816
	s_waitcnt lgkmcnt(6)
	v_mfma_f32_16x16x32_bf16 v[72:75], v[242:245], v[104:107], v[72:75]
	ds_read_b128 v[242:245], v118 offset:34880
	s_waitcnt lgkmcnt(6)
	v_mfma_f32_16x16x32_bf16 v[72:75], v[246:249], v[100:103], v[72:75]
	ds_read_b128 v[246:249], v118 offset:34944
	s_waitcnt lgkmcnt(6)
	v_mfma_f32_16x16x32_bf16 v[68:71], v[152:155], v[112:115], v[68:71]
	ds_read_b128 v[152:155], v118 offset:35008
	s_waitcnt lgkmcnt(6)
	v_mfma_f32_16x16x32_bf16 v[68:71], v[220:223], v[108:111], v[68:71]
	ds_read_b128 v[220:223], v118 offset:39168
	s_waitcnt lgkmcnt(6)
	v_mfma_f32_16x16x32_bf16 v[68:71], v[230:233], v[104:107], v[68:71]
	ds_read_b128 v[230:233], v118 offset:39232
	s_waitcnt lgkmcnt(6)
	v_mfma_f32_16x16x32_bf16 v[68:71], v[234:237], v[100:103], v[68:71]
	ds_read_b128 v[234:237], v118 offset:39296
	s_waitcnt lgkmcnt(6)
	v_mfma_f32_16x16x32_bf16 v[60:63], v[238:241], v[112:115], v[60:63]
	ds_read_b128 v[238:241], v118 offset:39360
	s_waitcnt lgkmcnt(6)
	v_mfma_f32_16x16x32_bf16 v[60:63], v[242:245], v[108:111], v[60:63]
	ds_read_b128 v[242:245], v118 offset:43520
	s_waitcnt lgkmcnt(6)
	v_mfma_f32_16x16x32_bf16 v[60:63], v[246:249], v[104:107], v[60:63]
	ds_read_b128 v[246:249], v118 offset:43584
	s_waitcnt lgkmcnt(6)
	v_mfma_f32_16x16x32_bf16 v[60:63], v[152:155], v[100:103], v[60:63]
	ds_read_b128 v[152:155], v118 offset:43648
	s_waitcnt lgkmcnt(6)
	v_mfma_f32_16x16x32_bf16 v[56:59], v[220:223], v[112:115], v[56:59]
	ds_read_b128 v[220:223], v118 offset:43712
	s_waitcnt lgkmcnt(6)
	v_mfma_f32_16x16x32_bf16 v[56:59], v[230:233], v[108:111], v[56:59]
	ds_read_b128 v[230:233], v118 offset:47872
	s_waitcnt lgkmcnt(6)
	v_mfma_f32_16x16x32_bf16 v[56:59], v[234:237], v[104:107], v[56:59]
	ds_read_b128 v[234:237], v118 offset:47936
	s_waitcnt lgkmcnt(6)
	v_mfma_f32_16x16x32_bf16 v[56:59], v[238:241], v[100:103], v[56:59]
	ds_read_b128 v[238:241], v118 offset:48000
	s_waitcnt lgkmcnt(6)
	v_mfma_f32_16x16x32_bf16 v[52:55], v[242:245], v[112:115], v[52:55]
	ds_read_b128 v[242:245], v118 offset:48064
	s_waitcnt lgkmcnt(6)
	v_mfma_f32_16x16x32_bf16 v[52:55], v[246:249], v[108:111], v[52:55]
	ds_read_b128 v[246:249], v118 offset:52224
	s_waitcnt lgkmcnt(6)
	v_mfma_f32_16x16x32_bf16 v[52:55], v[152:155], v[104:107], v[52:55]
	ds_read_b128 v[152:155], v118 offset:52288
	s_waitcnt lgkmcnt(6)
	v_mfma_f32_16x16x32_bf16 v[52:55], v[220:223], v[100:103], v[52:55]
	ds_read_b128 v[220:223], v118 offset:52352
	s_waitcnt lgkmcnt(6)
	v_mfma_f32_16x16x32_bf16 v[48:51], v[230:233], v[112:115], v[48:51]
	ds_read_b128 v[230:233], v118 offset:52416
	s_waitcnt lgkmcnt(6)
	v_mfma_f32_16x16x32_bf16 v[48:51], v[234:237], v[108:111], v[48:51]
	ds_read_b128 v[234:237], v118 offset:56576
	s_waitcnt lgkmcnt(6)
	v_mfma_f32_16x16x32_bf16 v[48:51], v[238:241], v[104:107], v[48:51]
	ds_read_b128 v[238:241], v118 offset:56640
	s_waitcnt lgkmcnt(6)
	v_mfma_f32_16x16x32_bf16 v[48:51], v[242:245], v[100:103], v[48:51]
	ds_read_b128 v[242:245], v118 offset:56704
	s_waitcnt lgkmcnt(6)
	v_mfma_f32_16x16x32_bf16 v[40:43], v[246:249], v[112:115], v[40:43]
	ds_read_b128 v[246:249], v118 offset:56768
	s_waitcnt lgkmcnt(6)
	v_mfma_f32_16x16x32_bf16 v[40:43], v[152:155], v[108:111], v[40:43]
	ds_read_b128 v[152:155], v118 offset:60928
	s_waitcnt lgkmcnt(6)
	v_mfma_f32_16x16x32_bf16 v[40:43], v[220:223], v[104:107], v[40:43]
	ds_read_b128 v[220:223], v118 offset:60992
	s_waitcnt lgkmcnt(6)
	v_mfma_f32_16x16x32_bf16 v[40:43], v[230:233], v[100:103], v[40:43]
	ds_read_b128 v[230:233], v118 offset:61056
	s_waitcnt lgkmcnt(6)
	v_mfma_f32_16x16x32_bf16 v[24:27], v[234:237], v[112:115], v[24:27]
	ds_read_b128 v[234:237], v118 offset:61120
	s_waitcnt lgkmcnt(6)
	v_mfma_f32_16x16x32_bf16 v[24:27], v[238:241], v[108:111], v[24:27]
	ds_read_b128 v[238:241], v118 offset:65280
	s_waitcnt lgkmcnt(6)
	v_mfma_f32_16x16x32_bf16 v[24:27], v[242:245], v[104:107], v[24:27]
	ds_read_b128 v[242:245], v118 offset:65344
	s_waitcnt lgkmcnt(6)
	v_mfma_f32_16x16x32_bf16 v[24:27], v[246:249], v[100:103], v[24:27]
	ds_read_b128 v[246:249], v118 offset:65408
	s_waitcnt lgkmcnt(6)
	v_mfma_f32_16x16x32_bf16 v[4:7], v[152:155], v[112:115], v[4:7]
	ds_read_b128 v[152:155], v118 offset:65472
	s_waitcnt lgkmcnt(6)
	v_mfma_f32_16x16x32_bf16 v[4:7], v[220:223], v[108:111], v[4:7]
	s_waitcnt lgkmcnt(5)
	v_mfma_f32_16x16x32_bf16 v[4:7], v[230:233], v[104:107], v[4:7]
	s_waitcnt lgkmcnt(4)
	v_mfma_f32_16x16x32_bf16 v[4:7], v[234:237], v[100:103], v[4:7]
	s_waitcnt lgkmcnt(3)
	v_mfma_f32_16x16x32_bf16 v[64:67], v[238:241], v[112:115], v[64:67]
	s_waitcnt lgkmcnt(2)
	v_mfma_f32_16x16x32_bf16 v[64:67], v[242:245], v[108:111], v[64:67]
	s_waitcnt lgkmcnt(1)
	v_mfma_f32_16x16x32_bf16 v[64:67], v[246:249], v[104:107], v[64:67]
	s_waitcnt lgkmcnt(0)
	v_mfma_f32_16x16x32_bf16 v[64:67], v[152:155], v[100:103], v[64:67]
	s_cbranch_scc1 .LBB0_393
; #define LAS __attribute__((address_space(3)))
; __device__ __forceinline__ f32x4 mfma16(bf16x8 a, bf16x8 b, f32x4 c) { return __builtin_amdgcn_mfma_f32_16x16x32_bf16(a, b, c, 0, 0, 0); }
; #define LDS_BARRIER() do { asm volatile("s_waitcnt lgkmcnt(0)" ::: "memory"); __builtin_amdgcn_s_barrier(); asm volatile("" ::: "memory"); } while (0)
; #define XLOAD(kvbase, c8) do { const bf16_t* _src = (kvbase) + (((c8) >= 4) ? 2048 : 0) + ((c8) & 3) * 128 + piece * 8; \
;         _Pragma("unroll") for (int _it = 0; _it < 8; ++_it) pre[_it] = *(const u32x4*)(_src + (size_t)(srow + 32 * _it) * 4096); } while (0)
; #define XSTORE(buf) do { _Pragma("unroll") for (int _it = 0; _it < 8; ++_it) *(LAS u32x4*)((buf) + (srow + 32 * _it) * KV_STRIDE + piece * 16) = pre[_it]; } while (0)
; __device__ void cross_items(const Params& p, LAS unsigned char* lds) {
;     ...
;         for (int c = 0; c < 4; ++c) {
;             LAS unsigned char* buf = lds + (c & 1) * KV_BUF;
;             XSTORE(buf);
;             bf16x8 qf[4];
; #pragma unroll
;             for (int ks = 0; ks < 4; ++ks) qf[ks] = *(const bf16x8*)(qrow + c * 128 + 32 * ks);
;             XLOAD(kvb, c + 1);
;             LDS_BARRIER();
; #pragma unroll
;             for (int kt = 0; kt < 16; ++kt)
; #pragma unroll
;                 for (int ks = 0; ks < 4; ++ks) sc[kt] = mfma16(frag_row(buf, KV_STRIDE, 16 * kt, 32 * ks, idx, g), qf[ks], sc[kt]);
	s_lshl_b32 s2, s6, 7
	s_and_b32 s2, s2, 0xf80
	s_add_i32 s7, s7, s2
	v_add_u32_e32 v100, s7, v1
	v_ashrrev_i32_e32 v101, 31, v100
	s_lshl_b32 s2, s6, 4
	v_lshlrev_b64 v[152:153], 11, v[100:101]
	v_lshlrev_b64 v[100:101], 12, v[100:101]
	s_and_b32 s2, s2, 0x600
	v_lshl_add_u64 v[100:101], s[92:93], 0, v[100:101]
	s_lshl_b32 s18, s2, 1
	v_lshl_add_u64 v[100:101], v[100:101], 0, s[18:19]
	v_mov_b32_e32 v147, v3
	v_lshl_add_u64 v[100:101], v[100:101], 0, v[146:147]
	s_waitcnt vmcnt(7)
	ds_write_b128 v139, v[8:11]
	s_waitcnt vmcnt(6)
	ds_write_b128 v139, v[12:15] offset:8704
	s_waitcnt vmcnt(5)
	ds_write_b128 v139, v[16:19] offset:17408
	s_waitcnt vmcnt(4)
	ds_write_b128 v139, v[20:23] offset:26112
	s_waitcnt vmcnt(3)
	ds_write_b128 v139, v[28:31] offset:34816
	s_waitcnt vmcnt(2)
	ds_write_b128 v139, v[32:35] offset:43520
	s_waitcnt vmcnt(1)
	ds_write_b128 v139, v[36:39] offset:52224
	s_waitcnt vmcnt(0)
	ds_write_b128 v139, v[44:47] offset:60928
	global_load_dwordx4 v[112:115], v[100:101], off offset:768
	global_load_dwordx4 v[108:111], v[100:101], off offset:832
	global_load_dwordx4 v[104:107], v[100:101], off offset:896
	s_nop 0
	global_load_dwordx4 v[100:103], v[100:101], off offset:960
	s_add_u32 s0, s30, s0
	s_addc_u32 s1, s31, s1
	s_add_u32 s0, s0, s18
	s_addc_u32 s1, s1, 0
	v_lshlrev_b32_e32 v154, 1, v136
	v_mov_b32_e32 v155, v3
	v_lshl_add_u64 v[8:9], s[0:1], 0, v[154:155]
	s_mov_b64 s[0:1], 0x1000
	v_lshl_add_u64 v[44:45], v[8:9], 0, s[0:1]
	v_lshl_add_u64 v[8:9], v[44:45], 0, v[120:121]
	v_lshl_add_u64 v[12:13], v[44:45], 0, v[122:123]
	v_lshl_add_u64 v[16:17], v[44:45], 0, v[124:125]
	v_lshl_add_u64 v[20:21], v[44:45], 0, v[126:127]
	v_lshl_add_u64 v[28:29], v[44:45], 0, v[128:129]
	v_lshl_add_u64 v[32:33], v[44:45], 0, v[130:131]
	v_lshl_add_u64 v[36:37], v[44:45], 0, v[132:133]
	v_lshl_add_u64 v[44:45], v[44:45], 0, v[134:135]
	global_load_dwordx4 v[8:11], v[8:9], off
	v_cmp_lt_i32_e32 vcc, v218, v216
	global_load_dwordx4 v[12:15], v[12:13], off
	s_mov_b32 s3, 0
	global_load_dwordx4 v[16:19], v[16:17], off
	s_nop 0
	global_load_dwordx4 v[20:23], v[20:21], off
	s_nop 0
	global_load_dwordx4 v[28:31], v[28:29], off
	s_nop 0
	global_load_dwordx4 v[32:35], v[32:33], off
	s_nop 0
	global_load_dwordx4 v[36:39], v[36:37], off
	s_nop 0
	global_load_dwordx4 v[44:47], v[44:45], off
	s_waitcnt lgkmcnt(0)
	s_barrier
	ds_read_b128 v[220:223], v167
	ds_read_b128 v[230:233], v167 offset:64
	ds_read_b128 v[234:237], v167 offset:128
	ds_read_b128 v[238:241], v167 offset:192
	ds_read_b128 v[242:245], v167 offset:4352
	ds_read_b128 v[246:249], v167 offset:4416
	s_waitcnt vmcnt(11) lgkmcnt(5)
	v_mfma_f32_16x16x32_bf16 v[96:99], v[220:223], v[112:115], v[96:99]
	ds_read_b128 v[220:223], v167 offset:4480
	s_waitcnt vmcnt(10) lgkmcnt(5)
	v_mfma_f32_16x16x32_bf16 v[96:99], v[230:233], v[108:111], v[96:99]
	ds_read_b128 v[230:233], v167 offset:4544
	s_waitcnt vmcnt(9) lgkmcnt(5)
	v_mfma_f32_16x16x32_bf16 v[96:99], v[234:237], v[104:107], v[96:99]
	ds_read_b128 v[234:237], v167 offset:8704
	s_waitcnt vmcnt(8) lgkmcnt(5)
	v_mfma_f32_16x16x32_bf16 v[96:99], v[238:241], v[100:103], v[96:99]
	ds_read_b128 v[238:241], v167 offset:8768
	s_waitcnt lgkmcnt(5)
	v_mfma_f32_16x16x32_bf16 v[92:95], v[242:245], v[112:115], v[92:95]
	ds_read_b128 v[242:245], v167 offset:8832
	s_waitcnt lgkmcnt(5)
	v_mfma_f32_16x16x32_bf16 v[92:95], v[246:249], v[108:111], v[92:95]
	ds_read_b128 v[246:249], v167 offset:8896
	s_waitcnt lgkmcnt(5)
	v_mfma_f32_16x16x32_bf16 v[92:95], v[220:223], v[104:107], v[92:95]
	ds_read_b128 v[220:223], v167 offset:13056
	s_waitcnt lgkmcnt(5)
	v_mfma_f32_16x16x32_bf16 v[92:95], v[230:233], v[100:103], v[92:95]
	ds_read_b128 v[230:233], v167 offset:13120
	s_waitcnt lgkmcnt(5)
	v_mfma_f32_16x16x32_bf16 v[88:91], v[234:237], v[112:115], v[88:91]
	ds_read_b128 v[234:237], v167 offset:13184
	s_waitcnt lgkmcnt(5)
	v_mfma_f32_16x16x32_bf16 v[88:91], v[238:241], v[108:111], v[88:91]
	ds_read_b128 v[238:241], v167 offset:13248
	s_waitcnt lgkmcnt(5)
	v_mfma_f32_16x16x32_bf16 v[88:91], v[242:245], v[104:107], v[88:91]
	ds_read_b128 v[242:245], v167 offset:17408
	s_waitcnt lgkmcnt(5)
	v_mfma_f32_16x16x32_bf16 v[88:91], v[246:249], v[100:103], v[88:91]
	ds_read_b128 v[246:249], v167 offset:17472
	s_waitcnt lgkmcnt(5)
	v_mfma_f32_16x16x32_bf16 v[84:87], v[220:223], v[112:115], v[84:87]
	ds_read_b128 v[220:223], v167 offset:17536
	s_waitcnt lgkmcnt(5)
	v_mfma_f32_16x16x32_bf16 v[84:87], v[230:233], v[108:111], v[84:87]
	ds_read_b128 v[230:233], v167 offset:17600
	s_waitcnt lgkmcnt(5)
	v_mfma_f32_16x16x32_bf16 v[84:87], v[234:237], v[104:107], v[84:87]
	ds_read_b128 v[234:237], v167 offset:21760
	s_waitcnt lgkmcnt(5)
	v_mfma_f32_16x16x32_bf16 v[84:87], v[238:241], v[100:103], v[84:87]
	ds_read_b128 v[238:241], v167 offset:21824
	s_waitcnt lgkmcnt(5)
	v_mfma_f32_16x16x32_bf16 v[80:83], v[242:245], v[112:115], v[80:83]
	ds_read_b128 v[242:245], v167 offset:21888
	s_waitcnt lgkmcnt(5)
	v_mfma_f32_16x16x32_bf16 v[80:83], v[246:249], v[108:111], v[80:83]
	ds_read_b128 v[246:249], v167 offset:21952
	s_waitcnt lgkmcnt(5)
	v_mfma_f32_16x16x32_bf16 v[80:83], v[220:223], v[104:107], v[80:83]
	ds_read_b128 v[220:223], v167 offset:26112
	s_waitcnt lgkmcnt(5)
	v_mfma_f32_16x16x32_bf16 v[80:83], v[230:233], v[100:103], v[80:83]
	ds_read_b128 v[230:233], v167 offset:26176
	s_waitcnt lgkmcnt(5)
	v_mfma_f32_16x16x32_bf16 v[76:79], v[234:237], v[112:115], v[76:79]
	ds_read_b128 v[234:237], v167 offset:26240
	s_waitcnt lgkmcnt(5)
	v_mfma_f32_16x16x32_bf16 v[76:79], v[238:241], v[108:111], v[76:79]
	ds_read_b128 v[238:241], v167 offset:26304
	s_waitcnt lgkmcnt(5)
; __device__ __forceinline__ f32x4 mfma16(bf16x8 a, bf16x8 b, f32x4 c) { return __builtin_amdgcn_mfma_f32_16x16x32_bf16(a, b, c, 0, 0, 0); }
; __device__ void cross_items(const Params& p, LAS unsigned char* lds) {
;     ...
; #pragma unroll
;             for (int kt = 0; kt < 16; ++kt)
; #pragma unroll
;                 for (int ks = 0; ks < 4; ++ks) sc[kt] = mfma16(frag_row(buf, KV_STRIDE, 16 * kt, 32 * ks, idx, g), qf[ks], sc[kt]);
	v_mfma_f32_16x16x32_bf16 v[76:79], v[242:245], v[104:107], v[76:79]
	ds_read_b128 v[242:245], v167 offset:30464
	s_waitcnt lgkmcnt(5)
	v_mfma_f32_16x16x32_bf16 v[76:79], v[246:249], v[100:103], v[76:79]
	ds_read_b128 v[246:249], v167 offset:30528
	s_waitcnt lgkmcnt(5)
	v_mfma_f32_16x16x32_bf16 v[72:75], v[220:223], v[112:115], v[72:75]
	ds_read_b128 v[220:223], v167 offset:30592
	s_waitcnt lgkmcnt(5)
	v_mfma_f32_16x16x32_bf16 v[72:75], v[230:233], v[108:111], v[72:75]
	ds_read_b128 v[230:233], v167 offset:30656
	s_waitcnt lgkmcnt(5)
	v_mfma_f32_16x16x32_bf16 v[72:75], v[234:237], v[104:107], v[72:75]
	ds_read_b128 v[234:237], v167 offset:34816
	s_waitcnt lgkmcnt(5)
	v_mfma_f32_16x16x32_bf16 v[72:75], v[238:241], v[100:103], v[72:75]
	ds_read_b128 v[238:241], v167 offset:34880
	s_waitcnt lgkmcnt(5)
	v_mfma_f32_16x16x32_bf16 v[68:71], v[242:245], v[112:115], v[68:71]
	ds_read_b128 v[242:245], v167 offset:34944
	s_waitcnt lgkmcnt(5)
	v_mfma_f32_16x16x32_bf16 v[68:71], v[246:249], v[108:111], v[68:71]
	ds_read_b128 v[246:249], v167 offset:35008
	s_waitcnt lgkmcnt(5)
	v_mfma_f32_16x16x32_bf16 v[68:71], v[220:223], v[104:107], v[68:71]
	ds_read_b128 v[220:223], v167 offset:39168
	s_waitcnt lgkmcnt(5)
	v_mfma_f32_16x16x32_bf16 v[116:119], v[230:233], v[100:103], v[68:71]
	ds_read_b128 v[230:233], v167 offset:39232
	s_waitcnt lgkmcnt(5)
	v_mfma_f32_16x16x32_bf16 v[60:63], v[234:237], v[112:115], v[60:63]
	ds_read_b128 v[234:237], v167 offset:39296
	s_waitcnt lgkmcnt(5)
	v_mfma_f32_16x16x32_bf16 v[60:63], v[238:241], v[108:111], v[60:63]
	ds_read_b128 v[238:241], v167 offset:39360
	s_waitcnt lgkmcnt(5)
	v_mfma_f32_16x16x32_bf16 v[60:63], v[242:245], v[104:107], v[60:63]
	ds_read_b128 v[242:245], v167 offset:43520
	s_waitcnt lgkmcnt(5)
	v_mfma_f32_16x16x32_bf16 v[68:71], v[246:249], v[100:103], v[60:63]
	ds_read_b128 v[246:249], v167 offset:43584
	s_waitcnt lgkmcnt(5)
	v_mfma_f32_16x16x32_bf16 v[56:59], v[220:223], v[112:115], v[56:59]
	ds_read_b128 v[220:223], v167 offset:43648
	s_waitcnt lgkmcnt(5)
	v_mfma_f32_16x16x32_bf16 v[56:59], v[230:233], v[108:111], v[56:59]
	ds_read_b128 v[230:233], v167 offset:43712
	s_waitcnt lgkmcnt(5)
	v_mfma_f32_16x16x32_bf16 v[56:59], v[234:237], v[104:107], v[56:59]
	ds_read_b128 v[234:237], v167 offset:47872
	s_waitcnt lgkmcnt(5)
	v_mfma_f32_16x16x32_bf16 v[60:63], v[238:241], v[100:103], v[56:59]
	ds_read_b128 v[238:241], v167 offset:47936
	s_waitcnt lgkmcnt(5)
	v_mfma_f32_16x16x32_bf16 v[52:55], v[242:245], v[112:115], v[52:55]
	ds_read_b128 v[242:245], v167 offset:48000
	s_waitcnt lgkmcnt(5)
	v_mfma_f32_16x16x32_bf16 v[52:55], v[246:249], v[108:111], v[52:55]
	ds_read_b128 v[246:249], v167 offset:48064
	s_waitcnt lgkmcnt(5)
	v_mfma_f32_16x16x32_bf16 v[52:55], v[220:223], v[104:107], v[52:55]
	ds_read_b128 v[220:223], v167 offset:52224
	s_waitcnt lgkmcnt(5)
	v_mfma_f32_16x16x32_bf16 v[56:59], v[230:233], v[100:103], v[52:55]
	ds_read_b128 v[230:233], v167 offset:52288
	s_waitcnt lgkmcnt(5)
	v_mfma_f32_16x16x32_bf16 v[48:51], v[234:237], v[112:115], v[48:51]
	ds_read_b128 v[234:237], v167 offset:52352
	s_waitcnt lgkmcnt(5)
	v_mfma_f32_16x16x32_bf16 v[48:51], v[238:241], v[108:111], v[48:51]
	ds_read_b128 v[238:241], v167 offset:52416
	s_waitcnt lgkmcnt(5)
	v_mfma_f32_16x16x32_bf16 v[48:51], v[242:245], v[104:107], v[48:51]
	ds_read_b128 v[242:245], v167 offset:56576
	s_waitcnt lgkmcnt(5)
	v_mfma_f32_16x16x32_bf16 v[52:55], v[246:249], v[100:103], v[48:51]
	ds_read_b128 v[246:249], v167 offset:56640
	s_waitcnt lgkmcnt(5)
	v_mfma_f32_16x16x32_bf16 v[40:43], v[220:223], v[112:115], v[40:43]
	ds_read_b128 v[220:223], v167 offset:56704
	s_waitcnt lgkmcnt(5)
	v_mfma_f32_16x16x32_bf16 v[40:43], v[230:233], v[108:111], v[40:43]
	ds_read_b128 v[230:233], v167 offset:56768
	s_waitcnt lgkmcnt(5)
	v_mfma_f32_16x16x32_bf16 v[40:43], v[234:237], v[104:107], v[40:43]
	ds_read_b128 v[234:237], v167 offset:60928
	s_waitcnt lgkmcnt(5)
	v_mfma_f32_16x16x32_bf16 v[48:51], v[238:241], v[100:103], v[40:43]
	ds_read_b128 v[238:241], v167 offset:60992
	s_waitcnt lgkmcnt(5)
	v_mfma_f32_16x16x32_bf16 v[24:27], v[242:245], v[112:115], v[24:27]
	ds_read_b128 v[242:245], v167 offset:61056
	s_waitcnt lgkmcnt(5)
	v_mfma_f32_16x16x32_bf16 v[24:27], v[246:249], v[108:111], v[24:27]
	ds_read_b128 v[246:249], v167 offset:61120
	s_waitcnt lgkmcnt(5)
	v_mfma_f32_16x16x32_bf16 v[24:27], v[220:223], v[104:107], v[24:27]
	ds_read_b128 v[220:223], v167 offset:65280
	s_waitcnt lgkmcnt(5)
	v_mfma_f32_16x16x32_bf16 v[40:43], v[230:233], v[100:103], v[24:27]
	ds_read_b128 v[230:233], v167 offset:65344
	s_waitcnt lgkmcnt(5)
	v_mfma_f32_16x16x32_bf16 v[4:7], v[234:237], v[112:115], v[4:7]
	ds_read_b128 v[234:237], v167 offset:65408
	s_waitcnt lgkmcnt(5)
	v_mfma_f32_16x16x32_bf16 v[4:7], v[238:241], v[108:111], v[4:7]
	ds_read_b128 v[238:241], v167 offset:65472
	s_waitcnt lgkmcnt(5)
	v_mfma_f32_16x16x32_bf16 v[4:7], v[242:245], v[104:107], v[4:7]
	s_waitcnt lgkmcnt(4)
	v_mfma_f32_16x16x32_bf16 v[24:27], v[246:249], v[100:103], v[4:7]
	s_waitcnt lgkmcnt(3)
	v_mfma_f32_16x16x32_bf16 v[4:7], v[220:223], v[112:115], v[64:67]
	s_waitcnt lgkmcnt(2)
	v_mfma_f32_16x16x32_bf16 v[4:7], v[230:233], v[108:111], v[4:7]
	s_waitcnt lgkmcnt(1)
	v_mfma_f32_16x16x32_bf16 v[4:7], v[234:237], v[104:107], v[4:7]
	s_waitcnt lgkmcnt(0)
; __device__ __forceinline__ float fexp2(float x) { return __builtin_amdgcn_exp2f(x); }
; __device__ __forceinline__ f32x4 mfma16(bf16x8 a, bf16x8 b, f32x4 c) { return __builtin_amdgcn_mfma_f32_16x16x32_bf16(a, b, c, 0, 0, 0); }
; __device__ void cross_items(const Params& p, LAS unsigned char* lds) {
;     ...
; #pragma unroll
;             for (int kt = 0; kt < 16; ++kt)
; #pragma unroll
;                 for (int ks = 0; ks < 4; ++ks) sc[kt] = mfma16(frag_row(buf, KV_STRIDE, 16 * kt, 32 * ks, idx, g), qf[ks], sc[kt]);
;         }
;         const float scl = 0.04419417382415922f * LOG2E;
;         float mx = -1e30f;
; #pragma unroll
;         for (int kt = 0; kt < 16; ++kt)
; #pragma unroll
;             for (int rr = 0; rr < 4; ++rr) { const float sv = sc[kt][rr] * scl; sc[kt][rr] = sv; mx = fmaxf(mx, sv); }
;         mx = fmaxf(mx, __shfl_xor(mx, 16)); mx = fmaxf(mx, __shfl_xor(mx, 32));
;         float sum = 0.f;
; #pragma unroll
;         for (int kt = 0; kt < 16; ++kt)
; #pragma unroll
;             for (int rr = 0; rr < 4; ++rr) { const float e = fexp2(sc[kt][rr] - mx); sc[kt][rr] = e; sum += e; }
;         sum += __shfl_xor(sum, 16); sum += __shfl_xor(sum, 32);
	v_mfma_f32_16x16x32_bf16 v[4:7], v[238:241], v[100:103], v[4:7]
	v_mul_f32_e32 v64, 0x3d8293ee, v96
	v_mul_f32_e32 v65, 0x3d8293ee, v97
	v_max3_f32 v64, v64, s49, v65
	v_mul_f32_e32 v65, 0x3d8293ee, v98
	v_mul_f32_e32 v66, 0x3d8293ee, v99
	v_max3_f32 v64, v64, v65, v66
	v_mul_f32_e32 v65, 0x3d8293ee, v92
	v_mul_f32_e32 v66, 0x3d8293ee, v93
	v_max3_f32 v64, v64, v65, v66
	v_mul_f32_e32 v65, 0x3d8293ee, v94
	v_mul_f32_e32 v66, 0x3d8293ee, v95
	v_max3_f32 v64, v64, v65, v66
	v_mul_f32_e32 v65, 0x3d8293ee, v88
	v_mul_f32_e32 v66, 0x3d8293ee, v89
	v_max3_f32 v64, v64, v65, v66
	v_mul_f32_e32 v65, 0x3d8293ee, v90
	v_mul_f32_e32 v66, 0x3d8293ee, v91
	v_max3_f32 v64, v64, v65, v66
	v_mul_f32_e32 v65, 0x3d8293ee, v84
	v_mul_f32_e32 v66, 0x3d8293ee, v85
	v_max3_f32 v64, v64, v65, v66
	v_mul_f32_e32 v65, 0x3d8293ee, v86
	v_mul_f32_e32 v66, 0x3d8293ee, v87
	v_max3_f32 v64, v64, v65, v66
	v_mul_f32_e32 v65, 0x3d8293ee, v80
	v_mul_f32_e32 v66, 0x3d8293ee, v81
	v_max3_f32 v64, v64, v65, v66
	v_mul_f32_e32 v65, 0x3d8293ee, v82
	v_mul_f32_e32 v66, 0x3d8293ee, v83
	v_max3_f32 v64, v64, v65, v66
	v_mul_f32_e32 v65, 0x3d8293ee, v76
	v_mul_f32_e32 v66, 0x3d8293ee, v77
	v_max3_f32 v64, v64, v65, v66
	v_mul_f32_e32 v65, 0x3d8293ee, v78
	v_mul_f32_e32 v66, 0x3d8293ee, v79
	v_max3_f32 v64, v64, v65, v66
	v_mul_f32_e32 v65, 0x3d8293ee, v72
	v_mul_f32_e32 v66, 0x3d8293ee, v73
	v_max3_f32 v64, v64, v65, v66
	v_mul_f32_e32 v65, 0x3d8293ee, v74
	v_mul_f32_e32 v66, 0x3d8293ee, v75
	v_max3_f32 v64, v64, v65, v66
	v_mul_f32_e32 v65, 0x3d8293ee, v116
	v_mul_f32_e32 v66, 0x3d8293ee, v117
	v_max3_f32 v64, v64, v65, v66
	v_mul_f32_e32 v65, 0x3d8293ee, v118
	v_mul_f32_e32 v66, 0x3d8293ee, v119
	v_max3_f32 v64, v64, v65, v66
	v_mul_f32_e32 v65, 0x3d8293ee, v68
	v_mul_f32_e32 v66, 0x3d8293ee, v69
	v_max3_f32 v64, v64, v65, v66
	v_mul_f32_e32 v65, 0x3d8293ee, v70
	v_mul_f32_e32 v66, 0x3d8293ee, v71
	v_max3_f32 v64, v64, v65, v66
	v_mul_f32_e32 v65, 0x3d8293ee, v60
	v_mul_f32_e32 v66, 0x3d8293ee, v61
	v_max3_f32 v64, v64, v65, v66
	v_mul_f32_e32 v65, 0x3d8293ee, v62
	v_mul_f32_e32 v66, 0x3d8293ee, v63
	v_max3_f32 v64, v64, v65, v66
	v_mul_f32_e32 v65, 0x3d8293ee, v56
	v_mul_f32_e32 v66, 0x3d8293ee, v57
	v_max3_f32 v64, v64, v65, v66
	v_mul_f32_e32 v65, 0x3d8293ee, v58
	v_mul_f32_e32 v66, 0x3d8293ee, v59
	v_max3_f32 v64, v64, v65, v66
	v_mul_f32_e32 v65, 0x3d8293ee, v52
	v_mul_f32_e32 v66, 0x3d8293ee, v53
	v_max3_f32 v64, v64, v65, v66
	v_mul_f32_e32 v65, 0x3d8293ee, v54
	v_mul_f32_e32 v66, 0x3d8293ee, v55
	v_max3_f32 v64, v64, v65, v66
	v_mul_f32_e32 v65, 0x3d8293ee, v48
	v_mul_f32_e32 v66, 0x3d8293ee, v49
	v_max3_f32 v64, v64, v65, v66
	v_mul_f32_e32 v65, 0x3d8293ee, v50
	v_mul_f32_e32 v66, 0x3d8293ee, v51
	v_max3_f32 v64, v64, v65, v66
	v_mul_f32_e32 v65, 0x3d8293ee, v40
	v_mul_f32_e32 v66, 0x3d8293ee, v41
	v_max3_f32 v64, v64, v65, v66
	v_mul_f32_e32 v65, 0x3d8293ee, v42
	v_mul_f32_e32 v66, 0x3d8293ee, v43
	v_max3_f32 v64, v64, v65, v66
	v_mul_f32_e32 v65, 0x3d8293ee, v24
	v_mul_f32_e32 v66, 0x3d8293ee, v25
	v_max3_f32 v64, v64, v65, v66
	v_mul_f32_e32 v65, 0x3d8293ee, v26
	v_mul_f32_e32 v66, 0x3d8293ee, v27
	v_max3_f32 v64, v64, v65, v66
	v_mul_f32_e32 v65, 0x3d8293ee, v4
	v_mul_f32_e32 v66, 0x3d8293ee, v5
	v_max3_f32 v64, v64, v65, v66
	v_mul_f32_e32 v65, 0x3d8293ee, v6
	v_mul_f32_e32 v66, 0x3d8293ee, v7
	v_max3_f32 v64, v64, v65, v66
	v_cndmask_b32_e32 v65, v215, v218, vcc
	v_lshlrev_b32_e32 v65, 2, v65
	ds_bpermute_b32 v66, v65, v64
	v_cmp_lt_i32_e32 vcc, v217, v216
	s_waitcnt lgkmcnt(0)
	v_max_f32_e32 v66, v66, v66
	v_max_f32_e32 v64, v64, v66
	v_cndmask_b32_e32 v66, v215, v217, vcc
	v_lshlrev_b32_e32 v66, 2, v66
	ds_bpermute_b32 v67, v66, v64
	s_waitcnt lgkmcnt(0)
	v_max_f32_e32 v67, v67, v67
	v_max_f32_e32 v100, v64, v67
	v_fma_f32 v64, v96, s52, -v100
	v_exp_f32_e32 v64, v64
	v_fma_f32 v67, v97, s52, -v100
	v_exp_f32_e32 v67, v67
	v_fma_f32 v92, v92, s52, -v100
	v_add_f32_e32 v96, 0, v64
	v_exp_f32_e32 v92, v92
	v_add_f32_e32 v97, v67, v96
	v_fma_f32 v96, v98, s52, -v100
	v_exp_f32_e32 v96, v96
	v_fma_f32 v93, v93, s52, -v100
	v_exp_f32_e32 v93, v93
	v_fma_f32 v94, v94, s52, -v100
	v_add_f32_e32 v98, v96, v97
	v_fma_f32 v97, v99, s52, -v100
	v_exp_f32_e32 v97, v97
	v_exp_f32_e32 v94, v94
	v_fma_f32 v95, v95, s52, -v100
	v_exp_f32_e32 v95, v95
	v_add_f32_e32 v98, v97, v98
	v_fma_f32 v88, v88, s52, -v100
	v_add_f32_e32 v98, v92, v98
	v_exp_f32_e32 v88, v88
	v_fma_f32 v89, v89, s52, -v100
	v_add_f32_e32 v98, v93, v98
	v_exp_f32_e32 v89, v89
	v_fma_f32 v90, v90, s52, -v100
	v_add_f32_e32 v98, v94, v98
	v_exp_f32_e32 v90, v90
	v_fma_f32 v91, v91, s52, -v100
	v_add_f32_e32 v98, v95, v98
	v_exp_f32_e32 v91, v91
	v_fma_f32 v84, v84, s52, -v100
	v_add_f32_e32 v98, v88, v98
	v_exp_f32_e32 v84, v84
	v_fma_f32 v85, v85, s52, -v100
	v_add_f32_e32 v98, v89, v98
	v_exp_f32_e32 v85, v85
	v_fma_f32 v86, v86, s52, -v100
	v_add_f32_e32 v98, v90, v98
	v_exp_f32_e32 v86, v86
	v_fma_f32 v87, v87, s52, -v100
	v_add_f32_e32 v98, v91, v98
	v_exp_f32_e32 v87, v87
	v_fma_f32 v80, v80, s52, -v100
	v_add_f32_e32 v98, v84, v98
	v_exp_f32_e32 v80, v80
	v_fma_f32 v81, v81, s52, -v100
	v_add_f32_e32 v98, v85, v98
	v_exp_f32_e32 v81, v81
	v_fma_f32 v82, v82, s52, -v100
	v_add_f32_e32 v98, v86, v98
	v_exp_f32_e32 v82, v82
	v_fma_f32 v83, v83, s52, -v100
	v_add_f32_e32 v98, v87, v98
	v_exp_f32_e32 v83, v83
	v_fma_f32 v76, v76, s52, -v100
	v_add_f32_e32 v98, v80, v98
	v_exp_f32_e32 v76, v76
	v_fma_f32 v77, v77, s52, -v100
	v_add_f32_e32 v98, v81, v98
	v_exp_f32_e32 v77, v77
	v_fma_f32 v78, v78, s52, -v100
	v_add_f32_e32 v98, v82, v98
	v_exp_f32_e32 v78, v78
	v_fma_f32 v79, v79, s52, -v100
; __device__ __forceinline__ unsigned cvt_pk_bf16(float lo, float hi) { const f32x2v v = {lo, hi}; const b16x2v r = __builtin_convertvector(v, b16x2v); return __builtin_bit_cast(unsigned, r); }
; __device__ __forceinline__ float fexp2(float x) { return __builtin_amdgcn_exp2f(x); }
; __device__ void cross_items(const Params& p, LAS unsigned char* lds) {
;     ...
;         float sum = 0.f;
; #pragma unroll
;         for (int kt = 0; kt < 16; ++kt)
; #pragma unroll
;             for (int rr = 0; rr < 4; ++rr) { const float e = fexp2(sc[kt][rr] - mx); sc[kt][rr] = e; sum += e; }
;         sum += __shfl_xor(sum, 16); sum += __shfl_xor(sum, 32);
;         const float inv = 1.0f / sum;
;         bf16x8 pf[8];
; #pragma unroll
;         for (int sx = 0; sx < 8; ++sx) { u32x4 pw; pw.x = cvt_pk_bf16(sc[2 * sx][0], sc[2 * sx][1]); pw.y = cvt_pk_bf16(sc[2 * sx][2], sc[2 * sx][3]); pw.z = cvt_pk_bf16(sc[2 * sx + 1][0], sc[2 * sx + 1][1]); pw.w = cvt_pk_bf16(sc[2 * sx + 1][2], sc[2 * sx + 1][3]);
;             pf[sx] = __builtin_bit_cast(bf16x8, pw); }
;         const int nitem = (item + 1 < item0 + 2) ? item + 1 : 512;
;         const bf16_t* nkvb = (const bf16_t*)(ws + OFF_MKV) + (size_t)(((nitem < 512 ? nitem : item) >> 7) * 256) * 4096 + (((nitem < 512 ? nitem : item) >> 5) & 3) * 512;
	v_add_f32_e32 v98, v83, v98
	v_exp_f32_e32 v79, v79
	v_fma_f32 v72, v72, s52, -v100
	v_add_f32_e32 v98, v76, v98
	v_exp_f32_e32 v72, v72
	v_fma_f32 v73, v73, s52, -v100
	v_add_f32_e32 v98, v77, v98
	v_exp_f32_e32 v73, v73
	v_fma_f32 v74, v74, s52, -v100
	v_add_f32_e32 v98, v78, v98
	v_exp_f32_e32 v74, v74
	v_fma_f32 v75, v75, s52, -v100
	v_add_f32_e32 v98, v79, v98
	v_exp_f32_e32 v75, v75
	v_fma_f32 v99, v116, s52, -v100
	v_add_f32_e32 v98, v72, v98
	v_exp_f32_e32 v99, v99
	v_fma_f32 v101, v117, s52, -v100
	v_add_f32_e32 v98, v73, v98
	v_exp_f32_e32 v101, v101
	v_fma_f32 v102, v118, s52, -v100
	v_add_f32_e32 v98, v74, v98
	v_exp_f32_e32 v102, v102
	v_fma_f32 v103, v119, s52, -v100
	v_add_f32_e32 v98, v75, v98
	v_exp_f32_e32 v103, v103
	v_fma_f32 v68, v68, s52, -v100
	v_add_f32_e32 v98, v99, v98
	v_exp_f32_e32 v68, v68
	v_fma_f32 v69, v69, s52, -v100
	v_add_f32_e32 v98, v101, v98
	v_exp_f32_e32 v69, v69
	v_fma_f32 v70, v70, s52, -v100
	v_add_f32_e32 v98, v102, v98
	v_exp_f32_e32 v70, v70
	v_fma_f32 v71, v71, s52, -v100
	v_add_f32_e32 v98, v103, v98
	v_exp_f32_e32 v71, v71
	v_fma_f32 v60, v60, s52, -v100
	v_add_f32_e32 v98, v68, v98
	v_exp_f32_e32 v104, v60
	v_add_f32_e32 v98, v69, v98
	v_add_f32_e32 v98, v70, v98
	v_add_f32_e32 v98, v71, v98
	v_fma_f32 v61, v61, s52, -v100
	v_add_f32_e32 v60, v104, v98
	v_exp_f32_e32 v98, v61
	v_fma_f32 v61, v62, s52, -v100
	v_exp_f32_e32 v105, v61
	v_fma_f32 v61, v63, s52, -v100
	v_exp_f32_e32 v106, v61
	v_fma_f32 v56, v56, s52, -v100
	v_exp_f32_e32 v107, v56
	v_fma_f32 v57, v57, s52, -v100
	v_add_f32_e32 v60, v98, v60
	v_exp_f32_e32 v108, v57
	v_fma_f32 v57, v58, s52, -v100
	v_add_f32_e32 v60, v105, v60
	v_exp_f32_e32 v109, v57
	v_fma_f32 v57, v59, s52, -v100
	v_add_f32_e32 v60, v106, v60
	v_exp_f32_e32 v110, v57
	v_fma_f32 v52, v52, s52, -v100
	v_add_f32_e32 v56, v107, v60
	v_exp_f32_e32 v111, v52
	v_fma_f32 v53, v53, s52, -v100
	v_add_f32_e32 v56, v108, v56
	v_exp_f32_e32 v112, v53
	v_fma_f32 v53, v54, s52, -v100
	v_add_f32_e32 v56, v109, v56
	v_exp_f32_e32 v113, v53
	v_fma_f32 v53, v55, s52, -v100
	v_add_f32_e32 v56, v110, v56
	v_exp_f32_e32 v114, v53
	v_fma_f32 v48, v48, s52, -v100
	v_add_f32_e32 v52, v111, v56
	v_exp_f32_e32 v115, v48
	v_fma_f32 v49, v49, s52, -v100
	v_add_f32_e32 v52, v112, v52
	v_exp_f32_e32 v116, v49
	v_fma_f32 v49, v50, s52, -v100
	v_add_f32_e32 v52, v113, v52
	v_exp_f32_e32 v117, v49
	v_fma_f32 v49, v51, s52, -v100
	v_add_f32_e32 v52, v114, v52
	v_exp_f32_e32 v118, v49
	v_fma_f32 v40, v40, s52, -v100
	v_add_f32_e32 v48, v115, v52
	v_exp_f32_e32 v119, v40
	v_fma_f32 v41, v41, s52, -v100
	v_add_f32_e32 v48, v116, v48
	v_exp_f32_e32 v147, v41
	v_fma_f32 v41, v42, s52, -v100
	v_add_f32_e32 v48, v117, v48
	v_exp_f32_e32 v155, v41
	v_fma_f32 v41, v43, s52, -v100
	v_add_f32_e32 v48, v118, v48
	v_exp_f32_e32 v201, v41
	v_fma_f32 v24, v24, s52, -v100
	v_add_f32_e32 v40, v119, v48
	v_exp_f32_e32 v202, v24
	v_fma_f32 v25, v25, s52, -v100
	v_add_f32_e32 v40, v147, v40
	v_exp_f32_e32 v203, v25
	v_fma_f32 v25, v26, s52, -v100
	v_add_f32_e32 v40, v155, v40
	v_exp_f32_e32 v204, v25
	v_fma_f32 v25, v27, s52, -v100
	v_add_f32_e32 v40, v201, v40
	v_exp_f32_e32 v205, v25
	v_fma_f32 v4, v4, s52, -v100
	v_add_f32_e32 v24, v202, v40
	v_exp_f32_e32 v206, v4
	v_fma_f32 v5, v5, s52, -v100
	v_add_f32_e32 v24, v203, v24
	v_exp_f32_e32 v207, v5
	v_fma_f32 v5, v6, s52, -v100
	v_add_f32_e32 v24, v204, v24
	v_exp_f32_e32 v208, v5
	v_fma_f32 v5, v7, s52, -v100
	v_add_f32_e32 v24, v205, v24
	v_exp_f32_e32 v7, v5
	v_add_f32_e32 v4, v206, v24
	v_add_f32_e32 v4, v207, v4
	v_add_f32_e32 v4, v208, v4
	v_add_f32_e32 v4, v7, v4
	ds_bpermute_b32 v5, v65, v4
	v_cvt_pk_bf16_f32 v48, v68, v69
	v_cvt_pk_bf16_f32 v49, v70, v71
	v_cvt_pk_bf16_f32 v52, v72, v73
	v_cvt_pk_bf16_f32 v64, v64, v67
	s_waitcnt lgkmcnt(0)
	v_add_f32_e32 v4, v4, v5
	ds_bpermute_b32 v5, v66, v4
	v_cvt_pk_bf16_f32 v65, v96, v97
	v_cvt_pk_bf16_f32 v66, v92, v93
	v_cvt_pk_bf16_f32 v67, v94, v95
	v_cvt_pk_bf16_f32 v60, v88, v89
	s_waitcnt lgkmcnt(0)
	v_add_f32_e32 v100, v4, v5
	v_div_scale_f32 v68, s[0:1], v100, v100, 1.0
	v_rcp_f32_e32 v69, v68
	v_cvt_pk_bf16_f32 v61, v90, v91
	v_cvt_pk_bf16_f32 v62, v84, v85
	v_cvt_pk_bf16_f32 v63, v86, v87
	v_fma_f32 v70, -v68, v69, 1.0
	v_fmac_f32_e32 v69, v70, v69
	v_div_scale_f32 v70, vcc, 1.0, v100, 1.0
	v_mul_f32_e32 v71, v70, v69
	v_fma_f32 v72, -v68, v71, v70
	v_fmac_f32_e32 v71, v72, v69
	v_fma_f32 v68, -v68, v71, v70
	v_div_fmas_f32 v68, v68, v69, v71
	v_div_fixup_f32 v68, v68, v100, 1.0
	v_cvt_pk_bf16_f32 v56, v80, v81
	v_cvt_pk_bf16_f32 v57, v82, v83
	v_cvt_pk_bf16_f32 v58, v76, v77
	v_cvt_pk_bf16_f32 v59, v78, v79
	v_cvt_pk_bf16_f32 v53, v74, v75
	v_cvt_pk_bf16_f32 v54, v99, v101
	v_cvt_pk_bf16_f32 v55, v102, v103
	v_cvt_pk_bf16_f32 v50, v104, v98
	v_cvt_pk_bf16_f32 v51, v105, v106
	v_cvt_pk_bf16_f32 v40, v107, v108
	v_cvt_pk_bf16_f32 v41, v109, v110
	v_cvt_pk_bf16_f32 v42, v111, v112
	v_cvt_pk_bf16_f32 v43, v113, v114
	v_cvt_pk_bf16_f32 v24, v115, v116
	v_cvt_pk_bf16_f32 v25, v117, v118
	v_cvt_pk_bf16_f32 v26, v119, v147
	v_cvt_pk_bf16_f32 v27, v155, v201
	v_cvt_pk_bf16_f32 v4, v202, v203
	v_cvt_pk_bf16_f32 v5, v204, v205
	v_cvt_pk_bf16_f32 v6, v206, v207
	v_cvt_pk_bf16_f32 v7, v208, v7
	v_mov_b32_e32 v69, v68
	v_lshl_add_u64 v[70:71], v[144:145], 0, v[150:151]
	s_mov_b64 s[0:1], 0
; #define LAS __attribute__((address_space(3)))
; __device__ __forceinline__ f32x4 mfma16(bf16x8 a, bf16x8 b, f32x4 c) { return __builtin_amdgcn_mfma_f32_16x16x32_bf16(a, b, c, 0, 0, 0); }
; #define LDS_BARRIER() do { asm volatile("s_waitcnt lgkmcnt(0)" ::: "memory"); __builtin_amdgcn_s_barrier(); asm volatile("" ::: "memory"); } while (0)
; #define XLOAD(kvbase, c8) do { const bf16_t* _src = (kvbase) + (((c8) >= 4) ? 2048 : 0) + ((c8) & 3) * 128 + piece * 8; \
;         _Pragma("unroll") for (int _it = 0; _it < 8; ++_it) pre[_it] = *(const u32x4*)(_src + (size_t)(srow + 32 * _it) * 4096); } while (0)
; #define XSTORE(buf) do { _Pragma("unroll") for (int _it = 0; _it < 8; ++_it) *(LAS u32x4*)((buf) + (srow + 32 * _it) * KV_STRIDE + piece * 16) = pre[_it]; } while (0)
; __device__ void cross_items(const Params& p, LAS unsigned char* lds) {
;     ...
;         for (int c = 0; c < 4; ++c) {
;             LAS unsigned char* buf = lds + (c & 1) * KV_BUF;
;             XSTORE(buf);
;             if (c < 3) XLOAD(kvb, 5 + c); else XLOAD(nkvb, 0);
;             LDS_BARRIER();
;             f32x4 ot[8];
; #pragma unroll
;             for (int c8 = 0; c8 < 8; ++c8) ot[c8] = (f32x4){0.f, 0.f, 0.f, 0.f};
;             const unsigned bb = lbase + (unsigned)((c & 1) * KV_BUF);
; #pragma unroll
;             for (int sx = 0; sx < 8; ++sx) {
;                 const unsigned aA = bb + (unsigned)((32 * sx + 4 * g + (idx >> 2)) * KV_STRIDE + 8 * (idx & 3));
;                 const unsigned aB = aA + 16u * KV_STRIDE;
;                 bf16x8 vf[4];
;                 tr_frag4(aA, aB, vf);
; #pragma unroll
;                 for (int c8 = 0; c8 < 4; ++c8) ot[c8] = mfma16(vf[c8], pf[sx], ot[c8]);
;                 tr_frag4(aA + 128, aB + 128, vf);
; #pragma unroll
;                 for (int c8 = 0; c8 < 4; ++c8) ot[4 + c8] = mfma16(vf[c8], pf[sx], ot[4 + c8]);
;             }
.LBB0_395:
	v_lshl_add_u64 v[72:73], v[148:149], 0, s[0:1]
	s_mov_b32 s8, 0xc401000
	v_add_co_u32_e32 v74, vcc, s8, v72
	s_mov_b32 s8, 0xc441000
	s_nop 0
	v_addc_co_u32_e32 v75, vcc, 0, v73, vcc
	v_add_co_u32_e32 v76, vcc, s8, v72
	s_mov_b32 s8, 0xc481000
	s_nop 0
	v_addc_co_u32_e32 v77, vcc, 0, v73, vcc
	v_add_co_u32_e32 v78, vcc, s8, v72
	s_mov_b32 s8, 0xc4c1000
	s_nop 0
	v_addc_co_u32_e32 v79, vcc, 0, v73, vcc
	v_add_co_u32_e32 v80, vcc, s8, v72
	s_mov_b32 s8, 0xc501000
	s_nop 0
	v_addc_co_u32_e32 v81, vcc, 0, v73, vcc
	v_add_co_u32_e32 v82, vcc, s8, v72
	s_mov_b32 s8, 0xc541000
	s_nop 0
	v_addc_co_u32_e32 v83, vcc, 0, v73, vcc
	v_add_co_u32_e32 v84, vcc, s8, v72
	s_bitcmp1_b32 s3, 0
	s_nop 0
	v_addc_co_u32_e32 v85, vcc, 0, v73, vcc
	s_mov_b32 s8, 0xc581000
	s_cselect_b32 s7, 0x11000, 0
	v_add_co_u32_e32 v86, vcc, s8, v72
	s_mov_b32 s8, 0xc5c1000
	s_nop 0
	v_addc_co_u32_e32 v87, vcc, 0, v73, vcc
	v_add3_u32 v88, v137, s7, v157
	v_add_co_u32_e32 v72, vcc, s8, v72
	s_waitcnt vmcnt(7)
	ds_write_b128 v88, v[8:11]
	s_waitcnt vmcnt(6)
	ds_write_b128 v88, v[12:15] offset:8704
	s_waitcnt vmcnt(5)
	ds_write_b128 v88, v[16:19] offset:17408
	s_waitcnt vmcnt(4)
	ds_write_b128 v88, v[20:23] offset:26112
	s_waitcnt vmcnt(3)
	ds_write_b128 v88, v[28:31] offset:34816
	s_waitcnt vmcnt(2)
	ds_write_b128 v88, v[32:35] offset:43520
	s_waitcnt vmcnt(1)
	ds_write_b128 v88, v[36:39] offset:52224
	s_waitcnt vmcnt(0)
	ds_write_b128 v88, v[44:47] offset:60928
	v_addc_co_u32_e32 v73, vcc, 0, v73, vcc
	global_load_dwordx4 v[8:11], v[74:75], off offset:256
	global_load_dwordx4 v[12:15], v[76:77], off offset:256
	global_load_dwordx4 v[16:19], v[78:79], off offset:256
	global_load_dwordx4 v[20:23], v[80:81], off offset:256
	global_load_dwordx4 v[28:31], v[82:83], off offset:256
	global_load_dwordx4 v[32:35], v[84:85], off offset:256
	global_load_dwordx4 v[36:39], v[86:87], off offset:256
	global_load_dwordx4 v[44:47], v[72:73], off offset:256
	v_add_u32_e32 v147, s7, v156
	v_add_u32_e32 v88, v147, v159
	s_waitcnt lgkmcnt(0)
	s_barrier
	v_add_u32_e32 v89, 0x1100, v88
	ds_read_b64_tr_b16 v[116:117], v88
	ds_read_b64_tr_b16 v[112:113], v88 offset:32
	ds_read_b64_tr_b16 v[108:109], v88 offset:64
	ds_read_b64_tr_b16 v[104:105], v88 offset:96
	ds_read_b64_tr_b16 v[118:119], v89
	ds_read_b64_tr_b16 v[114:115], v89 offset:32
	ds_read_b64_tr_b16 v[110:111], v89 offset:64
	ds_read_b64_tr_b16 v[106:107], v89 offset:96
	v_add_u32_e32 v209, 0x80, v88
	v_add_u32_e32 v210, 0x1180, v88
	ds_read_b64_tr_b16 v[242:243], v209
	ds_read_b64_tr_b16 v[238:239], v209 offset:32
	ds_read_b64_tr_b16 v[234:235], v209 offset:64
	ds_read_b64_tr_b16 v[230:231], v209 offset:96
	ds_read_b64_tr_b16 v[244:245], v210
	ds_read_b64_tr_b16 v[240:241], v210 offset:32
	ds_read_b64_tr_b16 v[236:237], v210 offset:64
	ds_read_b64_tr_b16 v[232:233], v210 offset:96
	s_waitcnt lgkmcnt(8)
	v_mfma_f32_16x16x32_bf16 v[84:87], v[116:119], v[64:67], 0
	v_mfma_f32_16x16x32_bf16 v[76:79], v[108:111], v[64:67], 0
	v_mfma_f32_16x16x32_bf16 v[72:75], v[104:107], v[64:67], 0
	v_mfma_f32_16x16x32_bf16 v[80:83], v[112:115], v[64:67], 0
	v_add_u32_e32 v150, v147, v160
	v_add_u32_e32 v151, 0x1100, v150
	ds_read_b64_tr_b16 v[116:117], v150
	ds_read_b64_tr_b16 v[112:113], v150 offset:32
	ds_read_b64_tr_b16 v[108:109], v150 offset:64
	ds_read_b64_tr_b16 v[104:105], v150 offset:96
	ds_read_b64_tr_b16 v[118:119], v151
	ds_read_b64_tr_b16 v[114:115], v151 offset:32
	ds_read_b64_tr_b16 v[110:111], v151 offset:64
	ds_read_b64_tr_b16 v[106:107], v151 offset:96
	s_waitcnt lgkmcnt(8)
	v_mfma_f32_16x16x32_bf16 v[100:103], v[242:245], v[64:67], 0
	v_mfma_f32_16x16x32_bf16 v[96:99], v[238:241], v[64:67], 0
	v_mfma_f32_16x16x32_bf16 v[92:95], v[234:237], v[64:67], 0
	v_mfma_f32_16x16x32_bf16 v[88:91], v[230:233], v[64:67], 0
	v_add_u32_e32 v151, 0x80, v150
	v_add_u32_e32 v150, 0x1180, v150
	s_add_i32 s3, s3, 1
	ds_read_b64_tr_b16 v[242:243], v151
	ds_read_b64_tr_b16 v[238:239], v151 offset:32
	ds_read_b64_tr_b16 v[234:235], v151 offset:64
	ds_read_b64_tr_b16 v[230:231], v151 offset:96
	ds_read_b64_tr_b16 v[244:245], v150
	ds_read_b64_tr_b16 v[240:241], v150 offset:32
	ds_read_b64_tr_b16 v[236:237], v150 offset:64
	ds_read_b64_tr_b16 v[232:233], v150 offset:96
	s_waitcnt lgkmcnt(8)
	v_mfma_f32_16x16x32_bf16 v[84:87], v[116:119], v[60:63], v[84:87]
	v_mfma_f32_16x16x32_bf16 v[76:79], v[108:111], v[60:63], v[76:79]
	v_mfma_f32_16x16x32_bf16 v[72:75], v[104:107], v[60:63], v[72:75]
	v_mfma_f32_16x16x32_bf16 v[80:83], v[112:115], v[60:63], v[80:83]
	v_add_u32_e32 v150, v147, v161
	v_add_u32_e32 v151, 0x1100, v150
	ds_read_b64_tr_b16 v[116:117], v150
	ds_read_b64_tr_b16 v[112:113], v150 offset:32
	ds_read_b64_tr_b16 v[108:109], v150 offset:64
	ds_read_b64_tr_b16 v[104:105], v150 offset:96
	ds_read_b64_tr_b16 v[118:119], v151
	ds_read_b64_tr_b16 v[114:115], v151 offset:32
	ds_read_b64_tr_b16 v[110:111], v151 offset:64
	ds_read_b64_tr_b16 v[106:107], v151 offset:96
	s_waitcnt lgkmcnt(8)
	v_mfma_f32_16x16x32_bf16 v[100:103], v[242:245], v[60:63], v[100:103]
	v_mfma_f32_16x16x32_bf16 v[96:99], v[238:241], v[60:63], v[96:99]
	v_mfma_f32_16x16x32_bf16 v[92:95], v[234:237], v[60:63], v[92:95]
	v_mfma_f32_16x16x32_bf16 v[88:91], v[230:233], v[60:63], v[88:91]
	v_add_u32_e32 v151, 0x80, v150
	v_add_u32_e32 v150, 0x1180, v150
	ds_read_b64_tr_b16 v[242:243], v151
	ds_read_b64_tr_b16 v[238:239], v151 offset:32
	ds_read_b64_tr_b16 v[234:235], v151 offset:64
	ds_read_b64_tr_b16 v[230:231], v151 offset:96
	ds_read_b64_tr_b16 v[244:245], v150
	ds_read_b64_tr_b16 v[240:241], v150 offset:32
	ds_read_b64_tr_b16 v[236:237], v150 offset:64
	ds_read_b64_tr_b16 v[232:233], v150 offset:96
	s_waitcnt lgkmcnt(8)
; __device__ __forceinline__ f32x4 mfma16(bf16x8 a, bf16x8 b, f32x4 c) { return __builtin_amdgcn_mfma_f32_16x16x32_bf16(a, b, c, 0, 0, 0); }
; __device__ void cross_items(const Params& p, LAS unsigned char* lds) {
;     ...
; #pragma unroll
;             for (int sx = 0; sx < 8; ++sx) {
;                 const unsigned aA = bb + (unsigned)((32 * sx + 4 * g + (idx >> 2)) * KV_STRIDE + 8 * (idx & 3));
;                 const unsigned aB = aA + 16u * KV_STRIDE;
;                 bf16x8 vf[4];
;                 tr_frag4(aA, aB, vf);
; #pragma unroll
;                 for (int c8 = 0; c8 < 4; ++c8) ot[c8] = mfma16(vf[c8], pf[sx], ot[c8]);
;                 tr_frag4(aA + 128, aB + 128, vf);
; #pragma unroll
;                 for (int c8 = 0; c8 < 4; ++c8) ot[4 + c8] = mfma16(vf[c8], pf[sx], ot[4 + c8]);
;             }
	v_mfma_f32_16x16x32_bf16 v[84:87], v[116:119], v[56:59], v[84:87]
	v_mfma_f32_16x16x32_bf16 v[76:79], v[108:111], v[56:59], v[76:79]
	v_mfma_f32_16x16x32_bf16 v[72:75], v[104:107], v[56:59], v[72:75]
	v_mfma_f32_16x16x32_bf16 v[80:83], v[112:115], v[56:59], v[80:83]
	v_add_u32_e32 v150, v147, v162
	v_add_u32_e32 v151, 0x1100, v150
	ds_read_b64_tr_b16 v[116:117], v150
	ds_read_b64_tr_b16 v[112:113], v150 offset:32
	ds_read_b64_tr_b16 v[108:109], v150 offset:64
	ds_read_b64_tr_b16 v[104:105], v150 offset:96
	ds_read_b64_tr_b16 v[118:119], v151
	ds_read_b64_tr_b16 v[114:115], v151 offset:32
	ds_read_b64_tr_b16 v[110:111], v151 offset:64
	ds_read_b64_tr_b16 v[106:107], v151 offset:96
	s_waitcnt lgkmcnt(8)
	v_mfma_f32_16x16x32_bf16 v[100:103], v[242:245], v[56:59], v[100:103]
	v_mfma_f32_16x16x32_bf16 v[96:99], v[238:241], v[56:59], v[96:99]
	v_mfma_f32_16x16x32_bf16 v[92:95], v[234:237], v[56:59], v[92:95]
	v_mfma_f32_16x16x32_bf16 v[88:91], v[230:233], v[56:59], v[88:91]
	v_add_u32_e32 v151, 0x80, v150
	v_add_u32_e32 v150, 0x1180, v150
	ds_read_b64_tr_b16 v[242:243], v151
	ds_read_b64_tr_b16 v[238:239], v151 offset:32
	ds_read_b64_tr_b16 v[234:235], v151 offset:64
	ds_read_b64_tr_b16 v[230:231], v151 offset:96
	ds_read_b64_tr_b16 v[244:245], v150
	ds_read_b64_tr_b16 v[240:241], v150 offset:32
	ds_read_b64_tr_b16 v[236:237], v150 offset:64
	ds_read_b64_tr_b16 v[232:233], v150 offset:96
	s_waitcnt lgkmcnt(8)
	v_mfma_f32_16x16x32_bf16 v[84:87], v[116:119], v[52:55], v[84:87]
	v_mfma_f32_16x16x32_bf16 v[76:79], v[108:111], v[52:55], v[76:79]
	v_mfma_f32_16x16x32_bf16 v[72:75], v[104:107], v[52:55], v[72:75]
	v_mfma_f32_16x16x32_bf16 v[80:83], v[112:115], v[52:55], v[80:83]
	v_add_u32_e32 v150, v147, v163
	v_add_u32_e32 v151, 0x1100, v150
	ds_read_b64_tr_b16 v[116:117], v150
	ds_read_b64_tr_b16 v[112:113], v150 offset:32
	ds_read_b64_tr_b16 v[108:109], v150 offset:64
	ds_read_b64_tr_b16 v[104:105], v150 offset:96
	ds_read_b64_tr_b16 v[118:119], v151
	ds_read_b64_tr_b16 v[114:115], v151 offset:32
	ds_read_b64_tr_b16 v[110:111], v151 offset:64
	ds_read_b64_tr_b16 v[106:107], v151 offset:96
	s_waitcnt lgkmcnt(8)
	v_mfma_f32_16x16x32_bf16 v[100:103], v[242:245], v[52:55], v[100:103]
	v_mfma_f32_16x16x32_bf16 v[96:99], v[238:241], v[52:55], v[96:99]
	v_mfma_f32_16x16x32_bf16 v[92:95], v[234:237], v[52:55], v[92:95]
	v_mfma_f32_16x16x32_bf16 v[88:91], v[230:233], v[52:55], v[88:91]
	v_add_u32_e32 v151, 0x80, v150
	v_add_u32_e32 v150, 0x1180, v150
	ds_read_b64_tr_b16 v[242:243], v151
	ds_read_b64_tr_b16 v[238:239], v151 offset:32
	ds_read_b64_tr_b16 v[234:235], v151 offset:64
	ds_read_b64_tr_b16 v[230:231], v151 offset:96
	ds_read_b64_tr_b16 v[244:245], v150
	ds_read_b64_tr_b16 v[240:241], v150 offset:32
	ds_read_b64_tr_b16 v[236:237], v150 offset:64
	ds_read_b64_tr_b16 v[232:233], v150 offset:96
	s_waitcnt lgkmcnt(8)
	v_mfma_f32_16x16x32_bf16 v[84:87], v[116:119], v[48:51], v[84:87]
	v_mfma_f32_16x16x32_bf16 v[76:79], v[108:111], v[48:51], v[76:79]
	v_mfma_f32_16x16x32_bf16 v[72:75], v[104:107], v[48:51], v[72:75]
	v_mfma_f32_16x16x32_bf16 v[80:83], v[112:115], v[48:51], v[80:83]
	v_add_u32_e32 v150, v147, v164
	v_add_u32_e32 v151, 0x1100, v150
	ds_read_b64_tr_b16 v[116:117], v150
	ds_read_b64_tr_b16 v[112:113], v150 offset:32
	ds_read_b64_tr_b16 v[108:109], v150 offset:64
	ds_read_b64_tr_b16 v[104:105], v150 offset:96
	ds_read_b64_tr_b16 v[118:119], v151
	ds_read_b64_tr_b16 v[114:115], v151 offset:32
	ds_read_b64_tr_b16 v[110:111], v151 offset:64
	ds_read_b64_tr_b16 v[106:107], v151 offset:96
	s_waitcnt lgkmcnt(8)
	v_mfma_f32_16x16x32_bf16 v[100:103], v[242:245], v[48:51], v[100:103]
	v_mfma_f32_16x16x32_bf16 v[96:99], v[238:241], v[48:51], v[96:99]
	v_mfma_f32_16x16x32_bf16 v[92:95], v[234:237], v[48:51], v[92:95]
	v_mfma_f32_16x16x32_bf16 v[88:91], v[230:233], v[48:51], v[88:91]
	v_add_u32_e32 v151, 0x80, v150
	v_add_u32_e32 v150, 0x1180, v150
	ds_read_b64_tr_b16 v[242:243], v151
	ds_read_b64_tr_b16 v[238:239], v151 offset:32
	ds_read_b64_tr_b16 v[234:235], v151 offset:64
	ds_read_b64_tr_b16 v[230:231], v151 offset:96
	ds_read_b64_tr_b16 v[244:245], v150
	ds_read_b64_tr_b16 v[240:241], v150 offset:32
	ds_read_b64_tr_b16 v[236:237], v150 offset:64
	ds_read_b64_tr_b16 v[232:233], v150 offset:96
	s_waitcnt lgkmcnt(8)
	v_mfma_f32_16x16x32_bf16 v[84:87], v[116:119], v[40:43], v[84:87]
	v_mfma_f32_16x16x32_bf16 v[76:79], v[108:111], v[40:43], v[76:79]
	v_mfma_f32_16x16x32_bf16 v[72:75], v[104:107], v[40:43], v[72:75]
	v_mfma_f32_16x16x32_bf16 v[80:83], v[112:115], v[40:43], v[80:83]
	v_add_u32_e32 v150, v147, v165
	v_add_u32_e32 v151, 0x1100, v150
	v_add_u32_e32 v147, v147, v166
	ds_read_b64_tr_b16 v[116:117], v150
	ds_read_b64_tr_b16 v[112:113], v150 offset:32
	ds_read_b64_tr_b16 v[108:109], v150 offset:64
	ds_read_b64_tr_b16 v[104:105], v150 offset:96
	ds_read_b64_tr_b16 v[118:119], v151
	ds_read_b64_tr_b16 v[114:115], v151 offset:32
	ds_read_b64_tr_b16 v[110:111], v151 offset:64
	ds_read_b64_tr_b16 v[106:107], v151 offset:96
	s_waitcnt lgkmcnt(8)
	v_mfma_f32_16x16x32_bf16 v[100:103], v[242:245], v[40:43], v[100:103]
	v_mfma_f32_16x16x32_bf16 v[96:99], v[238:241], v[40:43], v[96:99]
	v_mfma_f32_16x16x32_bf16 v[92:95], v[234:237], v[40:43], v[92:95]
	v_mfma_f32_16x16x32_bf16 v[88:91], v[230:233], v[40:43], v[88:91]
	v_add_u32_e32 v151, 0x80, v150
	v_add_u32_e32 v150, 0x1180, v150
	ds_read_b64_tr_b16 v[242:243], v151
	ds_read_b64_tr_b16 v[238:239], v151 offset:32
	ds_read_b64_tr_b16 v[234:235], v151 offset:64
	ds_read_b64_tr_b16 v[230:231], v151 offset:96
	ds_read_b64_tr_b16 v[244:245], v150
	ds_read_b64_tr_b16 v[240:241], v150 offset:32
	ds_read_b64_tr_b16 v[236:237], v150 offset:64
	ds_read_b64_tr_b16 v[232:233], v150 offset:96
	s_waitcnt lgkmcnt(8)
; #define LAS __attribute__((address_space(3)))
; __device__ __forceinline__ unsigned cvt_pk_bf16(float lo, float hi) { const f32x2v v = {lo, hi}; const b16x2v r = __builtin_convertvector(v, b16x2v); return __builtin_bit_cast(unsigned, r); }
; __device__ __forceinline__ f32x4 mfma16(bf16x8 a, bf16x8 b, f32x4 c) { return __builtin_amdgcn_mfma_f32_16x16x32_bf16(a, b, c, 0, 0, 0); }
; #define LDS_BARRIER() do { asm volatile("s_waitcnt lgkmcnt(0)" ::: "memory"); __builtin_amdgcn_s_barrier(); asm volatile("" ::: "memory"); } while (0)
; #define XLOAD(kvbase, c8) do { const bf16_t* _src = (kvbase) + (((c8) >= 4) ? 2048 : 0) + ((c8) & 3) * 128 + piece * 8; \
;         _Pragma("unroll") for (int _it = 0; _it < 8; ++_it) pre[_it] = *(const u32x4*)(_src + (size_t)(srow + 32 * _it) * 4096); } while (0)
; #define XSTORE(buf) do { _Pragma("unroll") for (int _it = 0; _it < 8; ++_it) *(LAS u32x4*)((buf) + (srow + 32 * _it) * KV_STRIDE + piece * 16) = pre[_it]; } while (0)
; __device__ void cross_items(const Params& p, LAS unsigned char* lds) {
;     ...
;         for (int c = 0; c < 4; ++c) {
;             LAS unsigned char* buf = lds + (c & 1) * KV_BUF;
;             XSTORE(buf);
;             if (c < 3) XLOAD(kvb, 5 + c); else XLOAD(nkvb, 0);
;             LDS_BARRIER();
;             f32x4 ot[8];
; #pragma unroll
;             for (int c8 = 0; c8 < 8; ++c8) ot[c8] = (f32x4){0.f, 0.f, 0.f, 0.f};
;             const unsigned bb = lbase + (unsigned)((c & 1) * KV_BUF);
; #pragma unroll
;             for (int sx = 0; sx < 8; ++sx) {
;                 const unsigned aA = bb + (unsigned)((32 * sx + 4 * g + (idx >> 2)) * KV_STRIDE + 8 * (idx & 3));
;                 const unsigned aB = aA + 16u * KV_STRIDE;
;                 bf16x8 vf[4];
;                 tr_frag4(aA, aB, vf);
; #pragma unroll
;                 for (int c8 = 0; c8 < 4; ++c8) ot[c8] = mfma16(vf[c8], pf[sx], ot[c8]);
;                 tr_frag4(aA + 128, aB + 128, vf);
; #pragma unroll
;                 for (int c8 = 0; c8 < 4; ++c8) ot[4 + c8] = mfma16(vf[c8], pf[sx], ot[4 + c8]);
;             }
; #pragma unroll
;             for (int c8 = 0; c8 < 8; ++c8) { u32x2 wv; wv.x = cvt_pk_bf16(ot[c8][0] * inv, ot[c8][1] * inv); wv.y = cvt_pk_bf16(ot[c8][2] * inv, ot[c8][3] * inv);
;                 *(u32x2*)(oc + tok * DM + head * 512 + c * 128 + 16 * c8 + 4 * g) = wv; }
;         }
	v_mfma_f32_16x16x32_bf16 v[84:87], v[116:119], v[24:27], v[84:87]
	v_mfma_f32_16x16x32_bf16 v[76:79], v[108:111], v[24:27], v[76:79]
	v_mfma_f32_16x16x32_bf16 v[72:75], v[104:107], v[24:27], v[72:75]
	v_mfma_f32_16x16x32_bf16 v[80:83], v[112:115], v[24:27], v[80:83]
	s_waitcnt lgkmcnt(0)
	v_mfma_f32_16x16x32_bf16 v[100:103], v[242:245], v[24:27], v[100:103]
	v_mfma_f32_16x16x32_bf16 v[96:99], v[238:241], v[24:27], v[96:99]
	v_mfma_f32_16x16x32_bf16 v[92:95], v[234:237], v[24:27], v[92:95]
	v_mfma_f32_16x16x32_bf16 v[88:91], v[230:233], v[24:27], v[88:91]
	v_add_u32_e32 v150, 0x1100, v147
	ds_read_b64_tr_b16 v[116:117], v147
	ds_read_b64_tr_b16 v[112:113], v147 offset:32
	ds_read_b64_tr_b16 v[108:109], v147 offset:64
	ds_read_b64_tr_b16 v[104:105], v147 offset:96
	ds_read_b64_tr_b16 v[118:119], v150
	ds_read_b64_tr_b16 v[114:115], v150 offset:32
	ds_read_b64_tr_b16 v[110:111], v150 offset:64
	ds_read_b64_tr_b16 v[106:107], v150 offset:96
	s_waitcnt lgkmcnt(0)
	v_add_u32_e32 v150, 0x80, v147
	v_add_u32_e32 v147, 0x1180, v147
	v_mfma_f32_16x16x32_bf16 v[84:87], v[116:119], v[4:7], v[84:87]
	v_mfma_f32_16x16x32_bf16 v[76:79], v[108:111], v[4:7], v[76:79]
	v_mfma_f32_16x16x32_bf16 v[72:75], v[104:107], v[4:7], v[72:75]
	s_nop 5
	v_mul_f32_e64 v84, v68, v84
	v_mul_f32_e64 v85, v69, v85
	v_pk_mul_f32 v[86:87], v[68:69], v[86:87]
	v_pk_mul_f32 v[76:77], v[68:69], v[76:77]
	v_mfma_f32_16x16x32_bf16 v[80:83], v[112:115], v[4:7], v[80:83]
	ds_read_b64_tr_b16 v[116:117], v150
	ds_read_b64_tr_b16 v[112:113], v150 offset:32
	ds_read_b64_tr_b16 v[108:109], v150 offset:64
	ds_read_b64_tr_b16 v[104:105], v150 offset:96
	ds_read_b64_tr_b16 v[118:119], v147
	ds_read_b64_tr_b16 v[114:115], v147 offset:32
	ds_read_b64_tr_b16 v[110:111], v147 offset:64
	ds_read_b64_tr_b16 v[106:107], v147 offset:96
	s_waitcnt lgkmcnt(0)
	v_mul_f32_e64 v78, v68, v78
	v_mul_f32_e64 v79, v69, v79
	v_pk_mul_f32 v[72:73], v[68:69], v[72:73]
	v_mfma_f32_16x16x32_bf16 v[100:103], v[116:119], v[4:7], v[100:103]
	v_mul_f32_e64 v74, v68, v74
	v_mul_f32_e64 v75, v69, v75
	s_nop 1
	v_pk_mul_f32 v[80:81], v[68:69], v[80:81]
	v_pk_mul_f32 v[82:83], v[68:69], v[82:83]
	v_mfma_f32_16x16x32_bf16 v[96:99], v[112:115], v[4:7], v[96:99]
	v_lshl_add_u64 v[112:113], v[70:71], 0, s[0:1]
	s_add_u32 s0, s0, 0x100
	s_addc_u32 s1, s1, 0
	v_mfma_f32_16x16x32_bf16 v[92:95], v[108:111], v[4:7], v[92:95]
	v_cvt_pk_bf16_f32 v84, v84, v85
	v_cvt_pk_bf16_f32 v85, v86, v87
	v_cvt_pk_bf16_f32 v76, v76, v77
	v_mfma_f32_16x16x32_bf16 v[88:91], v[104:107], v[4:7], v[88:91]
	v_cvt_pk_bf16_f32 v77, v78, v79
	v_cvt_pk_bf16_f32 v72, v72, v73
	v_cvt_pk_bf16_f32 v73, v74, v75
	v_pk_mul_f32 v[74:75], v[68:69], v[100:101]
	v_pk_mul_f32 v[78:79], v[68:69], v[102:103]
	s_cmpk_eq_i32 s0, 0x300
	v_cvt_pk_bf16_f32 v80, v80, v81
	v_cvt_pk_bf16_f32 v81, v82, v83
	v_pk_mul_f32 v[82:83], v[68:69], v[96:97]
	v_pk_mul_f32 v[86:87], v[68:69], v[98:99]
	v_pk_mul_f32 v[92:93], v[68:69], v[92:93]
	v_pk_mul_f32 v[94:95], v[68:69], v[94:95]
	v_pk_mul_f32 v[88:89], v[68:69], v[88:89]
	v_pk_mul_f32 v[90:91], v[68:69], v[90:91]
	global_store_dwordx2 v[112:113], v[84:85], off offset:-128
	global_store_dwordx2 v[112:113], v[80:81], off offset:-96
	global_store_dwordx2 v[112:113], v[76:77], off offset:-64
	global_store_dwordx2 v[112:113], v[72:73], off offset:-32
	v_cvt_pk_bf16_f32 v72, v74, v75
	v_cvt_pk_bf16_f32 v73, v78, v79
	v_cvt_pk_bf16_f32 v74, v82, v83
	v_cvt_pk_bf16_f32 v75, v86, v87
	v_cvt_pk_bf16_f32 v76, v92, v93
	v_cvt_pk_bf16_f32 v77, v94, v95
	v_cvt_pk_bf16_f32 v78, v88, v89
	v_cvt_pk_bf16_f32 v79, v90, v91
	global_store_dwordx2 v[112:113], v[72:73], off
	global_store_dwordx2 v[112:113], v[74:75], off offset:32
	global_store_dwordx2 v[112:113], v[76:77], off offset:64
	global_store_dwordx2 v[112:113], v[78:79], off offset:96
	s_cbranch_scc0 .LBB0_395
	s_add_i32 s0, s6, 1
	v_readlane_b32 s1, v253, 58
	s_cmp_gt_i32 s6, s1
	s_cselect_b64 s[8:9], -1, 0
	s_and_b64 vcc, s[8:9], exec
	s_cselect_b32 s1, 0x200, s0
	s_cmpk_lt_i32 s1, 0x200
	s_cselect_b32 s1, s1, s6
	s_lshl_b32 s3, s1, 1
	s_and_b32 s6, s3, 0xffffff00
	s_ashr_i32 s7, s6, 31
	s_lshl_b64 s[6:7], s[6:7], 13
	s_add_u32 s3, s30, s6
	s_addc_u32 s7, s31, s7
	s_lshl_b32 s1, s1, 5
	s_and_b32 s1, s1, 0xc00
	s_add_u32 s6, s3, s1
	s_addc_u32 s7, s7, 0
	v_mov_b32_e32 v155, v3
	v_lshl_add_u64 v[72:73], s[6:7], 0, v[154:155]
	s_waitcnt vmcnt(15)
	ds_write_b128 v200, v[8:11]
	s_waitcnt vmcnt(14)
	ds_write_b128 v200, v[12:15] offset:8704
	s_waitcnt vmcnt(13)
	ds_write_b128 v200, v[16:19] offset:17408
	s_waitcnt vmcnt(12)
	ds_write_b128 v200, v[20:23] offset:26112
	s_waitcnt vmcnt(11)
	ds_write_b128 v200, v[28:31] offset:34816
	s_waitcnt vmcnt(10)
	ds_write_b128 v200, v[32:35] offset:43520
	s_waitcnt vmcnt(9)
	ds_write_b128 v200, v[36:39] offset:52224
	s_waitcnt vmcnt(8)
	ds_write_b128 v200, v[44:47] offset:60928
	v_lshl_add_u64 v[8:9], v[72:73], 0, v[134:135]
	global_load_dwordx4 v[44:47], v[8:9], off
	v_lshl_add_u64 v[8:9], v[72:73], 0, v[132:133]
	global_load_dwordx4 v[36:39], v[8:9], off
	v_lshl_add_u64 v[8:9], v[72:73], 0, v[130:131]
	global_load_dwordx4 v[32:35], v[8:9], off
	v_lshl_add_u64 v[8:9], v[72:73], 0, v[128:129]
	global_load_dwordx4 v[28:31], v[8:9], off
	v_lshl_add_u64 v[8:9], v[72:73], 0, v[126:127]
	global_load_dwordx4 v[20:23], v[8:9], off
	v_lshl_add_u64 v[8:9], v[72:73], 0, v[124:125]
	global_load_dwordx4 v[16:19], v[8:9], off
	v_lshl_add_u64 v[8:9], v[72:73], 0, v[122:123]
	global_load_dwordx4 v[12:15], v[8:9], off
	v_lshl_add_u64 v[8:9], v[72:73], 0, v[120:121]
	global_load_dwordx4 v[8:11], v[8:9], off
	s_waitcnt lgkmcnt(0)
	s_barrier
; __device__ __forceinline__ f32x4 mfma16(bf16x8 a, bf16x8 b, f32x4 c) { return __builtin_amdgcn_mfma_f32_16x16x32_bf16(a, b, c, 0, 0, 0); }
; __device__ void cross_items(const Params& p, LAS unsigned char* lds) {
;     ...
; #pragma unroll
;             for (int c8 = 0; c8 < 8; ++c8) ot[c8] = (f32x4){0.f, 0.f, 0.f, 0.f};
;             const unsigned bb = lbase + (unsigned)((c & 1) * KV_BUF);
; #pragma unroll
;             for (int sx = 0; sx < 8; ++sx) {
;                 const unsigned aA = bb + (unsigned)((32 * sx + 4 * g + (idx >> 2)) * KV_STRIDE + 8 * (idx & 3));
;                 const unsigned aB = aA + 16u * KV_STRIDE;
;                 bf16x8 vf[4];
;                 tr_frag4(aA, aB, vf);
; #pragma unroll
;                 for (int c8 = 0; c8 < 4; ++c8) ot[c8] = mfma16(vf[c8], pf[sx], ot[c8]);
;                 tr_frag4(aA + 128, aB + 128, vf);
; #pragma unroll
;                 for (int c8 = 0; c8 < 4; ++c8) ot[4 + c8] = mfma16(vf[c8], pf[sx], ot[4 + c8]);
;             }
	ds_read_b64_tr_b16 v[84:85], v168
	ds_read_b64_tr_b16 v[80:81], v168 offset:32
	ds_read_b64_tr_b16 v[76:77], v168 offset:64
	ds_read_b64_tr_b16 v[72:73], v168 offset:96
	ds_read_b64_tr_b16 v[86:87], v169
	ds_read_b64_tr_b16 v[82:83], v169 offset:32
	ds_read_b64_tr_b16 v[78:79], v169 offset:64
	ds_read_b64_tr_b16 v[74:75], v169 offset:96
	s_waitcnt lgkmcnt(0)
	ds_read_b64_tr_b16 v[100:101], v170
	ds_read_b64_tr_b16 v[96:97], v170 offset:32
	ds_read_b64_tr_b16 v[92:93], v170 offset:64
	ds_read_b64_tr_b16 v[88:89], v170 offset:96
	ds_read_b64_tr_b16 v[102:103], v171
	ds_read_b64_tr_b16 v[98:99], v171 offset:32
	ds_read_b64_tr_b16 v[94:95], v171 offset:64
	ds_read_b64_tr_b16 v[90:91], v171 offset:96
	s_waitcnt lgkmcnt(0)
	v_lshl_add_u64 v[70:71], v[152:153], 1, s[26:27]
	v_mfma_f32_16x16x32_bf16 v[84:87], v[84:87], v[64:67], 0
	s_lshl_b32 s18, s2, 1
	v_lshl_add_u64 v[70:71], v[70:71], 0, s[18:19]
	v_lshl_add_u64 v[70:71], v[70:71], 0, v[2:3]
	v_mfma_f32_16x16x32_bf16 v[80:83], v[80:83], v[64:67], 0
	s_add_i32 s5, s5, 16
	s_add_i32 s4, s4, 1
	s_mov_b32 s6, s0
	v_mfma_f32_16x16x32_bf16 v[76:79], v[76:79], v[64:67], 0
	v_mfma_f32_16x16x32_bf16 v[72:75], v[72:75], v[64:67], 0
	v_mfma_f32_16x16x32_bf16 v[100:103], v[100:103], v[64:67], 0
	v_mfma_f32_16x16x32_bf16 v[96:99], v[96:99], v[64:67], 0
	v_mfma_f32_16x16x32_bf16 v[92:95], v[92:95], v[64:67], 0
	v_mfma_f32_16x16x32_bf16 v[64:67], v[88:91], v[64:67], 0
	ds_read_b64_tr_b16 v[116:117], v172
	ds_read_b64_tr_b16 v[112:113], v172 offset:32
	ds_read_b64_tr_b16 v[108:109], v172 offset:64
	ds_read_b64_tr_b16 v[104:105], v172 offset:96
	ds_read_b64_tr_b16 v[118:119], v173
	ds_read_b64_tr_b16 v[114:115], v173 offset:32
	ds_read_b64_tr_b16 v[110:111], v173 offset:64
	ds_read_b64_tr_b16 v[106:107], v173 offset:96
	ds_read_b64_tr_b16 v[242:243], v174
	ds_read_b64_tr_b16 v[238:239], v174 offset:32
	ds_read_b64_tr_b16 v[234:235], v174 offset:64
	ds_read_b64_tr_b16 v[230:231], v174 offset:96
	ds_read_b64_tr_b16 v[244:245], v175
	ds_read_b64_tr_b16 v[240:241], v175 offset:32
	ds_read_b64_tr_b16 v[236:237], v175 offset:64
	ds_read_b64_tr_b16 v[232:233], v175 offset:96
	s_waitcnt lgkmcnt(8)
	v_mfma_f32_16x16x32_bf16 v[84:87], v[116:119], v[60:63], v[84:87]
	v_mfma_f32_16x16x32_bf16 v[80:83], v[112:115], v[60:63], v[80:83]
	v_mfma_f32_16x16x32_bf16 v[76:79], v[108:111], v[60:63], v[76:79]
	v_mfma_f32_16x16x32_bf16 v[72:75], v[104:107], v[60:63], v[72:75]
	ds_read_b64_tr_b16 v[116:117], v176
	ds_read_b64_tr_b16 v[112:113], v176 offset:32
	ds_read_b64_tr_b16 v[108:109], v176 offset:64
	ds_read_b64_tr_b16 v[104:105], v176 offset:96
	ds_read_b64_tr_b16 v[118:119], v177
	ds_read_b64_tr_b16 v[114:115], v177 offset:32
	ds_read_b64_tr_b16 v[110:111], v177 offset:64
	ds_read_b64_tr_b16 v[106:107], v177 offset:96
	s_waitcnt lgkmcnt(8)
	v_mfma_f32_16x16x32_bf16 v[100:103], v[242:245], v[60:63], v[100:103]
	v_mfma_f32_16x16x32_bf16 v[96:99], v[238:241], v[60:63], v[96:99]
	v_mfma_f32_16x16x32_bf16 v[92:95], v[234:237], v[60:63], v[92:95]
	v_mfma_f32_16x16x32_bf16 v[60:63], v[230:233], v[60:63], v[64:67]
	ds_read_b64_tr_b16 v[242:243], v178
	ds_read_b64_tr_b16 v[238:239], v178 offset:32
	ds_read_b64_tr_b16 v[234:235], v178 offset:64
	ds_read_b64_tr_b16 v[230:231], v178 offset:96
	ds_read_b64_tr_b16 v[244:245], v179
	ds_read_b64_tr_b16 v[240:241], v179 offset:32
	ds_read_b64_tr_b16 v[236:237], v179 offset:64
	ds_read_b64_tr_b16 v[232:233], v179 offset:96
	s_waitcnt lgkmcnt(8)
	v_mfma_f32_16x16x32_bf16 v[84:87], v[116:119], v[56:59], v[84:87]
	v_mfma_f32_16x16x32_bf16 v[80:83], v[112:115], v[56:59], v[80:83]
	v_mfma_f32_16x16x32_bf16 v[76:79], v[108:111], v[56:59], v[76:79]
	v_mfma_f32_16x16x32_bf16 v[64:67], v[104:107], v[56:59], v[72:75]
	ds_read_b64_tr_b16 v[116:117], v180
	ds_read_b64_tr_b16 v[112:113], v180 offset:32
	ds_read_b64_tr_b16 v[108:109], v180 offset:64
	ds_read_b64_tr_b16 v[104:105], v180 offset:96
	ds_read_b64_tr_b16 v[118:119], v181
	ds_read_b64_tr_b16 v[114:115], v181 offset:32
	ds_read_b64_tr_b16 v[110:111], v181 offset:64
	ds_read_b64_tr_b16 v[106:107], v181 offset:96
	s_waitcnt lgkmcnt(8)
	v_mfma_f32_16x16x32_bf16 v[100:103], v[242:245], v[56:59], v[100:103]
	v_mfma_f32_16x16x32_bf16 v[96:99], v[238:241], v[56:59], v[96:99]
	v_mfma_f32_16x16x32_bf16 v[88:91], v[234:237], v[56:59], v[92:95]
	v_mfma_f32_16x16x32_bf16 v[56:59], v[230:233], v[56:59], v[60:63]
	ds_read_b64_tr_b16 v[242:243], v182
	ds_read_b64_tr_b16 v[238:239], v182 offset:32
	ds_read_b64_tr_b16 v[234:235], v182 offset:64
	ds_read_b64_tr_b16 v[230:231], v182 offset:96
	ds_read_b64_tr_b16 v[244:245], v183
	ds_read_b64_tr_b16 v[240:241], v183 offset:32
	ds_read_b64_tr_b16 v[236:237], v183 offset:64
	ds_read_b64_tr_b16 v[232:233], v183 offset:96
	s_waitcnt lgkmcnt(8)
	v_mfma_f32_16x16x32_bf16 v[84:87], v[116:119], v[52:55], v[84:87]
	v_mfma_f32_16x16x32_bf16 v[80:83], v[112:115], v[52:55], v[80:83]
	v_mfma_f32_16x16x32_bf16 v[72:75], v[108:111], v[52:55], v[76:79]
	v_mfma_f32_16x16x32_bf16 v[60:63], v[104:107], v[52:55], v[64:67]
	ds_read_b64_tr_b16 v[116:117], v184
	ds_read_b64_tr_b16 v[112:113], v184 offset:32
	ds_read_b64_tr_b16 v[108:109], v184 offset:64
	ds_read_b64_tr_b16 v[104:105], v184 offset:96
	ds_read_b64_tr_b16 v[118:119], v185
	ds_read_b64_tr_b16 v[114:115], v185 offset:32
	ds_read_b64_tr_b16 v[110:111], v185 offset:64
	ds_read_b64_tr_b16 v[106:107], v185 offset:96
	s_waitcnt lgkmcnt(8)
; __device__ __forceinline__ unsigned cvt_pk_bf16(float lo, float hi) { const f32x2v v = {lo, hi}; const b16x2v r = __builtin_convertvector(v, b16x2v); return __builtin_bit_cast(unsigned, r); }
; __device__ __forceinline__ f32x4 mfma16(bf16x8 a, bf16x8 b, f32x4 c) { return __builtin_amdgcn_mfma_f32_16x16x32_bf16(a, b, c, 0, 0, 0); }
; __device__ void cross_items(const Params& p, LAS unsigned char* lds) {
;     ...
; #pragma unroll
;             for (int sx = 0; sx < 8; ++sx) {
;                 const unsigned aA = bb + (unsigned)((32 * sx + 4 * g + (idx >> 2)) * KV_STRIDE + 8 * (idx & 3));
;                 const unsigned aB = aA + 16u * KV_STRIDE;
;                 bf16x8 vf[4];
;                 tr_frag4(aA, aB, vf);
; #pragma unroll
;                 for (int c8 = 0; c8 < 4; ++c8) ot[c8] = mfma16(vf[c8], pf[sx], ot[c8]);
;                 tr_frag4(aA + 128, aB + 128, vf);
; #pragma unroll
;                 for (int c8 = 0; c8 < 4; ++c8) ot[4 + c8] = mfma16(vf[c8], pf[sx], ot[4 + c8]);
;             }
; #pragma unroll
;             for (int c8 = 0; c8 < 8; ++c8) { u32x2 wv; wv.x = cvt_pk_bf16(ot[c8][0] * inv, ot[c8][1] * inv); wv.y = cvt_pk_bf16(ot[c8][2] * inv, ot[c8][3] * inv);
;                 *(u32x2*)(oc + tok * DM + head * 512 + c * 128 + 16 * c8 + 4 * g) = wv; }
;         }
;     }
	v_mfma_f32_16x16x32_bf16 v[100:103], v[242:245], v[52:55], v[100:103]
	v_mfma_f32_16x16x32_bf16 v[92:95], v[238:241], v[52:55], v[96:99]
	v_mfma_f32_16x16x32_bf16 v[76:79], v[234:237], v[52:55], v[88:91]
	v_mfma_f32_16x16x32_bf16 v[52:55], v[230:233], v[52:55], v[56:59]
	ds_read_b64_tr_b16 v[242:243], v186
	ds_read_b64_tr_b16 v[238:239], v186 offset:32
	ds_read_b64_tr_b16 v[234:235], v186 offset:64
	ds_read_b64_tr_b16 v[230:231], v186 offset:96
	ds_read_b64_tr_b16 v[244:245], v187
	ds_read_b64_tr_b16 v[240:241], v187 offset:32
	ds_read_b64_tr_b16 v[236:237], v187 offset:64
	ds_read_b64_tr_b16 v[232:233], v187 offset:96
	s_waitcnt lgkmcnt(8)
	v_mfma_f32_16x16x32_bf16 v[84:87], v[116:119], v[48:51], v[84:87]
	v_mfma_f32_16x16x32_bf16 v[80:83], v[112:115], v[48:51], v[80:83]
	v_mfma_f32_16x16x32_bf16 v[64:67], v[108:111], v[48:51], v[72:75]
	v_mfma_f32_16x16x32_bf16 v[56:59], v[104:107], v[48:51], v[60:63]
	ds_read_b64_tr_b16 v[116:117], v188
	ds_read_b64_tr_b16 v[112:113], v188 offset:32
	ds_read_b64_tr_b16 v[108:109], v188 offset:64
	ds_read_b64_tr_b16 v[104:105], v188 offset:96
	ds_read_b64_tr_b16 v[118:119], v189
	ds_read_b64_tr_b16 v[114:115], v189 offset:32
	ds_read_b64_tr_b16 v[110:111], v189 offset:64
	ds_read_b64_tr_b16 v[106:107], v189 offset:96
	s_waitcnt lgkmcnt(8)
	v_mfma_f32_16x16x32_bf16 v[96:99], v[242:245], v[48:51], v[100:103]
	v_mfma_f32_16x16x32_bf16 v[88:91], v[238:241], v[48:51], v[92:95]
	v_mfma_f32_16x16x32_bf16 v[72:75], v[234:237], v[48:51], v[76:79]
	v_mfma_f32_16x16x32_bf16 v[48:51], v[230:233], v[48:51], v[52:55]
	ds_read_b64_tr_b16 v[242:243], v190
	ds_read_b64_tr_b16 v[238:239], v190 offset:32
	ds_read_b64_tr_b16 v[234:235], v190 offset:64
	ds_read_b64_tr_b16 v[230:231], v190 offset:96
	ds_read_b64_tr_b16 v[244:245], v191
	ds_read_b64_tr_b16 v[240:241], v191 offset:32
	ds_read_b64_tr_b16 v[236:237], v191 offset:64
	ds_read_b64_tr_b16 v[232:233], v191 offset:96
	s_waitcnt lgkmcnt(8)
	v_mfma_f32_16x16x32_bf16 v[84:87], v[116:119], v[40:43], v[84:87]
	v_mfma_f32_16x16x32_bf16 v[76:79], v[112:115], v[40:43], v[80:83]
	v_mfma_f32_16x16x32_bf16 v[60:63], v[108:111], v[40:43], v[64:67]
	v_mfma_f32_16x16x32_bf16 v[52:55], v[104:107], v[40:43], v[56:59]
	ds_read_b64_tr_b16 v[116:117], v192
	ds_read_b64_tr_b16 v[112:113], v192 offset:32
	ds_read_b64_tr_b16 v[108:109], v192 offset:64
	ds_read_b64_tr_b16 v[104:105], v192 offset:96
	ds_read_b64_tr_b16 v[118:119], v193
	ds_read_b64_tr_b16 v[114:115], v193 offset:32
	ds_read_b64_tr_b16 v[110:111], v193 offset:64
	ds_read_b64_tr_b16 v[106:107], v193 offset:96
	s_waitcnt lgkmcnt(8)
	v_mfma_f32_16x16x32_bf16 v[92:95], v[242:245], v[40:43], v[96:99]
	v_mfma_f32_16x16x32_bf16 v[80:83], v[238:241], v[40:43], v[88:91]
	v_mfma_f32_16x16x32_bf16 v[64:67], v[234:237], v[40:43], v[72:75]
	v_mfma_f32_16x16x32_bf16 v[40:43], v[230:233], v[40:43], v[48:51]
	ds_read_b64_tr_b16 v[242:243], v194
	ds_read_b64_tr_b16 v[238:239], v194 offset:32
	ds_read_b64_tr_b16 v[234:235], v194 offset:64
	ds_read_b64_tr_b16 v[230:231], v194 offset:96
	ds_read_b64_tr_b16 v[244:245], v195
	ds_read_b64_tr_b16 v[240:241], v195 offset:32
	ds_read_b64_tr_b16 v[236:237], v195 offset:64
	ds_read_b64_tr_b16 v[232:233], v195 offset:96
	s_waitcnt lgkmcnt(8)
	v_mfma_f32_16x16x32_bf16 v[84:87], v[116:119], v[24:27], v[84:87]
	v_mfma_f32_16x16x32_bf16 v[72:75], v[112:115], v[24:27], v[76:79]
	v_mfma_f32_16x16x32_bf16 v[56:59], v[108:111], v[24:27], v[60:63]
	v_mfma_f32_16x16x32_bf16 v[48:51], v[104:107], v[24:27], v[52:55]
	ds_read_b64_tr_b16 v[116:117], v196
	ds_read_b64_tr_b16 v[112:113], v196 offset:32
	ds_read_b64_tr_b16 v[108:109], v196 offset:64
	ds_read_b64_tr_b16 v[104:105], v196 offset:96
	ds_read_b64_tr_b16 v[118:119], v197
	ds_read_b64_tr_b16 v[114:115], v197 offset:32
	ds_read_b64_tr_b16 v[110:111], v197 offset:64
	ds_read_b64_tr_b16 v[106:107], v197 offset:96
	s_waitcnt lgkmcnt(8)
	v_mfma_f32_16x16x32_bf16 v[88:91], v[242:245], v[24:27], v[92:95]
	v_mfma_f32_16x16x32_bf16 v[76:79], v[238:241], v[24:27], v[80:83]
	v_mfma_f32_16x16x32_bf16 v[60:63], v[234:237], v[24:27], v[64:67]
	v_mfma_f32_16x16x32_bf16 v[24:27], v[230:233], v[24:27], v[40:43]
	ds_read_b64_tr_b16 v[242:243], v198
	ds_read_b64_tr_b16 v[238:239], v198 offset:32
	ds_read_b64_tr_b16 v[234:235], v198 offset:64
	ds_read_b64_tr_b16 v[230:231], v198 offset:96
	ds_read_b64_tr_b16 v[244:245], v199
	ds_read_b64_tr_b16 v[240:241], v199 offset:32
	ds_read_b64_tr_b16 v[236:237], v199 offset:64
	ds_read_b64_tr_b16 v[232:233], v199 offset:96
	s_waitcnt lgkmcnt(8)
	v_mfma_f32_16x16x32_bf16 v[80:83], v[116:119], v[4:7], v[84:87]
	v_mfma_f32_16x16x32_bf16 v[64:67], v[112:115], v[4:7], v[72:75]
	v_mfma_f32_16x16x32_bf16 v[52:55], v[108:111], v[4:7], v[56:59]
	v_mfma_f32_16x16x32_bf16 v[40:43], v[104:107], v[4:7], v[48:51]
	s_waitcnt lgkmcnt(0)
	v_mfma_f32_16x16x32_bf16 v[84:87], v[242:245], v[4:7], v[88:91]
	v_mfma_f32_16x16x32_bf16 v[72:75], v[238:241], v[4:7], v[76:79]
	v_mfma_f32_16x16x32_bf16 v[56:59], v[234:237], v[4:7], v[60:63]
	v_mfma_f32_16x16x32_bf16 v[4:7], v[230:233], v[4:7], v[24:27]
	s_nop 2
	v_mul_f32_e64 v24, v68, v80
	v_mul_f32_e64 v25, v69, v81
	v_pk_mul_f32 v[26:27], v[68:69], v[82:83]
	v_cvt_pk_bf16_f32 v24, v24, v25
	v_cvt_pk_bf16_f32 v25, v26, v27
	global_store_dwordx2 v[70:71], v[24:25], off offset:768
	v_pk_mul_f32 v[24:25], v[68:69], v[64:65]
	v_pk_mul_f32 v[26:27], v[68:69], v[66:67]
	v_cvt_pk_bf16_f32 v24, v24, v25
	v_cvt_pk_bf16_f32 v25, v26, v27
	global_store_dwordx2 v[70:71], v[24:25], off offset:800
	v_pk_mul_f32 v[24:25], v[68:69], v[52:53]
	v_pk_mul_f32 v[26:27], v[68:69], v[54:55]
	v_cvt_pk_bf16_f32 v24, v24, v25
	v_cvt_pk_bf16_f32 v25, v26, v27
	global_store_dwordx2 v[70:71], v[24:25], off offset:832
	v_pk_mul_f32 v[24:25], v[68:69], v[40:41]
	v_pk_mul_f32 v[26:27], v[68:69], v[42:43]
	v_cvt_pk_bf16_f32 v24, v24, v25
	v_cvt_pk_bf16_f32 v25, v26, v27
	global_store_dwordx2 v[70:71], v[24:25], off offset:864
	v_pk_mul_f32 v[24:25], v[68:69], v[84:85]
	v_pk_mul_f32 v[26:27], v[68:69], v[86:87]
	v_cvt_pk_bf16_f32 v24, v24, v25
	v_cvt_pk_bf16_f32 v25, v26, v27
	global_store_dwordx2 v[70:71], v[24:25], off offset:896
	v_pk_mul_f32 v[24:25], v[68:69], v[72:73]
	v_pk_mul_f32 v[26:27], v[68:69], v[74:75]
	v_cvt_pk_bf16_f32 v24, v24, v25
	v_cvt_pk_bf16_f32 v25, v26, v27
	global_store_dwordx2 v[70:71], v[24:25], off offset:928
	v_pk_mul_f32 v[24:25], v[68:69], v[56:57]
	v_pk_mul_f32 v[26:27], v[68:69], v[58:59]
	v_pk_mul_f32 v[4:5], v[68:69], v[4:5]
	v_pk_mul_f32 v[6:7], v[68:69], v[6:7]
	v_cvt_pk_bf16_f32 v24, v24, v25
	v_cvt_pk_bf16_f32 v25, v26, v27
	v_cvt_pk_bf16_f32 v4, v4, v5
	v_cvt_pk_bf16_f32 v5, v6, v7
	global_store_dwordx2 v[70:71], v[24:25], off offset:960
	global_store_dwordx2 v[70:71], v[4:5], off offset:992
	s_cbranch_vccz .LBB0_392
	s_waitcnt vmcnt(0)
	s_waitcnt lgkmcnt(0)
	s_barrier
